# first K-iteration after an epilogue peeled in all 12 GEMM loops (first two waits count the epilogue stores)
# baseline (speedup 1.0000x reference)
; #define PG8_STAGE_A(bufoff, off) PG8_STAGE_X(bufoff, rsA, g.A, off, voffA)
; #define PG8_STAGE_B(bufoff, off) PG8_STAGE_X(bufoff, rsB, g.Bt, off, voffB)
; #define PG8_WAIT_V(n) asm volatile("s_waitcnt vmcnt(" #n ")" ::: "memory")
; #define PG8_BAR __builtin_amdgcn_s_barrier()
; template <class Epi, class Sched, bool ALIGN_EPI, bool F8 = false>
; __device__ __forceinline__ void gemm_phase(LAS unsigned char* lds, const Gemm g, const Sched& S, const Epi& E) {
;     ...
;     const unsigned lds_w32 = (unsigned)__builtin_amdgcn_readfirstlane((int)((unsigned)(uintptr_t)lds + ldsw));
;     constexpr int KOFF = F8 ? 16 : 1024;
;     const int aoff = lds_byte(wr * 64 + fr, F8 ? fq * 16 : fq * 8), boff = lds_byte(wc * 32 + fr, F8 ? fq * 16 : fq * 8);
;     ...
;     PG8_STAGE_B(PG8_SB(0, 0), cB); PG8_STAGE_B(PG8_SB(0, 1), cB + hstepB); PG8_STAGE_A(PG8_SA(0, 0), cA); PG8_STAGE_A(PG8_SA(0, 1), cA + hstepA);
;     if (wr == 1) PG8_BAR;
;     PG8_WAIT_V(2); PG8_BAR;
;     PG8_STAGE_B(PG8_SB(1, 0), cB + kstep); PG8_STAGE_A(PG8_SA(1, 0), cA + kstep); PG8_STAGE_B(PG8_SB(1, 1), cB + hstepB + kstep);
;     PG8_WAIT_V(6); PG8_BAR;
.LBB0_605:
	s_or_b32 s1, s6, 0x80
	s_add_i32 m0, s37, 0x18000
	v_add_u32_e32 v6, s1, v158
	s_waitcnt vmcnt(2)
	s_barrier
	global_load_lds_dwordx4 v6, s[26:27]
	v_add_u32_e32 v6, s1, v160
	s_add_i32 m0, s37, 0x1a000
	s_or_b32 s1, s7, 0x80
	s_add_i32 s42, s37, 0x8000
	global_load_lds_dwordx4 v6, s[26:27]
	v_add_u32_e32 v6, s1, v157
	s_mov_b32 m0, s42
	s_add_i32 s43, s37, 0xa000
	global_load_lds_dwordx4 v6, s[24:25]
	v_add_u32_e32 v6, s1, v159
	s_mov_b32 m0, s43
	s_or_b32 s1, s6, 0x80080
	global_load_lds_dwordx4 v6, s[24:25]
	s_add_i32 m0, s37, 0x1c000
	v_add_u32_e32 v6, s1, v158
	global_load_lds_dwordx4 v6, s[26:27]
	v_add_u32_e32 v6, s1, v160
	s_add_i32 m0, s37, 0x1e000
	v_lshlrev_b32_e32 v7, 6, v253
	global_load_lds_dwordx4 v6, s[26:27]
	v_and_b32_e32 v6, 48, v253
	s_movk_i32 s1, 0x3c0
	v_and_or_b32 v6, v7, s1, v6
	v_lshlrev_b32_e32 v7, 2, v253
	s_lshl_b32 s48, s0, 6
	s_lshl_b32 s0, s0, 13
	v_and_b32_e32 v7, 32, v7
	v_readlane_b32 s1, v254, 15
	v_bitop3_b32 v8, v6, s0, v7 bitop3:0xde
	s_lshl_b32 s0, s1, 5
	s_and_b32 s49, s0, 0x60
	s_lshl_b32 s0, s49, 7
	v_bitop3_b32 v156, v6, s0, v7 bitop3:0xde
	v_lshlrev_b32_e32 v6, 15, v3
	v_and_b32_e32 v6, 0xffff0000, v6
	v_lshl_add_u32 v4, v4, 12, v6
	v_and_b32_e32 v3, 1, v3
	s_mov_b32 s0, 0x80080
	v_lshl_or_b32 v3, v3, 6, v4
	v_lshlrev_b32_e32 v4, 1, v5
	v_add3_u32 v161, v3, v4, s0
	v_lshlrev_b32_e32 v3, 15, v0
	v_and_b32_e32 v3, 0xffff0000, v3
	s_waitcnt vmcnt(6)
	s_cmp_lt_u32 s1, 4
	v_lshl_add_u32 v1, v1, 12, v3
	v_and_b32_e32 v0, 1, v0
	s_cselect_b64 s[30:31], -1, 0
	v_lshl_or_b32 v0, v0, 6, v1
	v_lshlrev_b32_e32 v1, 1, v2
	s_add_i32 s52, 0, 0x10000
	s_add_i32 s53, 0, 0x14000
	s_or_b32 s50, s49, 0xffffde00
	s_ashr_i32 s51, s18, 31
	v_add3_u32 v162, v0, v1, s0
	v_mov_b64_e32 v[132:133], 0x400
	v_mov_b64_e32 v[134:135], 0x3ff
	v_add_u32_e32 v163, s52, v156
	v_add_u32_e32 v164, s53, v156
	v_add_u32_e32 v165, 0, v8
	v_mov_b32_e32 v166, 0x358637bd
	s_mov_b32 s54, 0x800000
	s_movk_i32 s55, 0x4400
	s_movk_i32 s56, 0x3000
	s_barrier
	s_mov_b32 s80, 0
	s_branch .LBB0_608

; template <class Epi, class Sched, bool ALIGN_EPI, bool F8 = false>
; __device__ __forceinline__ void gemm_phase(LAS unsigned char* lds, const Gemm g, const Sched& S, const Epi& E) {
;     ...
;         if (!has_next) break;
; #pragma unroll
;         for (int a = 0; a < 2; ++a)
; #pragma unroll
;             for (int b = 0; b < 2; ++b)
; #pragma unroll
;                 for (int m = 0; m < 4; ++m)
; #pragma unroll
;                     for (int n = 0; n < 2; ++n) acc[a][b][m][n] = (f32x4){0.f, 0.f, 0.f, 0.f};
;         cur = nxt; cA = nA; cB = nB; ++ui;
.LBB0_607:
	s_mov_b32 s80, 1
	s_andn2_b64 vcc, exec, s[0:1]
	s_mov_b32 s5, s57
	s_mov_b32 s4, s58
	s_mov_b32 s6, s60
	s_mov_b32 s7, s59
	s_cbranch_vccz .LBB0_629

; #define PG8_STAGE_A(bufoff, off) PG8_STAGE_X(bufoff, rsA, g.A, off, voffA)
; #define PG8_LDA(dst, b, h) do { _Pragma("unroll") for (int m = 0; m < 4; ++m) _Pragma("unroll") for (int k = 0; k < 2; ++k) { const v4i_t f_ = *(const LAS v4i_t*)(lds + PG8_SA(b, h) + aoff + m * 2048 + k * KOFF); dst[m][4 * k] = f_[0]; dst[m][4 * k + 1] = f_[1]; dst[m][4 * k + 2] = f_[2]; dst[m][4 * k + 3] = f_[3]; } } while (0)
; #define PG8_LDB(dst, b, h) do { _Pragma("unroll") for (int n = 0; n < 2; ++n) _Pragma("unroll") for (int k = 0; k < 2; ++k) { const v4i_t f_ = *(const LAS v4i_t*)(lds + PG8_SB(b, h) + boff + n * 2048 + k * KOFF); dst[n][4 * k] = f_[0]; dst[n][4 * k + 1] = f_[1]; dst[n][4 * k + 2] = f_[2]; dst[n][4 * k + 3] = f_[3]; } } while (0)
; #define PG8_WAIT_V(n) asm volatile("s_waitcnt vmcnt(" #n ")" ::: "memory")
; #define PG8_WAIT_L(n) asm volatile("s_waitcnt lgkmcnt(" #n ")" ::: "memory")
; #define PG8_BAR __builtin_amdgcn_s_barrier()
; #define PG8_SCHED __builtin_amdgcn_sched_barrier(0)
; template <class Epi, class Sched, bool ALIGN_EPI, bool F8 = false>
; __device__ __forceinline__ void gemm_phase(LAS unsigned char* lds, const Gemm g, const Sched& S, const Epi& E) {
;     ...
;         for (int t = 0; t < nt; t += 2) {
;             const bool last = (t == nt - 2);
;             const unsigned a1 = cA + (unsigned)(t + 1) * kstep;
;             const unsigned a2 = last ? nA : cA + (unsigned)(t + 2) * kstep; const unsigned b2 = last ? nB : cB + (unsigned)(t + 2) * kstep;
;             const unsigned a3 = a2 + kstep; const unsigned b3 = b2 + kstep;
;             PG8_LDB(B0, 0, 0); PG8_LDB(B1, 0, 1); PG8_SCHED; PG8_LDA(At, 0, 0); PG8_STAGE_A(PG8_SA(1, 1), a1 + hstepA);
;             PG8_WAIT_V(8); PG8_WAIT_L(0); PG8_BAR; PG8_MMA(0, 0, At, B0); PG8_MMA(0, 1, At, B1); PG8_BAR; PG8_SCHED;
;     ...
;         for (int a = 0; a < 2; ++a)
; #pragma unroll
;             for (int b = 0; b < 2; ++b)
; #pragma unroll
;                 for (int m = 0; m < 4; ++m)
; #pragma unroll
;                     for (int n = 0; n < 2; ++n) acc[a][b][m][n] = (f32x4){0.f, 0.f, 0.f, 0.f};
.LBB0_614:
	s_lshl_b32 s59, s58, 20
	s_and_b64 s[0:1], s[2:3], exec
	s_cselect_b32 s0, s59, s7
	s_lshl_b32 s60, s57, 20
	s_and_b64 s[8:9], s[2:3], exec
	v_mov_b32_e32 v0, 0
	s_cselect_b32 s1, s60, s6
	v_add_u32_e32 v128, s7, v161
	v_add_u32_e32 v129, s7, v162
	s_addk_i32 s6, 0x100
	s_addk_i32 s7, 0x100
	s_mov_b32 s8, -2
	v_mov_b32_e32 v1, v0
	v_mov_b32_e32 v2, v0
	v_mov_b32_e32 v3, v0
	v_mov_b32_e32 v4, v0
	v_mov_b32_e32 v5, v0
	v_mov_b32_e32 v6, v0
	v_mov_b32_e32 v7, v0
	v_mov_b32_e32 v16, v0
	v_mov_b32_e32 v17, v0
	v_mov_b32_e32 v18, v0
	v_mov_b32_e32 v19, v0
	v_mov_b32_e32 v20, v0
	v_mov_b32_e32 v21, v0
	v_mov_b32_e32 v22, v0
	v_mov_b32_e32 v23, v0
	v_mov_b32_e32 v32, v0
	v_mov_b32_e32 v33, v0
	v_mov_b32_e32 v34, v0
	v_mov_b32_e32 v35, v0
	v_mov_b32_e32 v36, v0
	v_mov_b32_e32 v37, v0
	v_mov_b32_e32 v38, v0
	v_mov_b32_e32 v39, v0
	v_mov_b32_e32 v48, v0
	v_mov_b32_e32 v49, v0
	v_mov_b32_e32 v50, v0
	v_mov_b32_e32 v51, v0
	v_mov_b32_e32 v52, v0
	v_mov_b32_e32 v53, v0
	v_mov_b32_e32 v54, v0
	v_mov_b32_e32 v55, v0
	v_mov_b32_e32 v8, v0
	v_mov_b32_e32 v9, v0
	v_mov_b32_e32 v10, v0
	v_mov_b32_e32 v11, v0
	v_mov_b32_e32 v12, v0
	v_mov_b32_e32 v13, v0
	v_mov_b32_e32 v14, v0
	v_mov_b32_e32 v15, v0
	v_mov_b32_e32 v24, v0
	v_mov_b32_e32 v25, v0
	v_mov_b32_e32 v26, v0
	v_mov_b32_e32 v27, v0
	v_mov_b32_e32 v28, v0
	v_mov_b32_e32 v29, v0
	v_mov_b32_e32 v30, v0
	v_mov_b32_e32 v31, v0
	v_mov_b32_e32 v40, v0
	v_mov_b32_e32 v41, v0
	v_mov_b32_e32 v42, v0
	v_mov_b32_e32 v43, v0
	v_mov_b32_e32 v44, v0
	v_mov_b32_e32 v45, v0
	v_mov_b32_e32 v46, v0
	v_mov_b32_e32 v47, v0
	v_mov_b32_e32 v56, v0
	v_mov_b32_e32 v57, v0
	v_mov_b32_e32 v58, v0
	v_mov_b32_e32 v59, v0
	v_mov_b32_e32 v60, v0
	v_mov_b32_e32 v61, v0
	v_mov_b32_e32 v62, v0
	v_mov_b32_e32 v63, v0
	v_mov_b32_e32 v64, v0
	v_mov_b32_e32 v65, v0
	v_mov_b32_e32 v66, v0
	v_mov_b32_e32 v67, v0
	v_mov_b32_e32 v68, v0
	v_mov_b32_e32 v69, v0
	v_mov_b32_e32 v70, v0
	v_mov_b32_e32 v71, v0
	v_mov_b32_e32 v80, v0
	v_mov_b32_e32 v81, v0
	v_mov_b32_e32 v82, v0
	v_mov_b32_e32 v83, v0
	v_mov_b32_e32 v84, v0
	v_mov_b32_e32 v85, v0
	v_mov_b32_e32 v86, v0
	v_mov_b32_e32 v87, v0
	v_mov_b32_e32 v96, v0
	v_mov_b32_e32 v97, v0
	v_mov_b32_e32 v98, v0
	v_mov_b32_e32 v99, v0
	v_mov_b32_e32 v100, v0
	v_mov_b32_e32 v101, v0
	v_mov_b32_e32 v102, v0
	v_mov_b32_e32 v103, v0
	v_mov_b32_e32 v112, v0
	v_mov_b32_e32 v113, v0
	v_mov_b32_e32 v114, v0
	v_mov_b32_e32 v115, v0
	v_mov_b32_e32 v116, v0
	v_mov_b32_e32 v117, v0
	v_mov_b32_e32 v118, v0
	v_mov_b32_e32 v119, v0
	v_mov_b32_e32 v72, v0
	v_mov_b32_e32 v73, v0
	v_mov_b32_e32 v74, v0
	v_mov_b32_e32 v75, v0
	v_mov_b32_e32 v76, v0
	v_mov_b32_e32 v77, v0
	v_mov_b32_e32 v78, v0
	v_mov_b32_e32 v79, v0
	v_mov_b32_e32 v88, v0
	v_mov_b32_e32 v89, v0
	v_mov_b32_e32 v90, v0
	v_mov_b32_e32 v91, v0
	v_mov_b32_e32 v92, v0
	v_mov_b32_e32 v93, v0
	v_mov_b32_e32 v94, v0
	v_mov_b32_e32 v95, v0
	v_mov_b32_e32 v104, v0
	v_mov_b32_e32 v105, v0
	v_mov_b32_e32 v106, v0
	v_mov_b32_e32 v107, v0
	v_mov_b32_e32 v108, v0
	v_mov_b32_e32 v109, v0
	v_mov_b32_e32 v110, v0
	v_mov_b32_e32 v111, v0
	v_mov_b32_e32 v120, v0
	v_mov_b32_e32 v121, v0
	v_mov_b32_e32 v122, v0
	v_mov_b32_e32 v123, v0
	v_mov_b32_e32 v124, v0
	v_mov_b32_e32 v125, v0
	v_mov_b32_e32 v126, v0
	v_mov_b32_e32 v127, v0
	s_cmp_lg_u32 s80, 0
	s_cbranch_scc0 .LBB0_615
	ds_read_b128 v[136:139], v163
	ds_read_b128 v[140:143], v163 offset:1024
	ds_read_b128 v[144:147], v163 offset:2048
	ds_read_b128 v[150:153], v163 offset:3072
	ds_read_b128 v[168:171], v164
	ds_read_b128 v[172:175], v164 offset:1024
	ds_read_b128 v[176:179], v164 offset:2048
	ds_read_b128 v[180:183], v164 offset:3072
	s_cmp_eq_u32 s8, 28
	s_cselect_b32 s11, s0, s7
	s_cselect_b32 s10, s1, s6
	s_or_b32 s9, s11, 0x80
	s_add_i32 m0, s37, 0xc000
	ds_read_b128 v[184:187], v165
	ds_read_b128 v[188:191], v165 offset:1024
	ds_read_b128 v[192:195], v165 offset:2048
	ds_read_b128 v[196:199], v165 offset:3072
	ds_read_b128 v[200:203], v165 offset:4096
	ds_read_b128 v[204:207], v165 offset:5120
	ds_read_b128 v[208:211], v165 offset:6144
	ds_read_b128 v[212:215], v165 offset:7168
	global_load_lds_dwordx4 v129, s[24:25]
	s_add_i32 m0, s37, 0xe000
	s_nop 0
	global_load_lds_dwordx4 v128, s[24:25]
	s_waitcnt vmcnt(24)
	s_waitcnt lgkmcnt(0)
	s_barrier
	s_setprio 1
	s_waitcnt lgkmcnt(0)
	v_mfma_f32_16x16x32_bf16 v[124:127], v[136:139], v[184:187], v[124:127]
	v_mfma_f32_16x16x32_bf16 v[120:123], v[144:147], v[184:187], v[120:123]
	v_mfma_f32_16x16x32_bf16 v[108:111], v[136:139], v[192:195], v[108:111]
	v_mfma_f32_16x16x32_bf16 v[104:107], v[144:147], v[192:195], v[104:107]
	v_mfma_f32_16x16x32_bf16 v[92:95], v[136:139], v[200:203], v[92:95]
	v_mfma_f32_16x16x32_bf16 v[88:91], v[144:147], v[200:203], v[88:91]
	v_mfma_f32_16x16x32_bf16 v[76:79], v[136:139], v[208:211], v[76:79]
	v_mfma_f32_16x16x32_bf16 v[72:75], v[144:147], v[208:211], v[72:75]
	v_mfma_f32_16x16x32_bf16 v[124:127], v[140:143], v[188:191], v[124:127]
	v_mfma_f32_16x16x32_bf16 v[120:123], v[150:153], v[188:191], v[120:123]
	v_mfma_f32_16x16x32_bf16 v[108:111], v[140:143], v[196:199], v[108:111]
	v_mfma_f32_16x16x32_bf16 v[104:107], v[150:153], v[196:199], v[104:107]
	v_mfma_f32_16x16x32_bf16 v[92:95], v[140:143], v[204:207], v[92:95]
	v_mfma_f32_16x16x32_bf16 v[88:91], v[150:153], v[204:207], v[88:91]
	v_mfma_f32_16x16x32_bf16 v[76:79], v[140:143], v[212:215], v[76:79]
	v_mfma_f32_16x16x32_bf16 v[72:75], v[150:153], v[212:215], v[72:75]
	s_setprio 0
	s_setprio 1
	v_mfma_f32_16x16x32_bf16 v[116:119], v[168:171], v[184:187], v[116:119]
	v_mfma_f32_16x16x32_bf16 v[112:115], v[176:179], v[184:187], v[112:115]
	v_mfma_f32_16x16x32_bf16 v[100:103], v[168:171], v[192:195], v[100:103]
	v_mfma_f32_16x16x32_bf16 v[96:99], v[176:179], v[192:195], v[96:99]
	v_mfma_f32_16x16x32_bf16 v[84:87], v[168:171], v[200:203], v[84:87]
	v_mfma_f32_16x16x32_bf16 v[80:83], v[176:179], v[200:203], v[80:83]
	v_mfma_f32_16x16x32_bf16 v[68:71], v[168:171], v[208:211], v[68:71]
	v_mfma_f32_16x16x32_bf16 v[64:67], v[176:179], v[208:211], v[64:67]
	v_mfma_f32_16x16x32_bf16 v[116:119], v[172:175], v[188:191], v[116:119]
	v_mfma_f32_16x16x32_bf16 v[112:115], v[180:183], v[188:191], v[112:115]
	v_mfma_f32_16x16x32_bf16 v[100:103], v[172:175], v[196:199], v[100:103]
	v_mfma_f32_16x16x32_bf16 v[96:99], v[180:183], v[196:199], v[96:99]
	v_mfma_f32_16x16x32_bf16 v[84:87], v[172:175], v[204:207], v[84:87]
	v_mfma_f32_16x16x32_bf16 v[80:83], v[180:183], v[204:207], v[80:83]
	v_mfma_f32_16x16x32_bf16 v[68:71], v[172:175], v[212:215], v[68:71]
	v_mfma_f32_16x16x32_bf16 v[64:67], v[180:183], v[212:215], v[64:67]
	s_setprio 0
	s_barrier
; #define PG8_STAGE_A(bufoff, off) PG8_STAGE_X(bufoff, rsA, g.A, off, voffA)
; #define PG8_STAGE_B(bufoff, off) PG8_STAGE_X(bufoff, rsB, g.Bt, off, voffB)
; #define PG8_LDA(dst, b, h) do { _Pragma("unroll") for (int m = 0; m < 4; ++m) _Pragma("unroll") for (int k = 0; k < 2; ++k) { const v4i_t f_ = *(const LAS v4i_t*)(lds + PG8_SA(b, h) + aoff + m * 2048 + k * KOFF); dst[m][4 * k] = f_[0]; dst[m][4 * k + 1] = f_[1]; dst[m][4 * k + 2] = f_[2]; dst[m][4 * k + 3] = f_[3]; } } while (0)
; #define PG8_LDB(dst, b, h) do { _Pragma("unroll") for (int n = 0; n < 2; ++n) _Pragma("unroll") for (int k = 0; k < 2; ++k) { const v4i_t f_ = *(const LAS v4i_t*)(lds + PG8_SB(b, h) + boff + n * 2048 + k * KOFF); dst[n][4 * k] = f_[0]; dst[n][4 * k + 1] = f_[1]; dst[n][4 * k + 2] = f_[2]; dst[n][4 * k + 3] = f_[3]; } } while (0)
; #define PG8_WAIT_V(n) asm volatile("s_waitcnt vmcnt(" #n ")" ::: "memory")
; #define PG8_WAIT_L(n) asm volatile("s_waitcnt lgkmcnt(" #n ")" ::: "memory")
; #define PG8_BAR __builtin_amdgcn_s_barrier()
; #define PG8_SCHED __builtin_amdgcn_sched_barrier(0)
; template <class Epi, class Sched, bool ALIGN_EPI, bool F8 = false>
; __device__ __forceinline__ void gemm_phase(LAS unsigned char* lds, const Gemm g, const Sched& S, const Epi& E) {
;     ...
;             PG8_LDA(At, 0, 1); PG8_STAGE_B(PG8_SB(0, 0), b2); PG8_STAGE_B(PG8_SB(0, 1), b2 + hstepB); PG8_STAGE_A(PG8_SA(0, 0), a2);
;             PG8_WAIT_V(8); PG8_WAIT_L(0); PG8_BAR; PG8_MMA(1, 0, At, B0); PG8_MMA(1, 1, At, B1); PG8_BAR; PG8_SCHED;
;             PG8_LDB(B0, 1, 0); PG8_LDB(B1, 1, 1); PG8_SCHED; PG8_LDA(At, 1, 0); PG8_STAGE_A(PG8_SA(0, 1), a2 + hstepA);
	s_add_i32 s12, s52, s36
	v_add_u32_e32 v130, s10, v158
	s_mov_b32 m0, s12
	ds_read_b128 v[184:187], v165 offset:16384
	ds_read_b128 v[188:191], v165 offset:17408
	ds_read_b128 v[192:195], v165 offset:18432
	ds_read_b128 v[196:199], v165 offset:19456
	ds_read_b128 v[200:203], v165 offset:20480
	ds_read_b128 v[204:207], v165 offset:21504
	ds_read_b128 v[208:211], v165 offset:22528
	ds_read_b128 v[212:215], v165 offset:23552
	global_load_lds_dwordx4 v130, s[26:27]
	v_add_u32_e32 v130, s10, v160
	s_add_i32 m0, s12, 0x2000
	s_add_i32 s12, s10, 0x80000
	s_add_i32 s13, s53, s36
	global_load_lds_dwordx4 v130, s[26:27]
	v_add_u32_e32 v130, s12, v158
	s_mov_b32 m0, s13
	s_nop 0
	global_load_lds_dwordx4 v130, s[26:27]
	v_add_u32_e32 v130, s12, v160
	s_add_i32 m0, s13, 0x2000
	s_nop 0
	global_load_lds_dwordx4 v130, s[26:27]
	v_add_u32_e32 v130, s11, v157
	s_mov_b32 m0, s37
	s_nop 0
	global_load_lds_dwordx4 v130, s[24:25]
	v_add_u32_e32 v130, s11, v159
	s_mov_b32 m0, s38
	s_nop 0
	global_load_lds_dwordx4 v130, s[24:25]
	s_waitcnt vmcnt(24)
	s_waitcnt lgkmcnt(0)
	s_barrier
	s_setprio 1
	s_waitcnt lgkmcnt(0)
	v_mfma_f32_16x16x32_bf16 v[60:63], v[136:139], v[184:187], v[60:63]
	v_mfma_f32_16x16x32_bf16 v[56:59], v[144:147], v[184:187], v[56:59]
	v_mfma_f32_16x16x32_bf16 v[44:47], v[136:139], v[192:195], v[44:47]
	v_mfma_f32_16x16x32_bf16 v[40:43], v[144:147], v[192:195], v[40:43]
	v_mfma_f32_16x16x32_bf16 v[28:31], v[136:139], v[200:203], v[28:31]
	v_mfma_f32_16x16x32_bf16 v[24:27], v[144:147], v[200:203], v[24:27]
	v_mfma_f32_16x16x32_bf16 v[12:15], v[136:139], v[208:211], v[12:15]
	v_mfma_f32_16x16x32_bf16 v[8:11], v[144:147], v[208:211], v[8:11]
	v_mfma_f32_16x16x32_bf16 v[60:63], v[140:143], v[188:191], v[60:63]
	v_mfma_f32_16x16x32_bf16 v[56:59], v[150:153], v[188:191], v[56:59]
	v_mfma_f32_16x16x32_bf16 v[44:47], v[140:143], v[196:199], v[44:47]
	v_mfma_f32_16x16x32_bf16 v[40:43], v[150:153], v[196:199], v[40:43]
	v_mfma_f32_16x16x32_bf16 v[28:31], v[140:143], v[204:207], v[28:31]
	v_mfma_f32_16x16x32_bf16 v[24:27], v[150:153], v[204:207], v[24:27]
	v_mfma_f32_16x16x32_bf16 v[12:15], v[140:143], v[212:215], v[12:15]
	v_mfma_f32_16x16x32_bf16 v[8:11], v[150:153], v[212:215], v[8:11]
	s_setprio 0
	s_setprio 1
	v_mfma_f32_16x16x32_bf16 v[52:55], v[168:171], v[184:187], v[52:55]
	v_mfma_f32_16x16x32_bf16 v[48:51], v[176:179], v[184:187], v[48:51]
	v_mfma_f32_16x16x32_bf16 v[36:39], v[168:171], v[192:195], v[36:39]
	v_mfma_f32_16x16x32_bf16 v[32:35], v[176:179], v[192:195], v[32:35]
	v_mfma_f32_16x16x32_bf16 v[20:23], v[168:171], v[200:203], v[20:23]
	v_mfma_f32_16x16x32_bf16 v[16:19], v[176:179], v[200:203], v[16:19]
	v_mfma_f32_16x16x32_bf16 v[4:7], v[168:171], v[208:211], v[4:7]
	v_mfma_f32_16x16x32_bf16 v[0:3], v[176:179], v[208:211], v[0:3]
	v_mfma_f32_16x16x32_bf16 v[52:55], v[172:175], v[188:191], v[52:55]
	v_mfma_f32_16x16x32_bf16 v[48:51], v[180:183], v[188:191], v[48:51]
	v_mfma_f32_16x16x32_bf16 v[36:39], v[172:175], v[196:199], v[36:39]
	v_mfma_f32_16x16x32_bf16 v[32:35], v[180:183], v[196:199], v[32:35]
	v_mfma_f32_16x16x32_bf16 v[20:23], v[172:175], v[204:207], v[20:23]
	v_mfma_f32_16x16x32_bf16 v[16:19], v[180:183], v[204:207], v[16:19]
	v_mfma_f32_16x16x32_bf16 v[4:7], v[172:175], v[212:215], v[4:7]
	v_mfma_f32_16x16x32_bf16 v[0:3], v[180:183], v[212:215], v[0:3]
	s_setprio 0
	s_barrier
	s_add_i32 s12, 0, 0x18000
	v_add_u32_e32 v130, s12, v156
	s_add_i32 s13, 0, 0x1c000
	ds_read_b128 v[136:139], v130
	ds_read_b128 v[140:143], v130 offset:1024
	ds_read_b128 v[144:147], v130 offset:2048
	ds_read_b128 v[150:153], v130 offset:3072
	v_add_u32_e32 v130, s13, v156
	ds_read_b128 v[168:171], v130
	ds_read_b128 v[172:175], v130 offset:1024
	ds_read_b128 v[176:179], v130 offset:2048
	ds_read_b128 v[180:183], v130 offset:3072
	s_add_i32 s11, s11, 0x80000
	s_mov_b32 m0, s39
	v_add_u32_e32 v130, s11, v157
	ds_read_b128 v[184:187], v165 offset:32768
	ds_read_b128 v[188:191], v165 offset:33792
	ds_read_b128 v[192:195], v165 offset:34816
	ds_read_b128 v[196:199], v165 offset:35840
	ds_read_b128 v[200:203], v165 offset:36864
	ds_read_b128 v[204:207], v165 offset:37888
	ds_read_b128 v[208:211], v165 offset:38912
	ds_read_b128 v[212:215], v165 offset:39936
	global_load_lds_dwordx4 v130, s[24:25]
	v_add_u32_e32 v130, s11, v159
	s_mov_b32 m0, s40
	s_nop 0
	global_load_lds_dwordx4 v130, s[24:25]
	s_waitcnt vmcnt(8)
	s_waitcnt lgkmcnt(0)
	s_barrier
; #define PG8_STAGE_A(bufoff, off) PG8_STAGE_X(bufoff, rsA, g.A, off, voffA)
; #define PG8_STAGE_B(bufoff, off) PG8_STAGE_X(bufoff, rsB, g.Bt, off, voffB)
; #define PG8_LDA(dst, b, h) do { _Pragma("unroll") for (int m = 0; m < 4; ++m) _Pragma("unroll") for (int k = 0; k < 2; ++k) { const v4i_t f_ = *(const LAS v4i_t*)(lds + PG8_SA(b, h) + aoff + m * 2048 + k * KOFF); dst[m][4 * k] = f_[0]; dst[m][4 * k + 1] = f_[1]; dst[m][4 * k + 2] = f_[2]; dst[m][4 * k + 3] = f_[3]; } } while (0)
; #define PG8_LDB(dst, b, h) do { _Pragma("unroll") for (int n = 0; n < 2; ++n) _Pragma("unroll") for (int k = 0; k < 2; ++k) { const v4i_t f_ = *(const LAS v4i_t*)(lds + PG8_SB(b, h) + boff + n * 2048 + k * KOFF); dst[n][4 * k] = f_[0]; dst[n][4 * k + 1] = f_[1]; dst[n][4 * k + 2] = f_[2]; dst[n][4 * k + 3] = f_[3]; } } while (0)
; #define PG8_WAIT_V(n) asm volatile("s_waitcnt vmcnt(" #n ")" ::: "memory")
; #define PG8_WAIT_L(n) asm volatile("s_waitcnt lgkmcnt(" #n ")" ::: "memory")
; #define PG8_BAR __builtin_amdgcn_s_barrier()
; #define PG8_SCHED __builtin_amdgcn_sched_barrier(0)
; template <class Epi, class Sched, bool ALIGN_EPI, bool F8 = false>
; __device__ __forceinline__ void gemm_phase(LAS unsigned char* lds, const Gemm g, const Sched& S, const Epi& E) {
;     ...
;             PG8_LDB(B0, 1, 0); PG8_LDB(B1, 1, 1); PG8_SCHED; PG8_LDA(At, 1, 0); PG8_STAGE_A(PG8_SA(0, 1), a2 + hstepA);
;             PG8_WAIT_V(8); PG8_WAIT_L(0); PG8_BAR; PG8_MMA(0, 0, At, B0); PG8_MMA(0, 1, At, B1); PG8_BAR; PG8_SCHED;
;             PG8_LDA(At, 1, 1); PG8_STAGE_B(PG8_SB(1, 0), b3); PG8_STAGE_B(PG8_SB(1, 1), b3 + hstepB); PG8_STAGE_A(PG8_SA(1, 0), a3);
;             PG8_WAIT_V(8); PG8_WAIT_L(0); PG8_BAR; PG8_MMA(1, 0, At, B0); PG8_MMA(1, 1, At, B1); PG8_BAR; PG8_SCHED;
	s_setprio 1
	s_waitcnt lgkmcnt(0)
	v_mfma_f32_16x16x32_bf16 v[124:127], v[136:139], v[184:187], v[124:127]
	v_mfma_f32_16x16x32_bf16 v[120:123], v[144:147], v[184:187], v[120:123]
	v_mfma_f32_16x16x32_bf16 v[108:111], v[136:139], v[192:195], v[108:111]
	v_mfma_f32_16x16x32_bf16 v[104:107], v[144:147], v[192:195], v[104:107]
	v_mfma_f32_16x16x32_bf16 v[92:95], v[136:139], v[200:203], v[92:95]
	v_mfma_f32_16x16x32_bf16 v[88:91], v[144:147], v[200:203], v[88:91]
	v_mfma_f32_16x16x32_bf16 v[76:79], v[136:139], v[208:211], v[76:79]
	v_mfma_f32_16x16x32_bf16 v[72:75], v[144:147], v[208:211], v[72:75]
	v_mfma_f32_16x16x32_bf16 v[124:127], v[140:143], v[188:191], v[124:127]
	v_mfma_f32_16x16x32_bf16 v[120:123], v[150:153], v[188:191], v[120:123]
	v_mfma_f32_16x16x32_bf16 v[108:111], v[140:143], v[196:199], v[108:111]
	v_mfma_f32_16x16x32_bf16 v[104:107], v[150:153], v[196:199], v[104:107]
	v_mfma_f32_16x16x32_bf16 v[92:95], v[140:143], v[204:207], v[92:95]
	v_mfma_f32_16x16x32_bf16 v[88:91], v[150:153], v[204:207], v[88:91]
	v_mfma_f32_16x16x32_bf16 v[76:79], v[140:143], v[212:215], v[76:79]
	v_mfma_f32_16x16x32_bf16 v[72:75], v[150:153], v[212:215], v[72:75]
	s_setprio 0
	s_setprio 1
	v_mfma_f32_16x16x32_bf16 v[116:119], v[168:171], v[184:187], v[116:119]
	v_mfma_f32_16x16x32_bf16 v[112:115], v[176:179], v[184:187], v[112:115]
	v_mfma_f32_16x16x32_bf16 v[100:103], v[168:171], v[192:195], v[100:103]
	v_mfma_f32_16x16x32_bf16 v[96:99], v[176:179], v[192:195], v[96:99]
	v_mfma_f32_16x16x32_bf16 v[84:87], v[168:171], v[200:203], v[84:87]
	v_mfma_f32_16x16x32_bf16 v[80:83], v[176:179], v[200:203], v[80:83]
	v_mfma_f32_16x16x32_bf16 v[68:71], v[168:171], v[208:211], v[68:71]
	v_mfma_f32_16x16x32_bf16 v[64:67], v[176:179], v[208:211], v[64:67]
	v_mfma_f32_16x16x32_bf16 v[116:119], v[172:175], v[188:191], v[116:119]
	v_mfma_f32_16x16x32_bf16 v[112:115], v[180:183], v[188:191], v[112:115]
	v_mfma_f32_16x16x32_bf16 v[100:103], v[172:175], v[196:199], v[100:103]
	v_mfma_f32_16x16x32_bf16 v[96:99], v[180:183], v[196:199], v[96:99]
	v_mfma_f32_16x16x32_bf16 v[84:87], v[172:175], v[204:207], v[84:87]
	v_mfma_f32_16x16x32_bf16 v[80:83], v[180:183], v[204:207], v[80:83]
	v_mfma_f32_16x16x32_bf16 v[68:71], v[172:175], v[212:215], v[68:71]
	v_mfma_f32_16x16x32_bf16 v[64:67], v[180:183], v[212:215], v[64:67]
	s_setprio 0
	s_barrier
	s_or_b32 s11, s10, 0x80
	s_add_i32 s12, s12, s36
	v_add_u32_e32 v130, s11, v158
	s_mov_b32 m0, s12
	ds_read_b128 v[184:187], v165 offset:49152
	ds_read_b128 v[188:191], v165 offset:50176
	ds_read_b128 v[192:195], v165 offset:51200
	ds_read_b128 v[196:199], v165 offset:52224
	ds_read_b128 v[200:203], v165 offset:53248
	ds_read_b128 v[204:207], v165 offset:54272
	ds_read_b128 v[208:211], v165 offset:55296
	ds_read_b128 v[212:215], v165 offset:56320
	global_load_lds_dwordx4 v130, s[26:27]
	v_add_u32_e32 v130, s11, v160
	s_add_i32 m0, s12, 0x2000
	s_add_i32 s10, s10, 0x80080
	s_add_i32 s11, s13, s36
	global_load_lds_dwordx4 v130, s[26:27]
	v_add_u32_e32 v130, s10, v158
	s_mov_b32 m0, s11
	s_nop 0
	global_load_lds_dwordx4 v130, s[26:27]
	v_add_u32_e32 v130, s10, v160
	s_add_i32 m0, s11, 0x2000
	s_nop 0
	global_load_lds_dwordx4 v130, s[26:27]
	v_add_u32_e32 v130, s9, v157
	s_mov_b32 m0, s42
	s_nop 0
	global_load_lds_dwordx4 v130, s[24:25]
	v_add_u32_e32 v130, s9, v159
	s_mov_b32 m0, s43
	s_nop 0
	global_load_lds_dwordx4 v130, s[24:25]
	s_waitcnt vmcnt(8)
	s_waitcnt lgkmcnt(0)
	s_barrier
	s_setprio 1
	s_waitcnt lgkmcnt(0)
	v_mfma_f32_16x16x32_bf16 v[60:63], v[136:139], v[184:187], v[60:63]
	v_mfma_f32_16x16x32_bf16 v[56:59], v[144:147], v[184:187], v[56:59]
	v_mfma_f32_16x16x32_bf16 v[44:47], v[136:139], v[192:195], v[44:47]
	v_mfma_f32_16x16x32_bf16 v[40:43], v[144:147], v[192:195], v[40:43]
	v_mfma_f32_16x16x32_bf16 v[28:31], v[136:139], v[200:203], v[28:31]
	v_mfma_f32_16x16x32_bf16 v[24:27], v[144:147], v[200:203], v[24:27]
	v_mfma_f32_16x16x32_bf16 v[12:15], v[136:139], v[208:211], v[12:15]
	v_mfma_f32_16x16x32_bf16 v[8:11], v[144:147], v[208:211], v[8:11]
	v_mfma_f32_16x16x32_bf16 v[60:63], v[140:143], v[188:191], v[60:63]
	v_mfma_f32_16x16x32_bf16 v[56:59], v[150:153], v[188:191], v[56:59]
	v_mfma_f32_16x16x32_bf16 v[44:47], v[140:143], v[196:199], v[44:47]
	v_mfma_f32_16x16x32_bf16 v[40:43], v[150:153], v[196:199], v[40:43]
	v_mfma_f32_16x16x32_bf16 v[28:31], v[140:143], v[204:207], v[28:31]
	v_mfma_f32_16x16x32_bf16 v[24:27], v[150:153], v[204:207], v[24:27]
	v_mfma_f32_16x16x32_bf16 v[12:15], v[140:143], v[212:215], v[12:15]
	v_mfma_f32_16x16x32_bf16 v[8:11], v[150:153], v[212:215], v[8:11]
	s_setprio 0
	s_setprio 1
	v_mfma_f32_16x16x32_bf16 v[52:55], v[168:171], v[184:187], v[52:55]
	v_mfma_f32_16x16x32_bf16 v[48:51], v[176:179], v[184:187], v[48:51]
	v_mfma_f32_16x16x32_bf16 v[36:39], v[168:171], v[192:195], v[36:39]
	v_mfma_f32_16x16x32_bf16 v[32:35], v[176:179], v[192:195], v[32:35]
	v_mfma_f32_16x16x32_bf16 v[20:23], v[168:171], v[200:203], v[20:23]
	v_mfma_f32_16x16x32_bf16 v[16:19], v[176:179], v[200:203], v[16:19]
	v_mfma_f32_16x16x32_bf16 v[4:7], v[168:171], v[208:211], v[4:7]
	v_mfma_f32_16x16x32_bf16 v[0:3], v[176:179], v[208:211], v[0:3]
	v_mfma_f32_16x16x32_bf16 v[52:55], v[172:175], v[188:191], v[52:55]
	v_mfma_f32_16x16x32_bf16 v[48:51], v[180:183], v[188:191], v[48:51]
	v_mfma_f32_16x16x32_bf16 v[36:39], v[172:175], v[196:199], v[36:39]
	v_mfma_f32_16x16x32_bf16 v[32:35], v[180:183], v[196:199], v[32:35]
	v_mfma_f32_16x16x32_bf16 v[20:23], v[172:175], v[204:207], v[20:23]
	v_mfma_f32_16x16x32_bf16 v[16:19], v[180:183], v[204:207], v[16:19]
	v_mfma_f32_16x16x32_bf16 v[4:7], v[172:175], v[212:215], v[4:7]
	v_mfma_f32_16x16x32_bf16 v[0:3], v[180:183], v[212:215], v[0:3]
	s_setprio 0
	s_barrier
	s_add_i32 s8, s8, 2
	s_addk_i32 s6, 0x100
	s_addk_i32 s7, 0x100
	v_add_u32_e32 v128, 0x100, v128
	s_cmp_gt_u32 s8, 29
	v_add_u32_e32 v129, 0x100, v129
	s_cbranch_scc0 .LBB0_615
	s_branch .Lpeel_after_pl1

; #define PG8_BAR __builtin_amdgcn_s_barrier()
; template <class Epi, class Sched, bool ALIGN_EPI, bool F8 = false>
; __device__ __forceinline__ void gemm_phase(LAS unsigned char* lds, const Gemm g, const Sched& S, const Epi& E) {
;     ...
;         if constexpr (ALIGN_EPI) { if (wr == 0) PG8_BAR; }
.Lpeel_after_pl1:
	s_and_b64 vcc, exec, s[30:31]
	s_cbranch_vccz .LBB0_618
	s_barrier

; #define PG8_STAGE_A(bufoff, off) PG8_STAGE_X(bufoff, rsA, g.A, off, voffA)
; #define PG8_STAGE_B(bufoff, off) PG8_STAGE_X(bufoff, rsB, g.Bt, off, voffB)
; #define PG8_WAIT_V(n) asm volatile("s_waitcnt vmcnt(" #n ")" ::: "memory")
; #define PG8_BAR __builtin_amdgcn_s_barrier()
; template <class Epi, class Sched, bool ALIGN_EPI, bool F8 = false>
; __device__ __forceinline__ void gemm_phase(LAS unsigned char* lds, const Gemm g, const Sched& S, const Epi& E) {
;     ...
;     const unsigned lds_w32 = (unsigned)__builtin_amdgcn_readfirstlane((int)((unsigned)(uintptr_t)lds + ldsw));
;     constexpr int KOFF = F8 ? 16 : 1024;
;     const int aoff = lds_byte(wr * 64 + fr, F8 ? fq * 16 : fq * 8), boff = lds_byte(wc * 32 + fr, F8 ? fq * 16 : fq * 8);
;     ...
;     PG8_STAGE_B(PG8_SB(0, 0), cB); PG8_STAGE_B(PG8_SB(0, 1), cB + hstepB); PG8_STAGE_A(PG8_SA(0, 0), cA); PG8_STAGE_A(PG8_SA(0, 1), cA + hstepA);
;     if (wr == 1) PG8_BAR;
;     PG8_WAIT_V(2); PG8_BAR;
;     PG8_STAGE_B(PG8_SB(1, 0), cB + kstep); PG8_STAGE_A(PG8_SA(1, 0), cA + kstep); PG8_STAGE_B(PG8_SB(1, 1), cB + hstepB + kstep);
;     PG8_WAIT_V(6); PG8_BAR;
.LBB0_1096:
	s_add_u32 s38, s22, 0x1ff00000
	s_addc_u32 s39, s23, 0
	s_add_i32 s40, s29, 0x18000
	s_or_b32 s1, s60, 0x80
	s_mov_b32 s14, s10
	s_mov_b32 s15, s11
	s_mov_b32 m0, s40
	s_add_i32 s41, s29, 0x1a000
	s_waitcnt vmcnt(2)
	s_barrier
	buffer_load_dwordx4 v193, s[12:15], s1 offen lds
	s_mov_b32 m0, s41
	s_add_i32 s42, s29, 0x8000
	buffer_load_dwordx4 v195, s[12:15], s1 offen lds
	s_or_b32 s1, s59, 0x80
	s_mov_b32 m0, s42
	s_add_i32 s43, s29, 0xa000
	buffer_load_dwordx4 v192, s[8:11], s1 offen lds
	s_mov_b32 m0, s43
	s_add_i32 s44, s29, 0x1c000
	buffer_load_dwordx4 v194, s[8:11], s1 offen lds
	s_or_b32 s1, s60, 0x20080
	s_mov_b32 m0, s44
	s_add_i32 s45, s29, 0x1e000
	buffer_load_dwordx4 v193, s[12:15], s1 offen lds
	s_mov_b32 m0, s45
	v_bfe_u32 v1, v0, 5, 1
	buffer_load_dwordx4 v195, s[12:15], s1 offen lds
	v_lshlrev_b32_e32 v2, 1, v0
	v_lshlrev_b32_e32 v3, 6, v0
	v_lshlrev_b32_e32 v0, 2, v0
	v_and_b32_e32 v2, 32, v2
	v_and_b32_e32 v3, 0x3c0, v3
	v_and_b32_e32 v0, 32, v0
	s_lshl_b32 s46, s0, 6
	v_or_b32_e32 v4, v3, v2
	s_lshl_b32 s0, s0, 13
	v_lshlrev_b32_e32 v5, 10, v1
	v_bitop3_b32 v2, v3, v0, v2 bitop3:0x36
	v_readlane_b32 s1, v254, 15
	v_or3_b32 v2, v5, s0, v2
	s_lshl_b32 s0, s1, 5
	s_and_b32 s47, s0, 0x60
	s_lshr_b32 s0, s47, 3
	v_or_b32_e32 v1, s0, v1
	v_lshlrev_b32_e32 v1, 10, v1
	v_bitop3_b32 v0, v4, v1, v0 bitop3:0xde
	s_waitcnt vmcnt(6)
	s_add_i32 s48, s29, 0xc000
	s_cmp_lt_u32 s1, 4
	v_add_u32_e32 v0, 0, v0
	s_cselect_b64 s[26:27], -1, 0
	s_add_i32 s49, s29, 0xe000
	s_ashr_i32 s50, s19, 31
	v_mov_b64_e32 v[164:165], 0x1ff
	v_add_u32_e32 v196, 0x10000, v0
	v_add_u32_e32 v197, 0x14000, v0
	v_add_u32_e32 v198, 0, v2
	v_add_u32_e32 v199, 0x18000, v0
	v_add_u32_e32 v200, 0x1c000, v0
	s_movk_i32 s51, 0x3000
	s_mov_b32 s28, 0x3b000000
	s_mov_b32 s52, 0
	s_barrier
	s_mov_b32 s80, 0
	s_branch .LBB0_1099

; template <class Epi, class Sched, bool ALIGN_EPI, bool F8 = false>
; __device__ __forceinline__ void gemm_phase(LAS unsigned char* lds, const Gemm g, const Sched& S, const Epi& E) {
;     ...
;         if (!has_next) break;
; #pragma unroll
;         for (int a = 0; a < 2; ++a)
; #pragma unroll
;             for (int b = 0; b < 2; ++b)
; #pragma unroll
;                 for (int m = 0; m < 4; ++m)
; #pragma unroll
;                     for (int n = 0; n < 2; ++n) acc[a][b][m][n] = (f32x4){0.f, 0.f, 0.f, 0.f};
;         cur = nxt; cA = nA; cB = nB; ++ui;
.LBB0_1098:
	s_mov_b32 s80, 1
	s_andn2_b64 vcc, exec, s[0:1]
	s_mov_b32 s58, s54
	s_mov_b32 s6, s53
	s_mov_b32 s7, s55
	s_mov_b32 s60, s57
	s_mov_b32 s59, s56
	s_cbranch_vccz .LBB0_1146

; #define PG8_STAGE_A(bufoff, off) PG8_STAGE_X(bufoff, rsA, g.A, off, voffA)
; #define PG8_LDA(dst, b, h) do { _Pragma("unroll") for (int m = 0; m < 4; ++m) _Pragma("unroll") for (int k = 0; k < 2; ++k) { const v4i_t f_ = *(const LAS v4i_t*)(lds + PG8_SA(b, h) + aoff + m * 2048 + k * KOFF); dst[m][4 * k] = f_[0]; dst[m][4 * k + 1] = f_[1]; dst[m][4 * k + 2] = f_[2]; dst[m][4 * k + 3] = f_[3]; } } while (0)
; #define PG8_LDB(dst, b, h) do { _Pragma("unroll") for (int n = 0; n < 2; ++n) _Pragma("unroll") for (int k = 0; k < 2; ++k) { const v4i_t f_ = *(const LAS v4i_t*)(lds + PG8_SB(b, h) + boff + n * 2048 + k * KOFF); dst[n][4 * k] = f_[0]; dst[n][4 * k + 1] = f_[1]; dst[n][4 * k + 2] = f_[2]; dst[n][4 * k + 3] = f_[3]; } } while (0)
; #define PG8_WAIT_V(n) asm volatile("s_waitcnt vmcnt(" #n ")" ::: "memory")
; #define PG8_WAIT_L(n) asm volatile("s_waitcnt lgkmcnt(" #n ")" ::: "memory")
; #define PG8_BAR __builtin_amdgcn_s_barrier()
; #define PG8_SCHED __builtin_amdgcn_sched_barrier(0)
; template <class Epi, class Sched, bool ALIGN_EPI, bool F8 = false>
; __device__ __forceinline__ void gemm_phase(LAS unsigned char* lds, const Gemm g, const Sched& S, const Epi& E) {
;     ...
;         for (int t = 0; t < nt; t += 2) {
;             const bool last = (t == nt - 2);
;             const unsigned a1 = cA + (unsigned)(t + 1) * kstep;
;             const unsigned a2 = last ? nA : cA + (unsigned)(t + 2) * kstep; const unsigned b2 = last ? nB : cB + (unsigned)(t + 2) * kstep;
;             const unsigned a3 = a2 + kstep; const unsigned b3 = b2 + kstep;
;             PG8_LDB(B0, 0, 0); PG8_LDB(B1, 0, 1); PG8_SCHED; PG8_LDA(At, 0, 0); PG8_STAGE_A(PG8_SA(1, 1), a1 + hstepA);
;             PG8_WAIT_V(8); PG8_WAIT_L(0); PG8_BAR; PG8_MMA(0, 0, At, B0); PG8_MMA(0, 1, At, B1); PG8_BAR; PG8_SCHED;
;     ...
;         for (int a = 0; a < 2; ++a)
; #pragma unroll
;             for (int b = 0; b < 2; ++b)
; #pragma unroll
;                 for (int m = 0; m < 4; ++m)
; #pragma unroll
;                     for (int n = 0; n < 2; ++n) acc[a][b][m][n] = (f32x4){0.f, 0.f, 0.f, 0.f};
.LBB0_1105:
	s_lshl_b32 s56, s55, 19
	s_lshl_b32 s0, s54, 10
	s_add_i32 s56, s56, s0
	s_and_b64 s[0:1], s[4:5], exec
	s_cselect_b32 s0, s56, s59
	s_lshl_b32 s57, s53, 18
	s_lshl_b32 s1, s54, 21
	s_add_i32 s57, s57, s1
	s_and_b64 s[14:15], s[4:5], exec
	v_mov_b32_e32 v0, 0
	s_cselect_b32 s1, s57, s60
	s_add_i32 s59, s59, 0x40080
	s_addk_i32 s60, 0x100
	s_mov_b32 s61, -2
	v_mov_b32_e32 v1, v0
	v_mov_b32_e32 v2, v0
	v_mov_b32_e32 v3, v0
	v_mov_b32_e32 v4, v0
	v_mov_b32_e32 v5, v0
	v_mov_b32_e32 v6, v0
	v_mov_b32_e32 v7, v0
	v_mov_b32_e32 v8, v0
	v_mov_b32_e32 v9, v0
	v_mov_b32_e32 v10, v0
	v_mov_b32_e32 v11, v0
	v_mov_b32_e32 v12, v0
	v_mov_b32_e32 v13, v0
	v_mov_b32_e32 v14, v0
	v_mov_b32_e32 v15, v0
	v_mov_b32_e32 v16, v0
	v_mov_b32_e32 v17, v0
	v_mov_b32_e32 v18, v0
	v_mov_b32_e32 v19, v0
	v_mov_b32_e32 v20, v0
	v_mov_b32_e32 v21, v0
	v_mov_b32_e32 v22, v0
	v_mov_b32_e32 v23, v0
	v_mov_b32_e32 v24, v0
	v_mov_b32_e32 v25, v0
	v_mov_b32_e32 v26, v0
	v_mov_b32_e32 v27, v0
	v_mov_b32_e32 v28, v0
	v_mov_b32_e32 v29, v0
	v_mov_b32_e32 v30, v0
	v_mov_b32_e32 v31, v0
	v_mov_b32_e32 v32, v0
	v_mov_b32_e32 v33, v0
	v_mov_b32_e32 v34, v0
	v_mov_b32_e32 v35, v0
	v_mov_b32_e32 v36, v0
	v_mov_b32_e32 v37, v0
	v_mov_b32_e32 v38, v0
	v_mov_b32_e32 v39, v0
	v_mov_b32_e32 v40, v0
	v_mov_b32_e32 v41, v0
	v_mov_b32_e32 v42, v0
	v_mov_b32_e32 v43, v0
	v_mov_b32_e32 v44, v0
	v_mov_b32_e32 v45, v0
	v_mov_b32_e32 v46, v0
	v_mov_b32_e32 v47, v0
	v_mov_b32_e32 v48, v0
	v_mov_b32_e32 v49, v0
	v_mov_b32_e32 v50, v0
	v_mov_b32_e32 v51, v0
	v_mov_b32_e32 v52, v0
	v_mov_b32_e32 v53, v0
	v_mov_b32_e32 v54, v0
	v_mov_b32_e32 v55, v0
	v_mov_b32_e32 v56, v0
	v_mov_b32_e32 v57, v0
	v_mov_b32_e32 v58, v0
	v_mov_b32_e32 v59, v0
	v_mov_b32_e32 v60, v0
	v_mov_b32_e32 v61, v0
	v_mov_b32_e32 v62, v0
	v_mov_b32_e32 v63, v0
	v_mov_b32_e32 v64, v0
	v_mov_b32_e32 v65, v0
	v_mov_b32_e32 v66, v0
	v_mov_b32_e32 v67, v0
	v_mov_b32_e32 v68, v0
	v_mov_b32_e32 v69, v0
	v_mov_b32_e32 v70, v0
	v_mov_b32_e32 v71, v0
	v_mov_b32_e32 v72, v0
	v_mov_b32_e32 v73, v0
	v_mov_b32_e32 v74, v0
	v_mov_b32_e32 v75, v0
	v_mov_b32_e32 v76, v0
	v_mov_b32_e32 v77, v0
	v_mov_b32_e32 v78, v0
	v_mov_b32_e32 v79, v0
	v_mov_b32_e32 v80, v0
	v_mov_b32_e32 v81, v0
	v_mov_b32_e32 v82, v0
	v_mov_b32_e32 v83, v0
	v_mov_b32_e32 v84, v0
	v_mov_b32_e32 v85, v0
	v_mov_b32_e32 v86, v0
	v_mov_b32_e32 v87, v0
	v_mov_b32_e32 v88, v0
	v_mov_b32_e32 v89, v0
	v_mov_b32_e32 v90, v0
	v_mov_b32_e32 v91, v0
	v_mov_b32_e32 v92, v0
	v_mov_b32_e32 v93, v0
	v_mov_b32_e32 v94, v0
	v_mov_b32_e32 v95, v0
	v_mov_b32_e32 v96, v0
	v_mov_b32_e32 v97, v0
	v_mov_b32_e32 v98, v0
	v_mov_b32_e32 v99, v0
	v_mov_b32_e32 v100, v0
	v_mov_b32_e32 v101, v0
	v_mov_b32_e32 v102, v0
	v_mov_b32_e32 v103, v0
	v_mov_b32_e32 v104, v0
	v_mov_b32_e32 v105, v0
	v_mov_b32_e32 v106, v0
	v_mov_b32_e32 v107, v0
	v_mov_b32_e32 v108, v0
	v_mov_b32_e32 v109, v0
	v_mov_b32_e32 v110, v0
	v_mov_b32_e32 v111, v0
	v_mov_b32_e32 v112, v0
	v_mov_b32_e32 v113, v0
	v_mov_b32_e32 v114, v0
	v_mov_b32_e32 v115, v0
	v_mov_b32_e32 v116, v0
	v_mov_b32_e32 v117, v0
	v_mov_b32_e32 v118, v0
	v_mov_b32_e32 v119, v0
	v_mov_b32_e32 v120, v0
	v_mov_b32_e32 v121, v0
	v_mov_b32_e32 v122, v0
	v_mov_b32_e32 v123, v0
	v_mov_b32_e32 v124, v0
	v_mov_b32_e32 v125, v0
	v_mov_b32_e32 v126, v0
	v_mov_b32_e32 v127, v0
	s_cmp_lg_u32 s80, 0
	s_cbranch_scc0 .LBB0_1106
	ds_read_b128 v[128:131], v196
	ds_read_b128 v[132:135], v196 offset:16
	ds_read_b128 v[136:139], v196 offset:2048
	ds_read_b128 v[140:143], v196 offset:2064
	ds_read_b128 v[144:147], v197
	ds_read_b128 v[148:151], v197 offset:16
	ds_read_b128 v[152:155], v197 offset:2048
	ds_read_b128 v[156:159], v197 offset:2064
	s_add_i32 s14, s59, 0xfffc0080
	s_cmp_eq_u32 s61, 4
	s_cselect_b32 s64, s0, s14
	s_cselect_b32 s63, s1, s60
	s_add_i32 s62, s64, 0x80
	s_mov_b32 m0, s48
	ds_read_b128 v[166:169], v198
	ds_read_b128 v[170:173], v198 offset:16
	ds_read_b128 v[174:177], v198 offset:2048
	ds_read_b128 v[178:181], v198 offset:2064
	ds_read_b128 v[182:185], v198 offset:4096
	ds_read_b128 v[186:189], v198 offset:4112
	ds_read_b128 v[202:205], v198 offset:6144
	ds_read_b128 v[206:209], v198 offset:6160
	buffer_load_dwordx4 v192, s[8:11], s59 offen lds
	s_mov_b32 m0, s49
	s_nop 0
	buffer_load_dwordx4 v194, s[8:11], s59 offen lds
	s_waitcnt vmcnt(24)
	s_waitcnt lgkmcnt(0)
	s_barrier
	s_setprio 1
	s_waitcnt lgkmcnt(6)
	v_mfma_f32_16x16x128_f8f6f4 v[124:127], v[128:135], v[166:173], v[124:127]
	v_mfma_f32_16x16x128_f8f6f4 v[120:123], v[136:143], v[166:173], v[120:123]
	s_waitcnt lgkmcnt(4)
	v_mfma_f32_16x16x128_f8f6f4 v[116:119], v[128:135], v[174:181], v[116:119]
	v_mfma_f32_16x16x128_f8f6f4 v[112:115], v[136:143], v[174:181], v[112:115]
	s_waitcnt lgkmcnt(2)
	v_mfma_f32_16x16x128_f8f6f4 v[108:111], v[128:135], v[182:189], v[108:111]
	v_mfma_f32_16x16x128_f8f6f4 v[104:107], v[136:143], v[182:189], v[104:107]
	s_waitcnt lgkmcnt(0)
	v_mfma_f32_16x16x128_f8f6f4 v[100:103], v[128:135], v[202:209], v[100:103]
	v_mfma_f32_16x16x128_f8f6f4 v[96:99], v[136:143], v[202:209], v[96:99]
	s_setprio 0
	s_setprio 1
	v_mfma_f32_16x16x128_f8f6f4 v[210:213], v[144:151], v[166:173], v[92:95]
	v_mfma_f32_16x16x128_f8f6f4 v[166:169], v[152:159], v[166:173], v[88:91]
	v_mfma_f32_16x16x128_f8f6f4 v[170:173], v[144:151], v[174:181], v[84:87]
	v_mfma_f32_16x16x128_f8f6f4 v[174:177], v[152:159], v[174:181], v[80:83]
	v_mfma_f32_16x16x128_f8f6f4 v[178:181], v[144:151], v[182:189], v[76:79]
	v_mfma_f32_16x16x128_f8f6f4 v[182:185], v[152:159], v[182:189], v[72:75]
	v_mfma_f32_16x16x128_f8f6f4 v[186:189], v[144:151], v[202:209], v[68:71]
	v_mfma_f32_16x16x128_f8f6f4 v[202:205], v[152:159], v[202:209], v[64:67]
	s_setprio 0
	s_barrier
; #define PG8_STAGE_A(bufoff, off) PG8_STAGE_X(bufoff, rsA, g.A, off, voffA)
; #define PG8_STAGE_B(bufoff, off) PG8_STAGE_X(bufoff, rsB, g.Bt, off, voffB)
; #define PG8_LDA(dst, b, h) do { _Pragma("unroll") for (int m = 0; m < 4; ++m) _Pragma("unroll") for (int k = 0; k < 2; ++k) { const v4i_t f_ = *(const LAS v4i_t*)(lds + PG8_SA(b, h) + aoff + m * 2048 + k * KOFF); dst[m][4 * k] = f_[0]; dst[m][4 * k + 1] = f_[1]; dst[m][4 * k + 2] = f_[2]; dst[m][4 * k + 3] = f_[3]; } } while (0)
; #define PG8_LDB(dst, b, h) do { _Pragma("unroll") for (int n = 0; n < 2; ++n) _Pragma("unroll") for (int k = 0; k < 2; ++k) { const v4i_t f_ = *(const LAS v4i_t*)(lds + PG8_SB(b, h) + boff + n * 2048 + k * KOFF); dst[n][4 * k] = f_[0]; dst[n][4 * k + 1] = f_[1]; dst[n][4 * k + 2] = f_[2]; dst[n][4 * k + 3] = f_[3]; } } while (0)
; #define PG8_WAIT_V(n) asm volatile("s_waitcnt vmcnt(" #n ")" ::: "memory")
; #define PG8_WAIT_L(n) asm volatile("s_waitcnt lgkmcnt(" #n ")" ::: "memory")
; #define PG8_BAR __builtin_amdgcn_s_barrier()
; #define PG8_SCHED __builtin_amdgcn_sched_barrier(0)
; template <class Epi, class Sched, bool ALIGN_EPI, bool F8 = false>
; __device__ __forceinline__ void gemm_phase(LAS unsigned char* lds, const Gemm g, const Sched& S, const Epi& E) {
;     ...
;             PG8_LDA(At, 0, 1); PG8_STAGE_B(PG8_SB(0, 0), b2); PG8_STAGE_B(PG8_SB(0, 1), b2 + hstepB); PG8_STAGE_A(PG8_SA(0, 0), a2);
;             PG8_WAIT_V(8); PG8_WAIT_L(0); PG8_BAR; PG8_MMA(1, 0, At, B0); PG8_MMA(1, 1, At, B1); PG8_BAR; PG8_SCHED;
;             PG8_LDB(B0, 1, 0); PG8_LDB(B1, 1, 1); PG8_SCHED; PG8_LDA(At, 1, 0); PG8_STAGE_A(PG8_SA(0, 1), a2 + hstepA);
;             PG8_WAIT_V(8); PG8_WAIT_L(0); PG8_BAR; PG8_MMA(0, 0, At, B0); PG8_MMA(0, 1, At, B1); PG8_BAR; PG8_SCHED;
;             PG8_LDA(At, 1, 1); PG8_STAGE_B(PG8_SB(1, 0), b3); PG8_STAGE_B(PG8_SB(1, 1), b3 + hstepB); PG8_STAGE_A(PG8_SA(1, 0), a3);
;             PG8_WAIT_V(8); PG8_WAIT_L(0); PG8_BAR; PG8_MMA(1, 0, At, B0); PG8_MMA(1, 1, At, B1); PG8_BAR; PG8_SCHED;
	s_mov_b32 m0, s30
	s_mov_b32 s14, s10
	s_mov_b32 s15, s11
	s_nop 1
	ds_read_b128 v[64:67], v198 offset:16384
	ds_read_b128 v[68:71], v198 offset:16400
	ds_read_b128 v[72:75], v198 offset:18432
	ds_read_b128 v[76:79], v198 offset:18448
	ds_read_b128 v[80:83], v198 offset:20480
	ds_read_b128 v[84:87], v198 offset:20496
	ds_read_b128 v[88:91], v198 offset:22528
	ds_read_b128 v[92:95], v198 offset:22544
	buffer_load_dwordx4 v193, s[12:15], s63 offen lds
	s_mov_b32 m0, s31
	s_add_i32 s65, s63, 0x20000
	buffer_load_dwordx4 v195, s[12:15], s63 offen lds
	s_mov_b32 m0, s33
	s_nop 0
	buffer_load_dwordx4 v193, s[12:15], s65 offen lds
	s_mov_b32 m0, s34
	s_nop 0
	buffer_load_dwordx4 v195, s[12:15], s65 offen lds
	s_mov_b32 m0, s29
	s_nop 0
	buffer_load_dwordx4 v192, s[8:11], s64 offen lds
	s_mov_b32 m0, s35
	s_nop 0
	buffer_load_dwordx4 v194, s[8:11], s64 offen lds
	s_waitcnt vmcnt(24)
	s_waitcnt lgkmcnt(0)
	s_barrier
	s_setprio 1
	s_waitcnt lgkmcnt(6)
	v_mfma_f32_16x16x128_f8f6f4 v[60:63], v[128:135], v[64:71], v[60:63]
	v_mfma_f32_16x16x128_f8f6f4 v[56:59], v[136:143], v[64:71], v[56:59]
	s_waitcnt lgkmcnt(4)
	v_mfma_f32_16x16x128_f8f6f4 v[52:55], v[128:135], v[72:79], v[52:55]
	v_mfma_f32_16x16x128_f8f6f4 v[48:51], v[136:143], v[72:79], v[48:51]
	s_waitcnt lgkmcnt(2)
	v_mfma_f32_16x16x128_f8f6f4 v[206:209], v[128:135], v[80:87], v[44:47]
	v_mfma_f32_16x16x128_f8f6f4 v[214:217], v[136:143], v[80:87], v[40:43]
	s_waitcnt lgkmcnt(0)
	v_mfma_f32_16x16x128_f8f6f4 v[218:221], v[128:135], v[88:95], v[36:39]
	v_mfma_f32_16x16x128_f8f6f4 v[222:225], v[136:143], v[88:95], v[32:35]
	s_setprio 0
	s_setprio 1
	v_mfma_f32_16x16x128_f8f6f4 v[226:229], v[144:151], v[64:71], v[28:31]
	v_mfma_f32_16x16x128_f8f6f4 v[230:233], v[152:159], v[64:71], v[24:27]
	v_mfma_f32_16x16x128_f8f6f4 v[234:237], v[144:151], v[72:79], v[20:23]
	v_mfma_f32_16x16x128_f8f6f4 v[238:241], v[152:159], v[72:79], v[16:19]
	v_mfma_f32_16x16x128_f8f6f4 v[242:245], v[144:151], v[80:87], v[12:15]
	v_mfma_f32_16x16x128_f8f6f4 v[246:249], v[152:159], v[80:87], v[8:11]
	v_mfma_f32_16x16x128_f8f6f4 v[250:253], v[144:151], v[88:95], v[4:7]
	v_mfma_f32_16x16x128_f8f6f4 v[160:163], v[152:159], v[88:95], v[0:3]
	s_setprio 0
	s_barrier
	s_nop 4
	ds_read_b128 v[0:3], v199
	ds_read_b128 v[4:7], v199 offset:16
	ds_read_b128 v[8:11], v199 offset:2048
	ds_read_b128 v[12:15], v199 offset:2064
	ds_read_b128 v[128:131], v200
	ds_read_b128 v[132:135], v200 offset:16
	ds_read_b128 v[136:139], v200 offset:2048
	ds_read_b128 v[140:143], v200 offset:2064
	s_add_i32 s64, s64, 0x40000
	s_mov_b32 m0, s36
	ds_read_b128 v[16:19], v198 offset:32768
	ds_read_b128 v[20:23], v198 offset:32784
	ds_read_b128 v[24:27], v198 offset:34816
	ds_read_b128 v[28:31], v198 offset:34832
	ds_read_b128 v[32:35], v198 offset:36864
	ds_read_b128 v[36:39], v198 offset:36880
	ds_read_b128 v[40:43], v198 offset:38912
	ds_read_b128 v[44:47], v198 offset:38928
	buffer_load_dwordx4 v192, s[8:11], s64 offen lds
	s_mov_b32 m0, s37
	s_nop 0
	buffer_load_dwordx4 v194, s[8:11], s64 offen lds
	s_waitcnt vmcnt(8)
	s_waitcnt lgkmcnt(0)
	s_barrier
	s_setprio 1
	s_waitcnt lgkmcnt(6)
	v_mfma_f32_16x16x128_f8f6f4 v[124:127], v[0:7], v[16:23], v[124:127]
	v_mfma_f32_16x16x128_f8f6f4 v[120:123], v[8:15], v[16:23], v[120:123]
	s_waitcnt lgkmcnt(4)
	v_mfma_f32_16x16x128_f8f6f4 v[116:119], v[0:7], v[24:31], v[116:119]
	v_mfma_f32_16x16x128_f8f6f4 v[112:115], v[8:15], v[24:31], v[112:115]
	s_waitcnt lgkmcnt(2)
	v_mfma_f32_16x16x128_f8f6f4 v[108:111], v[0:7], v[32:39], v[108:111]
	v_mfma_f32_16x16x128_f8f6f4 v[104:107], v[8:15], v[32:39], v[104:107]
	s_waitcnt lgkmcnt(0)
	v_mfma_f32_16x16x128_f8f6f4 v[100:103], v[0:7], v[40:47], v[100:103]
	v_mfma_f32_16x16x128_f8f6f4 v[96:99], v[8:15], v[40:47], v[96:99]
	s_setprio 0
	s_setprio 1
	v_mfma_f32_16x16x128_f8f6f4 v[92:95], v[128:135], v[16:23], v[210:213]
	v_mfma_f32_16x16x128_f8f6f4 v[88:91], v[136:143], v[16:23], v[166:169]
	v_mfma_f32_16x16x128_f8f6f4 v[84:87], v[128:135], v[24:31], v[170:173]
	v_mfma_f32_16x16x128_f8f6f4 v[80:83], v[136:143], v[24:31], v[174:177]
	v_mfma_f32_16x16x128_f8f6f4 v[76:79], v[128:135], v[32:39], v[178:181]
	v_mfma_f32_16x16x128_f8f6f4 v[72:75], v[136:143], v[32:39], v[182:185]
	v_mfma_f32_16x16x128_f8f6f4 v[68:71], v[128:135], v[40:47], v[186:189]
	v_mfma_f32_16x16x128_f8f6f4 v[64:67], v[136:143], v[40:47], v[202:205]
	s_setprio 0
	s_barrier
	s_mov_b32 m0, s40
	s_add_i32 s64, s63, 0x80
	ds_read_b128 v[16:19], v198 offset:49152
	ds_read_b128 v[20:23], v198 offset:49168
	ds_read_b128 v[144:147], v198 offset:51200
	ds_read_b128 v[148:151], v198 offset:51216
	ds_read_b128 v[152:155], v198 offset:53248
	ds_read_b128 v[156:159], v198 offset:53264
	ds_read_b128 v[166:169], v198 offset:55296
	ds_read_b128 v[170:173], v198 offset:55312
	buffer_load_dwordx4 v193, s[12:15], s64 offen lds
	s_mov_b32 m0, s41
	s_add_i32 s63, s63, 0x20080
	buffer_load_dwordx4 v195, s[12:15], s64 offen lds
	s_mov_b32 m0, s44
	s_nop 0
	buffer_load_dwordx4 v193, s[12:15], s63 offen lds
	s_mov_b32 m0, s45
	s_nop 0
	buffer_load_dwordx4 v195, s[12:15], s63 offen lds
	s_mov_b32 m0, s42
	s_nop 0
	buffer_load_dwordx4 v192, s[8:11], s62 offen lds
	s_mov_b32 m0, s43
	s_nop 0
	buffer_load_dwordx4 v194, s[8:11], s62 offen lds
	s_waitcnt vmcnt(8)
	s_waitcnt lgkmcnt(0)
	s_barrier
	s_setprio 1
	s_waitcnt lgkmcnt(6)
	v_mfma_f32_16x16x128_f8f6f4 v[60:63], v[0:7], v[16:23], v[60:63]
	v_mfma_f32_16x16x128_f8f6f4 v[56:59], v[8:15], v[16:23], v[56:59]
	s_waitcnt lgkmcnt(4)
	v_mfma_f32_16x16x128_f8f6f4 v[52:55], v[0:7], v[144:151], v[52:55]
	v_mfma_f32_16x16x128_f8f6f4 v[48:51], v[8:15], v[144:151], v[48:51]
	s_waitcnt lgkmcnt(2)
	v_mfma_f32_16x16x128_f8f6f4 v[44:47], v[0:7], v[152:159], v[206:209]
	v_mfma_f32_16x16x128_f8f6f4 v[40:43], v[8:15], v[152:159], v[214:217]
	s_waitcnt lgkmcnt(0)
	v_mfma_f32_16x16x128_f8f6f4 v[36:39], v[0:7], v[166:173], v[218:221]
	v_mfma_f32_16x16x128_f8f6f4 v[32:35], v[8:15], v[166:173], v[222:225]
	s_setprio 0
	s_setprio 1
	v_mfma_f32_16x16x128_f8f6f4 v[28:31], v[128:135], v[16:23], v[226:229]
	v_mfma_f32_16x16x128_f8f6f4 v[24:27], v[136:143], v[16:23], v[230:233]
	v_mfma_f32_16x16x128_f8f6f4 v[20:23], v[128:135], v[144:151], v[234:237]
	v_mfma_f32_16x16x128_f8f6f4 v[16:19], v[136:143], v[144:151], v[238:241]
	v_mfma_f32_16x16x128_f8f6f4 v[12:15], v[128:135], v[152:159], v[242:245]
	v_mfma_f32_16x16x128_f8f6f4 v[8:11], v[136:143], v[152:159], v[246:249]
	v_mfma_f32_16x16x128_f8f6f4 v[4:7], v[128:135], v[166:173], v[250:253]
	v_mfma_f32_16x16x128_f8f6f4 v[0:3], v[136:143], v[166:173], v[160:163]
	s_setprio 0
	s_barrier
	s_add_i32 s61, s61, 2
	s_addk_i32 s59, 0x100
	s_addk_i32 s60, 0x100
	s_cmp_gt_u32 s61, 5
	s_cbranch_scc0 .LBB0_1106
	s_branch .Lpeel_after_pl2

; #define PG8_BAR __builtin_amdgcn_s_barrier()
; template <class Epi, class Sched, bool ALIGN_EPI, bool F8 = false>
; __device__ __forceinline__ void gemm_phase(LAS unsigned char* lds, const Gemm g, const Sched& S, const Epi& E) {
;     ...
;         if constexpr (ALIGN_EPI) { if (wr == 0) PG8_BAR; }
.Lpeel_after_pl2:
	s_and_b64 vcc, exec, s[26:27]
	s_cbranch_vccz .LBB0_1109
	s_barrier

; #define PG8_STAGE_A(bufoff, off) PG8_STAGE_X(bufoff, rsA, g.A, off, voffA)
; #define PG8_STAGE_B(bufoff, off) PG8_STAGE_X(bufoff, rsB, g.Bt, off, voffB)
; #define PG8_WAIT_V(n) asm volatile("s_waitcnt vmcnt(" #n ")" ::: "memory")
; #define PG8_BAR __builtin_amdgcn_s_barrier()
; template <class Epi, class Sched, bool ALIGN_EPI, bool F8 = false>
; __device__ __forceinline__ void gemm_phase(LAS unsigned char* lds, const Gemm g, const Sched& S, const Epi& E) {
;     ...
;     const unsigned lds_w32 = (unsigned)__builtin_amdgcn_readfirstlane((int)((unsigned)(uintptr_t)lds + ldsw));
;     constexpr int KOFF = F8 ? 16 : 1024;
;     const int aoff = lds_byte(wr * 64 + fr, F8 ? fq * 16 : fq * 8), boff = lds_byte(wc * 32 + fr, F8 ? fq * 16 : fq * 8);
;     ...
;     PG8_STAGE_B(PG8_SB(0, 0), cB); PG8_STAGE_B(PG8_SB(0, 1), cB + hstepB); PG8_STAGE_A(PG8_SA(0, 0), cA); PG8_STAGE_A(PG8_SA(0, 1), cA + hstepA);
;     if (wr == 1) PG8_BAR;
;     PG8_WAIT_V(2); PG8_BAR;
;     PG8_STAGE_B(PG8_SB(1, 0), cB + kstep); PG8_STAGE_A(PG8_SA(1, 0), cA + kstep); PG8_STAGE_B(PG8_SB(1, 1), cB + hstepB + kstep);
;     PG8_WAIT_V(6); PG8_BAR;
.LBB0_1154:
	s_or_b32 s1, s42, 0x80
	s_add_i32 m0, s24, 0x18000
	v_add_u32_e32 v6, s1, v177
	s_waitcnt vmcnt(2)
	s_barrier
	global_load_lds_dwordx4 v6, s[6:7]
	v_add_u32_e32 v6, s1, v179
	s_add_i32 m0, s24, 0x1a000
	s_or_b32 s1, s43, 0x80
	s_add_i32 s29, s24, 0x8000
	global_load_lds_dwordx4 v6, s[6:7]
	v_add_u32_e32 v6, s1, v176
	s_mov_b32 m0, s29
	s_add_i32 s30, s24, 0xa000
	global_load_lds_dwordx4 v6, s[4:5]
	v_add_u32_e32 v6, s1, v178
	s_mov_b32 m0, s30
	s_or_b32 s1, s42, 0x40080
	global_load_lds_dwordx4 v6, s[4:5]
	s_add_i32 m0, s24, 0x1c000
	v_add_u32_e32 v6, s1, v177
	global_load_lds_dwordx4 v6, s[6:7]
	v_add_u32_e32 v6, s1, v179
	s_add_i32 m0, s24, 0x1e000
	v_lshlrev_b32_e32 v7, 6, v191
	global_load_lds_dwordx4 v6, s[6:7]
	v_and_b32_e32 v6, 48, v191
	s_movk_i32 s1, 0x3c0
	v_and_or_b32 v6, v7, s1, v6
	v_lshlrev_b32_e32 v7, 2, v191
	s_lshl_b32 s31, s0, 6
	s_lshl_b32 s0, s0, 13
	v_and_b32_e32 v7, 32, v7
	v_readlane_b32 s1, v254, 15
	v_bitop3_b32 v8, v6, s0, v7 bitop3:0xde
	s_lshl_b32 s0, s1, 5
	s_and_b32 s33, s0, 0x60
	s_lshl_b32 s0, s33, 7
	v_bitop3_b32 v180, v6, s0, v7 bitop3:0xde
	v_lshlrev_b32_e32 v6, 14, v3
	v_and_b32_e32 v6, 0xffff8000, v6
	v_lshl_add_u32 v4, v4, 11, v6
	v_and_b32_e32 v3, 1, v3
	s_mov_b32 s0, 0x40080
	v_lshl_or_b32 v3, v3, 6, v4
	v_lshlrev_b32_e32 v4, 1, v5
	s_cmp_lt_u32 s1, 4
	v_add3_u32 v181, v3, v4, s0
	v_lshlrev_b32_e32 v3, 14, v0
	s_cselect_b64 s[10:11], -1, 0
	s_ashr_i32 s34, s18, 31
	v_and_b32_e32 v3, 0xffff8000, v3
	s_waitcnt vmcnt(6)
	s_add_u32 s12, s22, 0x1ff02000
	v_lshl_add_u32 v1, v1, 11, v3
	v_and_b32_e32 v0, 1, v0
	s_addc_u32 s13, s23, 0
	v_lshl_or_b32 v0, v0, 6, v1
	v_lshlrev_b32_e32 v1, 1, v2
	s_add_i32 s22, 0, 0x10000
	s_add_i32 s23, 0, 0x14000
	v_add3_u32 v182, v0, v1, s0
	v_mov_b64_e32 v[156:157], 0x200
	v_mov_b64_e32 v[158:159], 0x1ff
	v_add_u32_e32 v183, s22, v180
	v_add_u32_e32 v184, s23, v180
	v_add_u32_e32 v185, 0, v8
	s_movk_i32 s35, 0x3000
	s_barrier
	s_mov_b32 s80, 0
	s_branch .LBB0_1157

; template <class Epi, class Sched, bool ALIGN_EPI, bool F8 = false>
; __device__ __forceinline__ void gemm_phase(LAS unsigned char* lds, const Gemm g, const Sched& S, const Epi& E) {
;     ...
;         if (!has_next) break;
; #pragma unroll
;         for (int a = 0; a < 2; ++a)
; #pragma unroll
;             for (int b = 0; b < 2; ++b)
; #pragma unroll
;                 for (int m = 0; m < 4; ++m)
; #pragma unroll
;                     for (int n = 0; n < 2; ++n) acc[a][b][m][n] = (f32x4){0.f, 0.f, 0.f, 0.f};
;         cur = nxt; cA = nA; cB = nB; ++ui;
.LBB0_1156:
	s_mov_b32 s80, 1
	s_andn2_b64 vcc, exec, s[0:1]
	s_mov_b32 s40, s36
	s_mov_b32 s41, s37
	s_mov_b32 s42, s39
	s_mov_b32 s43, s38
	s_cbranch_vccz .LBB0_1170

; #define PG8_STAGE_A(bufoff, off) PG8_STAGE_X(bufoff, rsA, g.A, off, voffA)
; #define PG8_LDA(dst, b, h) do { _Pragma("unroll") for (int m = 0; m < 4; ++m) _Pragma("unroll") for (int k = 0; k < 2; ++k) { const v4i_t f_ = *(const LAS v4i_t*)(lds + PG8_SA(b, h) + aoff + m * 2048 + k * KOFF); dst[m][4 * k] = f_[0]; dst[m][4 * k + 1] = f_[1]; dst[m][4 * k + 2] = f_[2]; dst[m][4 * k + 3] = f_[3]; } } while (0)
; #define PG8_LDB(dst, b, h) do { _Pragma("unroll") for (int n = 0; n < 2; ++n) _Pragma("unroll") for (int k = 0; k < 2; ++k) { const v4i_t f_ = *(const LAS v4i_t*)(lds + PG8_SB(b, h) + boff + n * 2048 + k * KOFF); dst[n][4 * k] = f_[0]; dst[n][4 * k + 1] = f_[1]; dst[n][4 * k + 2] = f_[2]; dst[n][4 * k + 3] = f_[3]; } } while (0)
; #define PG8_WAIT_V(n) asm volatile("s_waitcnt vmcnt(" #n ")" ::: "memory")
; #define PG8_WAIT_L(n) asm volatile("s_waitcnt lgkmcnt(" #n ")" ::: "memory")
; #define PG8_BAR __builtin_amdgcn_s_barrier()
; #define PG8_SCHED __builtin_amdgcn_sched_barrier(0)
; template <class Epi, class Sched, bool ALIGN_EPI, bool F8 = false>
; __device__ __forceinline__ void gemm_phase(LAS unsigned char* lds, const Gemm g, const Sched& S, const Epi& E) {
;     ...
;         for (int t = 0; t < nt; t += 2) {
;             const bool last = (t == nt - 2);
;             const unsigned a1 = cA + (unsigned)(t + 1) * kstep;
;             const unsigned a2 = last ? nA : cA + (unsigned)(t + 2) * kstep; const unsigned b2 = last ? nB : cB + (unsigned)(t + 2) * kstep;
;             const unsigned a3 = a2 + kstep; const unsigned b3 = b2 + kstep;
;             PG8_LDB(B0, 0, 0); PG8_LDB(B1, 0, 1); PG8_SCHED; PG8_LDA(At, 0, 0); PG8_STAGE_A(PG8_SA(1, 1), a1 + hstepA);
;             PG8_WAIT_V(8); PG8_WAIT_L(0); PG8_BAR; PG8_MMA(0, 0, At, B0); PG8_MMA(0, 1, At, B1); PG8_BAR; PG8_SCHED;
;     ...
;         for (int a = 0; a < 2; ++a)
; #pragma unroll
;             for (int b = 0; b < 2; ++b)
; #pragma unroll
;                 for (int m = 0; m < 4; ++m)
; #pragma unroll
;                     for (int n = 0; n < 2; ++n) acc[a][b][m][n] = (f32x4){0.f, 0.f, 0.f, 0.f};
.LBB0_1163:
	s_lshl_b32 s38, s37, 19
	s_and_b64 s[0:1], s[2:3], exec
	s_cselect_b32 s0, s38, s43
	s_lshl_b32 s39, s36, 19
	s_and_b64 s[44:45], s[2:3], exec
	v_mov_b32_e32 v0, 0
	s_cselect_b32 s1, s39, s42
	v_add_u32_e32 v128, s43, v181
	v_add_u32_e32 v129, s43, v182
	s_addk_i32 s42, 0x100
	s_addk_i32 s43, 0x100
	s_mov_b32 s44, -2
	v_mov_b32_e32 v1, v0
	v_mov_b32_e32 v2, v0
	v_mov_b32_e32 v3, v0
	v_mov_b32_e32 v4, v0
	v_mov_b32_e32 v5, v0
	v_mov_b32_e32 v6, v0
	v_mov_b32_e32 v7, v0
	v_mov_b32_e32 v8, v0
	v_mov_b32_e32 v9, v0
	v_mov_b32_e32 v10, v0
	v_mov_b32_e32 v11, v0
	v_mov_b32_e32 v12, v0
	v_mov_b32_e32 v13, v0
	v_mov_b32_e32 v14, v0
	v_mov_b32_e32 v15, v0
	v_mov_b32_e32 v16, v0
	v_mov_b32_e32 v17, v0
	v_mov_b32_e32 v18, v0
	v_mov_b32_e32 v19, v0
	v_mov_b32_e32 v20, v0
	v_mov_b32_e32 v21, v0
	v_mov_b32_e32 v22, v0
	v_mov_b32_e32 v23, v0
	v_mov_b32_e32 v24, v0
	v_mov_b32_e32 v25, v0
	v_mov_b32_e32 v26, v0
	v_mov_b32_e32 v27, v0
	v_mov_b32_e32 v28, v0
	v_mov_b32_e32 v29, v0
	v_mov_b32_e32 v30, v0
	v_mov_b32_e32 v31, v0
	v_mov_b32_e32 v32, v0
	v_mov_b32_e32 v33, v0
	v_mov_b32_e32 v34, v0
	v_mov_b32_e32 v35, v0
	v_mov_b32_e32 v36, v0
	v_mov_b32_e32 v37, v0
	v_mov_b32_e32 v38, v0
	v_mov_b32_e32 v39, v0
	v_mov_b32_e32 v40, v0
	v_mov_b32_e32 v41, v0
	v_mov_b32_e32 v42, v0
	v_mov_b32_e32 v43, v0
	v_mov_b32_e32 v44, v0
	v_mov_b32_e32 v45, v0
	v_mov_b32_e32 v46, v0
	v_mov_b32_e32 v47, v0
	v_mov_b32_e32 v48, v0
	v_mov_b32_e32 v49, v0
	v_mov_b32_e32 v50, v0
	v_mov_b32_e32 v51, v0
	v_mov_b32_e32 v52, v0
	v_mov_b32_e32 v53, v0
	v_mov_b32_e32 v54, v0
	v_mov_b32_e32 v55, v0
	v_mov_b32_e32 v56, v0
	v_mov_b32_e32 v57, v0
	v_mov_b32_e32 v58, v0
	v_mov_b32_e32 v59, v0
	v_mov_b32_e32 v60, v0
	v_mov_b32_e32 v61, v0
	v_mov_b32_e32 v62, v0
	v_mov_b32_e32 v63, v0
	v_mov_b32_e32 v64, v0
	v_mov_b32_e32 v65, v0
	v_mov_b32_e32 v66, v0
	v_mov_b32_e32 v67, v0
	v_mov_b32_e32 v68, v0
	v_mov_b32_e32 v69, v0
	v_mov_b32_e32 v70, v0
	v_mov_b32_e32 v71, v0
	v_mov_b32_e32 v72, v0
	v_mov_b32_e32 v73, v0
	v_mov_b32_e32 v74, v0
	v_mov_b32_e32 v75, v0
	v_mov_b32_e32 v76, v0
	v_mov_b32_e32 v77, v0
	v_mov_b32_e32 v78, v0
	v_mov_b32_e32 v79, v0
	v_mov_b32_e32 v80, v0
	v_mov_b32_e32 v81, v0
	v_mov_b32_e32 v82, v0
	v_mov_b32_e32 v83, v0
	v_mov_b32_e32 v84, v0
	v_mov_b32_e32 v85, v0
	v_mov_b32_e32 v86, v0
	v_mov_b32_e32 v87, v0
	v_mov_b32_e32 v88, v0
	v_mov_b32_e32 v89, v0
	v_mov_b32_e32 v90, v0
	v_mov_b32_e32 v91, v0
	v_mov_b32_e32 v92, v0
	v_mov_b32_e32 v93, v0
	v_mov_b32_e32 v94, v0
	v_mov_b32_e32 v95, v0
	v_mov_b32_e32 v96, v0
	v_mov_b32_e32 v97, v0
	v_mov_b32_e32 v98, v0
	v_mov_b32_e32 v99, v0
	v_mov_b32_e32 v100, v0
	v_mov_b32_e32 v101, v0
	v_mov_b32_e32 v102, v0
	v_mov_b32_e32 v103, v0
	v_mov_b32_e32 v104, v0
	v_mov_b32_e32 v105, v0
	v_mov_b32_e32 v106, v0
	v_mov_b32_e32 v107, v0
	v_mov_b32_e32 v108, v0
	v_mov_b32_e32 v109, v0
	v_mov_b32_e32 v110, v0
	v_mov_b32_e32 v111, v0
	v_mov_b32_e32 v112, v0
	v_mov_b32_e32 v113, v0
	v_mov_b32_e32 v114, v0
	v_mov_b32_e32 v115, v0
	v_mov_b32_e32 v116, v0
	v_mov_b32_e32 v117, v0
	v_mov_b32_e32 v118, v0
	v_mov_b32_e32 v119, v0
	v_mov_b32_e32 v120, v0
	v_mov_b32_e32 v121, v0
	v_mov_b32_e32 v122, v0
	v_mov_b32_e32 v123, v0
	v_mov_b32_e32 v124, v0
	v_mov_b32_e32 v125, v0
	v_mov_b32_e32 v126, v0
	v_mov_b32_e32 v127, v0
	s_cmp_lg_u32 s80, 0
	s_cbranch_scc0 .LBB0_1164
	ds_read_b128 v[130:133], v183
	ds_read_b128 v[134:137], v183 offset:1024
	ds_read_b128 v[138:141], v183 offset:2048
	ds_read_b128 v[142:145], v183 offset:3072
	ds_read_b128 v[146:149], v184
	ds_read_b128 v[150:153], v184 offset:1024
	ds_read_b128 v[160:163], v184 offset:2048
	ds_read_b128 v[164:167], v184 offset:3072
	s_cmp_eq_u32 s44, 12
	s_cselect_b32 s47, s0, s43
	s_cselect_b32 s46, s1, s42
	s_or_b32 s45, s47, 0x80
	s_add_i32 m0, s24, 0xc000
	ds_read_b128 v[168:171], v185
	ds_read_b128 v[172:175], v185 offset:1024
	ds_read_b128 v[186:189], v185 offset:2048
	ds_read_b128 v[192:195], v185 offset:3072
	ds_read_b128 v[196:199], v185 offset:4096
	ds_read_b128 v[200:203], v185 offset:5120
	ds_read_b128 v[204:207], v185 offset:6144
	ds_read_b128 v[208:211], v185 offset:7168
	global_load_lds_dwordx4 v129, s[4:5]
	s_add_i32 m0, s24, 0xe000
	s_nop 0
	global_load_lds_dwordx4 v128, s[4:5]
	s_waitcnt vmcnt(24)
	s_waitcnt lgkmcnt(0)
	s_barrier
	s_setprio 1
	s_waitcnt lgkmcnt(0)
	v_mfma_f32_16x16x32_bf16 v[124:127], v[130:133], v[168:171], v[124:127]
	v_mfma_f32_16x16x32_bf16 v[120:123], v[138:141], v[168:171], v[120:123]
	v_mfma_f32_16x16x32_bf16 v[116:119], v[130:133], v[186:189], v[116:119]
	v_mfma_f32_16x16x32_bf16 v[112:115], v[138:141], v[186:189], v[112:115]
	v_mfma_f32_16x16x32_bf16 v[108:111], v[130:133], v[196:199], v[108:111]
	v_mfma_f32_16x16x32_bf16 v[104:107], v[138:141], v[196:199], v[104:107]
	v_mfma_f32_16x16x32_bf16 v[100:103], v[130:133], v[204:207], v[100:103]
	v_mfma_f32_16x16x32_bf16 v[96:99], v[138:141], v[204:207], v[96:99]
	v_mfma_f32_16x16x32_bf16 v[124:127], v[134:137], v[172:175], v[124:127]
	v_mfma_f32_16x16x32_bf16 v[120:123], v[142:145], v[172:175], v[120:123]
	v_mfma_f32_16x16x32_bf16 v[116:119], v[134:137], v[192:195], v[116:119]
	v_mfma_f32_16x16x32_bf16 v[112:115], v[142:145], v[192:195], v[112:115]
	v_mfma_f32_16x16x32_bf16 v[108:111], v[134:137], v[200:203], v[108:111]
	v_mfma_f32_16x16x32_bf16 v[104:107], v[142:145], v[200:203], v[104:107]
	v_mfma_f32_16x16x32_bf16 v[100:103], v[134:137], v[208:211], v[100:103]
	v_mfma_f32_16x16x32_bf16 v[96:99], v[142:145], v[208:211], v[96:99]
	s_setprio 0
	s_setprio 1
	v_mfma_f32_16x16x32_bf16 v[92:95], v[146:149], v[168:171], v[92:95]
	v_mfma_f32_16x16x32_bf16 v[88:91], v[160:163], v[168:171], v[88:91]
	v_mfma_f32_16x16x32_bf16 v[84:87], v[146:149], v[186:189], v[84:87]
	v_mfma_f32_16x16x32_bf16 v[80:83], v[160:163], v[186:189], v[80:83]
	v_mfma_f32_16x16x32_bf16 v[76:79], v[146:149], v[196:199], v[76:79]
	v_mfma_f32_16x16x32_bf16 v[72:75], v[160:163], v[196:199], v[72:75]
	v_mfma_f32_16x16x32_bf16 v[68:71], v[146:149], v[204:207], v[68:71]
	v_mfma_f32_16x16x32_bf16 v[64:67], v[160:163], v[204:207], v[64:67]
	v_mfma_f32_16x16x32_bf16 v[92:95], v[150:153], v[172:175], v[92:95]
	v_mfma_f32_16x16x32_bf16 v[88:91], v[164:167], v[172:175], v[88:91]
	v_mfma_f32_16x16x32_bf16 v[84:87], v[150:153], v[192:195], v[84:87]
	v_mfma_f32_16x16x32_bf16 v[80:83], v[164:167], v[192:195], v[80:83]
	v_mfma_f32_16x16x32_bf16 v[76:79], v[150:153], v[200:203], v[76:79]
	v_mfma_f32_16x16x32_bf16 v[72:75], v[164:167], v[200:203], v[72:75]
	v_mfma_f32_16x16x32_bf16 v[68:71], v[150:153], v[208:211], v[68:71]
	v_mfma_f32_16x16x32_bf16 v[64:67], v[164:167], v[208:211], v[64:67]
	s_setprio 0
	s_barrier
; #define PG8_STAGE_A(bufoff, off) PG8_STAGE_X(bufoff, rsA, g.A, off, voffA)
; #define PG8_STAGE_B(bufoff, off) PG8_STAGE_X(bufoff, rsB, g.Bt, off, voffB)
; #define PG8_LDA(dst, b, h) do { _Pragma("unroll") for (int m = 0; m < 4; ++m) _Pragma("unroll") for (int k = 0; k < 2; ++k) { const v4i_t f_ = *(const LAS v4i_t*)(lds + PG8_SA(b, h) + aoff + m * 2048 + k * KOFF); dst[m][4 * k] = f_[0]; dst[m][4 * k + 1] = f_[1]; dst[m][4 * k + 2] = f_[2]; dst[m][4 * k + 3] = f_[3]; } } while (0)
; #define PG8_LDB(dst, b, h) do { _Pragma("unroll") for (int n = 0; n < 2; ++n) _Pragma("unroll") for (int k = 0; k < 2; ++k) { const v4i_t f_ = *(const LAS v4i_t*)(lds + PG8_SB(b, h) + boff + n * 2048 + k * KOFF); dst[n][4 * k] = f_[0]; dst[n][4 * k + 1] = f_[1]; dst[n][4 * k + 2] = f_[2]; dst[n][4 * k + 3] = f_[3]; } } while (0)
; #define PG8_WAIT_V(n) asm volatile("s_waitcnt vmcnt(" #n ")" ::: "memory")
; #define PG8_WAIT_L(n) asm volatile("s_waitcnt lgkmcnt(" #n ")" ::: "memory")
; #define PG8_BAR __builtin_amdgcn_s_barrier()
; #define PG8_SCHED __builtin_amdgcn_sched_barrier(0)
; template <class Epi, class Sched, bool ALIGN_EPI, bool F8 = false>
; __device__ __forceinline__ void gemm_phase(LAS unsigned char* lds, const Gemm g, const Sched& S, const Epi& E) {
;     ...
;             PG8_LDA(At, 0, 1); PG8_STAGE_B(PG8_SB(0, 0), b2); PG8_STAGE_B(PG8_SB(0, 1), b2 + hstepB); PG8_STAGE_A(PG8_SA(0, 0), a2);
;             PG8_WAIT_V(8); PG8_WAIT_L(0); PG8_BAR; PG8_MMA(1, 0, At, B0); PG8_MMA(1, 1, At, B1); PG8_BAR; PG8_SCHED;
;             PG8_LDB(B0, 1, 0); PG8_LDB(B1, 1, 1); PG8_SCHED; PG8_LDA(At, 1, 0); PG8_STAGE_A(PG8_SA(0, 1), a2 + hstepA);
	s_add_i32 s48, s22, s15
	v_add_u32_e32 v154, s46, v177
	s_mov_b32 m0, s48
	ds_read_b128 v[168:171], v185 offset:16384
	ds_read_b128 v[172:175], v185 offset:17408
	ds_read_b128 v[186:189], v185 offset:18432
	ds_read_b128 v[192:195], v185 offset:19456
	ds_read_b128 v[196:199], v185 offset:20480
	ds_read_b128 v[200:203], v185 offset:21504
	ds_read_b128 v[204:207], v185 offset:22528
	ds_read_b128 v[208:211], v185 offset:23552
	global_load_lds_dwordx4 v154, s[6:7]
	v_add_u32_e32 v154, s46, v179
	s_add_i32 m0, s48, 0x2000
	s_add_i32 s48, s46, 0x40000
	s_add_i32 s49, s23, s15
	global_load_lds_dwordx4 v154, s[6:7]
	v_add_u32_e32 v154, s48, v177
	s_mov_b32 m0, s49
	s_nop 0
	global_load_lds_dwordx4 v154, s[6:7]
	v_add_u32_e32 v154, s48, v179
	s_add_i32 m0, s49, 0x2000
	s_nop 0
	global_load_lds_dwordx4 v154, s[6:7]
	v_add_u32_e32 v154, s47, v176
	s_mov_b32 m0, s24
	s_nop 0
	global_load_lds_dwordx4 v154, s[4:5]
	v_add_u32_e32 v154, s47, v178
	s_mov_b32 m0, s25
	s_nop 0
	global_load_lds_dwordx4 v154, s[4:5]
	s_waitcnt vmcnt(24)
	s_waitcnt lgkmcnt(0)
	s_barrier
	s_setprio 1
	s_waitcnt lgkmcnt(0)
	v_mfma_f32_16x16x32_bf16 v[60:63], v[130:133], v[168:171], v[60:63]
	v_mfma_f32_16x16x32_bf16 v[56:59], v[138:141], v[168:171], v[56:59]
	v_mfma_f32_16x16x32_bf16 v[52:55], v[130:133], v[186:189], v[52:55]
	v_mfma_f32_16x16x32_bf16 v[48:51], v[138:141], v[186:189], v[48:51]
	v_mfma_f32_16x16x32_bf16 v[44:47], v[130:133], v[196:199], v[44:47]
	v_mfma_f32_16x16x32_bf16 v[40:43], v[138:141], v[196:199], v[40:43]
	v_mfma_f32_16x16x32_bf16 v[36:39], v[130:133], v[204:207], v[36:39]
	v_mfma_f32_16x16x32_bf16 v[32:35], v[138:141], v[204:207], v[32:35]
	v_mfma_f32_16x16x32_bf16 v[60:63], v[134:137], v[172:175], v[60:63]
	v_mfma_f32_16x16x32_bf16 v[56:59], v[142:145], v[172:175], v[56:59]
	v_mfma_f32_16x16x32_bf16 v[52:55], v[134:137], v[192:195], v[52:55]
	v_mfma_f32_16x16x32_bf16 v[48:51], v[142:145], v[192:195], v[48:51]
	v_mfma_f32_16x16x32_bf16 v[44:47], v[134:137], v[200:203], v[44:47]
	v_mfma_f32_16x16x32_bf16 v[40:43], v[142:145], v[200:203], v[40:43]
	v_mfma_f32_16x16x32_bf16 v[36:39], v[134:137], v[208:211], v[36:39]
	v_mfma_f32_16x16x32_bf16 v[32:35], v[142:145], v[208:211], v[32:35]
	s_setprio 0
	s_setprio 1
	v_mfma_f32_16x16x32_bf16 v[28:31], v[146:149], v[168:171], v[28:31]
	v_mfma_f32_16x16x32_bf16 v[24:27], v[160:163], v[168:171], v[24:27]
	v_mfma_f32_16x16x32_bf16 v[20:23], v[146:149], v[186:189], v[20:23]
	v_mfma_f32_16x16x32_bf16 v[16:19], v[160:163], v[186:189], v[16:19]
	v_mfma_f32_16x16x32_bf16 v[12:15], v[146:149], v[196:199], v[12:15]
	v_mfma_f32_16x16x32_bf16 v[8:11], v[160:163], v[196:199], v[8:11]
	v_mfma_f32_16x16x32_bf16 v[4:7], v[146:149], v[204:207], v[4:7]
	v_mfma_f32_16x16x32_bf16 v[0:3], v[160:163], v[204:207], v[0:3]
	v_mfma_f32_16x16x32_bf16 v[28:31], v[150:153], v[172:175], v[28:31]
	v_mfma_f32_16x16x32_bf16 v[24:27], v[164:167], v[172:175], v[24:27]
	v_mfma_f32_16x16x32_bf16 v[20:23], v[150:153], v[192:195], v[20:23]
	v_mfma_f32_16x16x32_bf16 v[16:19], v[164:167], v[192:195], v[16:19]
	v_mfma_f32_16x16x32_bf16 v[12:15], v[150:153], v[200:203], v[12:15]
	v_mfma_f32_16x16x32_bf16 v[8:11], v[164:167], v[200:203], v[8:11]
	v_mfma_f32_16x16x32_bf16 v[4:7], v[150:153], v[208:211], v[4:7]
	v_mfma_f32_16x16x32_bf16 v[0:3], v[164:167], v[208:211], v[0:3]
	s_setprio 0
	s_barrier
	s_add_i32 s48, 0, 0x18000
	s_add_i32 s49, 0, 0x1c000
	v_add_u32_e32 v142, s48, v180
	v_add_u32_e32 v154, s49, v180
	ds_read_b128 v[130:133], v142
	ds_read_b128 v[134:137], v142 offset:1024
	ds_read_b128 v[138:141], v142 offset:2048
	ds_read_b128 v[142:145], v142 offset:3072
	ds_read_b128 v[146:149], v154
	ds_read_b128 v[150:153], v154 offset:1024
	ds_read_b128 v[160:163], v154 offset:2048
	ds_read_b128 v[164:167], v154 offset:3072
	s_add_i32 s47, s47, 0x40000
	s_mov_b32 m0, s26
	v_add_u32_e32 v154, s47, v176
	ds_read_b128 v[168:171], v185 offset:32768
	ds_read_b128 v[172:175], v185 offset:33792
	ds_read_b128 v[186:189], v185 offset:34816
	ds_read_b128 v[192:195], v185 offset:35840
	ds_read_b128 v[196:199], v185 offset:36864
	ds_read_b128 v[200:203], v185 offset:37888
	ds_read_b128 v[204:207], v185 offset:38912
	ds_read_b128 v[208:211], v185 offset:39936
	global_load_lds_dwordx4 v154, s[4:5]
	v_add_u32_e32 v154, s47, v178
	s_mov_b32 m0, s27
	s_nop 0
	global_load_lds_dwordx4 v154, s[4:5]
	s_waitcnt vmcnt(8)
	s_waitcnt lgkmcnt(0)
	s_barrier
; #define PG8_STAGE_A(bufoff, off) PG8_STAGE_X(bufoff, rsA, g.A, off, voffA)
; #define PG8_STAGE_B(bufoff, off) PG8_STAGE_X(bufoff, rsB, g.Bt, off, voffB)
; #define PG8_LDA(dst, b, h) do { _Pragma("unroll") for (int m = 0; m < 4; ++m) _Pragma("unroll") for (int k = 0; k < 2; ++k) { const v4i_t f_ = *(const LAS v4i_t*)(lds + PG8_SA(b, h) + aoff + m * 2048 + k * KOFF); dst[m][4 * k] = f_[0]; dst[m][4 * k + 1] = f_[1]; dst[m][4 * k + 2] = f_[2]; dst[m][4 * k + 3] = f_[3]; } } while (0)
; #define PG8_LDB(dst, b, h) do { _Pragma("unroll") for (int n = 0; n < 2; ++n) _Pragma("unroll") for (int k = 0; k < 2; ++k) { const v4i_t f_ = *(const LAS v4i_t*)(lds + PG8_SB(b, h) + boff + n * 2048 + k * KOFF); dst[n][4 * k] = f_[0]; dst[n][4 * k + 1] = f_[1]; dst[n][4 * k + 2] = f_[2]; dst[n][4 * k + 3] = f_[3]; } } while (0)
; #define PG8_WAIT_V(n) asm volatile("s_waitcnt vmcnt(" #n ")" ::: "memory")
; #define PG8_WAIT_L(n) asm volatile("s_waitcnt lgkmcnt(" #n ")" ::: "memory")
; #define PG8_BAR __builtin_amdgcn_s_barrier()
; #define PG8_SCHED __builtin_amdgcn_sched_barrier(0)
; template <class Epi, class Sched, bool ALIGN_EPI, bool F8 = false>
; __device__ __forceinline__ void gemm_phase(LAS unsigned char* lds, const Gemm g, const Sched& S, const Epi& E) {
;     ...
;             PG8_LDB(B0, 1, 0); PG8_LDB(B1, 1, 1); PG8_SCHED; PG8_LDA(At, 1, 0); PG8_STAGE_A(PG8_SA(0, 1), a2 + hstepA);
;             PG8_WAIT_V(8); PG8_WAIT_L(0); PG8_BAR; PG8_MMA(0, 0, At, B0); PG8_MMA(0, 1, At, B1); PG8_BAR; PG8_SCHED;
;             PG8_LDA(At, 1, 1); PG8_STAGE_B(PG8_SB(1, 0), b3); PG8_STAGE_B(PG8_SB(1, 1), b3 + hstepB); PG8_STAGE_A(PG8_SA(1, 0), a3);
;             PG8_WAIT_V(8); PG8_WAIT_L(0); PG8_BAR; PG8_MMA(1, 0, At, B0); PG8_MMA(1, 1, At, B1); PG8_BAR; PG8_SCHED;
	s_setprio 1
	s_waitcnt lgkmcnt(0)
	v_mfma_f32_16x16x32_bf16 v[124:127], v[130:133], v[168:171], v[124:127]
	v_mfma_f32_16x16x32_bf16 v[120:123], v[138:141], v[168:171], v[120:123]
	v_mfma_f32_16x16x32_bf16 v[116:119], v[130:133], v[186:189], v[116:119]
	v_mfma_f32_16x16x32_bf16 v[112:115], v[138:141], v[186:189], v[112:115]
	v_mfma_f32_16x16x32_bf16 v[108:111], v[130:133], v[196:199], v[108:111]
	v_mfma_f32_16x16x32_bf16 v[104:107], v[138:141], v[196:199], v[104:107]
	v_mfma_f32_16x16x32_bf16 v[100:103], v[130:133], v[204:207], v[100:103]
	v_mfma_f32_16x16x32_bf16 v[96:99], v[138:141], v[204:207], v[96:99]
	v_mfma_f32_16x16x32_bf16 v[124:127], v[134:137], v[172:175], v[124:127]
	v_mfma_f32_16x16x32_bf16 v[120:123], v[142:145], v[172:175], v[120:123]
	v_mfma_f32_16x16x32_bf16 v[116:119], v[134:137], v[192:195], v[116:119]
	v_mfma_f32_16x16x32_bf16 v[112:115], v[142:145], v[192:195], v[112:115]
	v_mfma_f32_16x16x32_bf16 v[108:111], v[134:137], v[200:203], v[108:111]
	v_mfma_f32_16x16x32_bf16 v[104:107], v[142:145], v[200:203], v[104:107]
	v_mfma_f32_16x16x32_bf16 v[100:103], v[134:137], v[208:211], v[100:103]
	v_mfma_f32_16x16x32_bf16 v[96:99], v[142:145], v[208:211], v[96:99]
	s_setprio 0
	s_setprio 1
	v_mfma_f32_16x16x32_bf16 v[92:95], v[146:149], v[168:171], v[92:95]
	v_mfma_f32_16x16x32_bf16 v[88:91], v[160:163], v[168:171], v[88:91]
	v_mfma_f32_16x16x32_bf16 v[84:87], v[146:149], v[186:189], v[84:87]
	v_mfma_f32_16x16x32_bf16 v[80:83], v[160:163], v[186:189], v[80:83]
	v_mfma_f32_16x16x32_bf16 v[76:79], v[146:149], v[196:199], v[76:79]
	v_mfma_f32_16x16x32_bf16 v[72:75], v[160:163], v[196:199], v[72:75]
	v_mfma_f32_16x16x32_bf16 v[68:71], v[146:149], v[204:207], v[68:71]
	v_mfma_f32_16x16x32_bf16 v[64:67], v[160:163], v[204:207], v[64:67]
	v_mfma_f32_16x16x32_bf16 v[92:95], v[150:153], v[172:175], v[92:95]
	v_mfma_f32_16x16x32_bf16 v[88:91], v[164:167], v[172:175], v[88:91]
	v_mfma_f32_16x16x32_bf16 v[84:87], v[150:153], v[192:195], v[84:87]
	v_mfma_f32_16x16x32_bf16 v[80:83], v[164:167], v[192:195], v[80:83]
	v_mfma_f32_16x16x32_bf16 v[76:79], v[150:153], v[200:203], v[76:79]
	v_mfma_f32_16x16x32_bf16 v[72:75], v[164:167], v[200:203], v[72:75]
	v_mfma_f32_16x16x32_bf16 v[68:71], v[150:153], v[208:211], v[68:71]
	v_mfma_f32_16x16x32_bf16 v[64:67], v[164:167], v[208:211], v[64:67]
	s_setprio 0
	s_barrier
	s_or_b32 s47, s46, 0x80
	s_add_i32 s48, s48, s15
	v_add_u32_e32 v154, s47, v177
	s_mov_b32 m0, s48
	ds_read_b128 v[168:171], v185 offset:49152
	ds_read_b128 v[172:175], v185 offset:50176
	ds_read_b128 v[186:189], v185 offset:51200
	ds_read_b128 v[192:195], v185 offset:52224
	ds_read_b128 v[196:199], v185 offset:53248
	ds_read_b128 v[200:203], v185 offset:54272
	ds_read_b128 v[204:207], v185 offset:55296
	ds_read_b128 v[208:211], v185 offset:56320
	global_load_lds_dwordx4 v154, s[6:7]
	v_add_u32_e32 v154, s47, v179
	s_add_i32 m0, s48, 0x2000
	s_add_i32 s46, s46, 0x40080
	s_add_i32 s47, s49, s15
	global_load_lds_dwordx4 v154, s[6:7]
	v_add_u32_e32 v154, s46, v177
	s_mov_b32 m0, s47
	s_nop 0
	global_load_lds_dwordx4 v154, s[6:7]
	v_add_u32_e32 v154, s46, v179
	s_add_i32 m0, s47, 0x2000
	s_nop 0
	global_load_lds_dwordx4 v154, s[6:7]
	v_add_u32_e32 v154, s45, v176
	s_mov_b32 m0, s29
	s_nop 0
	global_load_lds_dwordx4 v154, s[4:5]
	v_add_u32_e32 v154, s45, v178
	s_mov_b32 m0, s30
	s_nop 0
	global_load_lds_dwordx4 v154, s[4:5]
	s_waitcnt vmcnt(8)
	s_waitcnt lgkmcnt(0)
	s_barrier
	s_setprio 1
	s_waitcnt lgkmcnt(0)
	v_mfma_f32_16x16x32_bf16 v[60:63], v[130:133], v[168:171], v[60:63]
	v_mfma_f32_16x16x32_bf16 v[56:59], v[138:141], v[168:171], v[56:59]
	v_mfma_f32_16x16x32_bf16 v[52:55], v[130:133], v[186:189], v[52:55]
	v_mfma_f32_16x16x32_bf16 v[48:51], v[138:141], v[186:189], v[48:51]
	v_mfma_f32_16x16x32_bf16 v[44:47], v[130:133], v[196:199], v[44:47]
	v_mfma_f32_16x16x32_bf16 v[40:43], v[138:141], v[196:199], v[40:43]
	v_mfma_f32_16x16x32_bf16 v[36:39], v[130:133], v[204:207], v[36:39]
	v_mfma_f32_16x16x32_bf16 v[32:35], v[138:141], v[204:207], v[32:35]
	v_mfma_f32_16x16x32_bf16 v[60:63], v[134:137], v[172:175], v[60:63]
	v_mfma_f32_16x16x32_bf16 v[56:59], v[142:145], v[172:175], v[56:59]
	v_mfma_f32_16x16x32_bf16 v[52:55], v[134:137], v[192:195], v[52:55]
	v_mfma_f32_16x16x32_bf16 v[48:51], v[142:145], v[192:195], v[48:51]
	v_mfma_f32_16x16x32_bf16 v[44:47], v[134:137], v[200:203], v[44:47]
	v_mfma_f32_16x16x32_bf16 v[40:43], v[142:145], v[200:203], v[40:43]
	v_mfma_f32_16x16x32_bf16 v[36:39], v[134:137], v[208:211], v[36:39]
	v_mfma_f32_16x16x32_bf16 v[32:35], v[142:145], v[208:211], v[32:35]
	s_setprio 0
	s_setprio 1
	v_mfma_f32_16x16x32_bf16 v[28:31], v[146:149], v[168:171], v[28:31]
	v_mfma_f32_16x16x32_bf16 v[24:27], v[160:163], v[168:171], v[24:27]
	v_mfma_f32_16x16x32_bf16 v[20:23], v[146:149], v[186:189], v[20:23]
	v_mfma_f32_16x16x32_bf16 v[16:19], v[160:163], v[186:189], v[16:19]
	v_mfma_f32_16x16x32_bf16 v[12:15], v[146:149], v[196:199], v[12:15]
	v_mfma_f32_16x16x32_bf16 v[8:11], v[160:163], v[196:199], v[8:11]
	v_mfma_f32_16x16x32_bf16 v[4:7], v[146:149], v[204:207], v[4:7]
	v_mfma_f32_16x16x32_bf16 v[0:3], v[160:163], v[204:207], v[0:3]
	v_mfma_f32_16x16x32_bf16 v[28:31], v[150:153], v[172:175], v[28:31]
	v_mfma_f32_16x16x32_bf16 v[24:27], v[164:167], v[172:175], v[24:27]
	v_mfma_f32_16x16x32_bf16 v[20:23], v[150:153], v[192:195], v[20:23]
	v_mfma_f32_16x16x32_bf16 v[16:19], v[164:167], v[192:195], v[16:19]
	v_mfma_f32_16x16x32_bf16 v[12:15], v[150:153], v[200:203], v[12:15]
	v_mfma_f32_16x16x32_bf16 v[8:11], v[164:167], v[200:203], v[8:11]
	v_mfma_f32_16x16x32_bf16 v[4:7], v[150:153], v[208:211], v[4:7]
	v_mfma_f32_16x16x32_bf16 v[0:3], v[164:167], v[208:211], v[0:3]
	s_setprio 0
	s_barrier
	s_add_i32 s44, s44, 2
	s_addk_i32 s42, 0x100
	s_addk_i32 s43, 0x100
	v_add_u32_e32 v128, 0x100, v128
	s_cmp_gt_u32 s44, 13
	v_add_u32_e32 v129, 0x100, v129
	s_cbranch_scc0 .LBB0_1164
	s_branch .Lpeel_after_pl3

; #define PG8_BAR __builtin_amdgcn_s_barrier()
; template <class Epi, class Sched, bool ALIGN_EPI, bool F8 = false>
; __device__ __forceinline__ void gemm_phase(LAS unsigned char* lds, const Gemm g, const Sched& S, const Epi& E) {
;     ...
;         if constexpr (ALIGN_EPI) { if (wr == 0) PG8_BAR; }
.Lpeel_after_pl3:
	s_and_b64 vcc, exec, s[10:11]
	s_cbranch_vccz .LBB0_1167
	s_barrier

; #define PG8_STAGE_A(bufoff, off) PG8_STAGE_X(bufoff, rsA, g.A, off, voffA)
; #define PG8_STAGE_B(bufoff, off) PG8_STAGE_X(bufoff, rsB, g.Bt, off, voffB)
; #define PG8_WAIT_V(n) asm volatile("s_waitcnt vmcnt(" #n ")" ::: "memory")
; #define PG8_BAR __builtin_amdgcn_s_barrier()
; template <class Epi, class Sched, bool ALIGN_EPI, bool F8 = false>
; __device__ __forceinline__ void gemm_phase(LAS unsigned char* lds, const Gemm g, const Sched& S, const Epi& E) {
;     ...
;     const unsigned lds_w32 = (unsigned)__builtin_amdgcn_readfirstlane((int)((unsigned)(uintptr_t)lds + ldsw));
;     constexpr int KOFF = F8 ? 16 : 1024;
;     const int aoff = lds_byte(wr * 64 + fr, F8 ? fq * 16 : fq * 8), boff = lds_byte(wc * 32 + fr, F8 ? fq * 16 : fq * 8);
;     ...
;     PG8_STAGE_B(PG8_SB(0, 0), cB); PG8_STAGE_B(PG8_SB(0, 1), cB + hstepB); PG8_STAGE_A(PG8_SA(0, 0), cA); PG8_STAGE_A(PG8_SA(0, 1), cA + hstepA);
;     if (wr == 1) PG8_BAR;
;     PG8_WAIT_V(2); PG8_BAR;
;     PG8_STAGE_B(PG8_SB(1, 0), cB + kstep); PG8_STAGE_A(PG8_SA(1, 0), cA + kstep); PG8_STAGE_B(PG8_SB(1, 1), cB + hstepB + kstep);
;     PG8_WAIT_V(6); PG8_BAR;
.LBB0_1229:
	s_add_u32 s20, s8, 0xef00000
	s_addc_u32 s21, s9, 0
	s_add_u32 s22, s8, 0x1af00000
	s_addc_u32 s23, s9, 0
	s_add_u32 s24, s8, 0x32f10000
	s_addc_u32 s25, s9, 0
	s_or_b32 s1, s51, 0x80
	s_add_i32 m0, s19, 0x18000
	v_add_u32_e32 v7, s1, v147
	s_waitcnt vmcnt(2)
	s_barrier
	global_load_lds_dwordx4 v7, s[14:15]
	v_add_u32_e32 v7, s1, v149
	s_add_i32 m0, s19, 0x1a000
	s_or_b32 s1, s52, 0x80
	s_add_i32 s37, s19, 0x8000
	global_load_lds_dwordx4 v7, s[14:15]
	v_add_u32_e32 v7, s1, v146
	s_mov_b32 m0, s37
	s_add_i32 s38, s19, 0xa000
	global_load_lds_dwordx4 v7, s[12:13]
	v_add_u32_e32 v7, s1, v148
	s_mov_b32 m0, s38
	s_or_b32 s1, s51, 0x80080
	global_load_lds_dwordx4 v7, s[12:13]
	s_add_i32 m0, s19, 0x1c000
	v_add_u32_e32 v7, s1, v147
	global_load_lds_dwordx4 v7, s[14:15]
	v_add_u32_e32 v7, s1, v149
	s_add_i32 m0, s19, 0x1e000
	v_lshlrev_b32_e32 v8, 6, v0
	global_load_lds_dwordx4 v7, s[14:15]
	v_and_b32_e32 v7, 48, v0
	s_movk_i32 s1, 0x3c0
	v_lshlrev_b32_e32 v0, 2, v0
	s_lshl_b32 s39, s0, 6
	s_lshl_b32 s0, s0, 13
	v_and_or_b32 v7, v8, s1, v7
	v_and_b32_e32 v0, 32, v0
	v_readlane_b32 s1, v254, 15
	v_bitop3_b32 v8, v7, s0, v0 bitop3:0xde
	s_lshl_b32 s0, s1, 5
	s_and_b32 s40, s0, 0x60
	s_lshl_b32 s0, s40, 7
	v_bitop3_b32 v150, v7, s0, v0 bitop3:0xde
	v_and_b32_e32 v7, 64, v144
	v_xor_b32_e32 v0, 16, v144
	v_add_u32_e32 v7, 64, v7
	v_cmp_lt_i32_e32 vcc, v0, v7
	s_mov_b32 s0, 0x80080
	s_waitcnt vmcnt(6)
	s_cmp_lt_u32 s1, 4
	v_cndmask_b32_e32 v0, v144, v0, vcc
	v_lshlrev_b32_e32 v151, 2, v0
	v_xor_b32_e32 v0, 32, v144
	v_cmp_lt_i32_e32 vcc, v0, v7
	s_cselect_b64 s[26:27], -1, 0
	s_add_i32 s43, 0, 0x10000
	v_cndmask_b32_e32 v0, v144, v0, vcc
	v_lshlrev_b32_e32 v152, 2, v0
	v_lshlrev_b32_e32 v0, 15, v4
	v_and_b32_e32 v0, 0xffff0000, v0
	v_lshl_add_u32 v0, v5, 12, v0
	v_and_b32_e32 v4, 1, v4
	v_lshl_or_b32 v0, v4, 6, v0
	v_lshlrev_b32_e32 v4, 1, v6
	v_add3_u32 v153, v0, v4, s0
	v_lshlrev_b32_e32 v0, 15, v1
	v_and_b32_e32 v0, 0xffff0000, v0
	v_lshl_add_u32 v0, v2, 12, v0
	v_and_b32_e32 v1, 1, v1
	v_lshl_or_b32 v0, v1, 6, v0
	v_lshlrev_b32_e32 v1, 1, v3
	s_add_i32 s44, 0, 0x14000
	s_ashr_i32 s41, s30, 31
	s_ashr_i32 s42, s31, 31
	v_add3_u32 v154, v0, v1, s0
	v_mov_b64_e32 v[128:129], 0x200
	v_mov_b64_e32 v[130:131], 0x1ff
	v_add_u32_e32 v155, s43, v150
	v_add_u32_e32 v156, s44, v150
	v_add_u32_e32 v157, 0, v8
	s_mov_b64 s[28:29], 0x80
	s_barrier
	s_mov_b32 s80, 0
	s_branch .LBB0_1232

; template <class Epi, class Sched, bool ALIGN_EPI, bool F8 = false>
; __device__ __forceinline__ void gemm_phase(LAS unsigned char* lds, const Gemm g, const Sched& S, const Epi& E) {
;     ...
;         if (!has_next) break;
; #pragma unroll
;         for (int a = 0; a < 2; ++a)
; #pragma unroll
;             for (int b = 0; b < 2; ++b)
; #pragma unroll
;                 for (int m = 0; m < 4; ++m)
; #pragma unroll
;                     for (int n = 0; n < 2; ++n) acc[a][b][m][n] = (f32x4){0.f, 0.f, 0.f, 0.f};
;         cur = nxt; cA = nA; cB = nB; ++ui;
.LBB0_1231:
	s_mov_b32 s80, 1
	s_andn2_b64 vcc, exec, s[0:1]
	s_mov_b32 s49, s45
	s_mov_b32 s50, s46
	s_mov_b32 s51, s48
	s_mov_b32 s52, s47
	s_cbranch_vccz .LBB0_1261

; #define PG8_STAGE_A(bufoff, off) PG8_STAGE_X(bufoff, rsA, g.A, off, voffA)
; #define PG8_LDA(dst, b, h) do { _Pragma("unroll") for (int m = 0; m < 4; ++m) _Pragma("unroll") for (int k = 0; k < 2; ++k) { const v4i_t f_ = *(const LAS v4i_t*)(lds + PG8_SA(b, h) + aoff + m * 2048 + k * KOFF); dst[m][4 * k] = f_[0]; dst[m][4 * k + 1] = f_[1]; dst[m][4 * k + 2] = f_[2]; dst[m][4 * k + 3] = f_[3]; } } while (0)
; #define PG8_LDB(dst, b, h) do { _Pragma("unroll") for (int n = 0; n < 2; ++n) _Pragma("unroll") for (int k = 0; k < 2; ++k) { const v4i_t f_ = *(const LAS v4i_t*)(lds + PG8_SB(b, h) + boff + n * 2048 + k * KOFF); dst[n][4 * k] = f_[0]; dst[n][4 * k + 1] = f_[1]; dst[n][4 * k + 2] = f_[2]; dst[n][4 * k + 3] = f_[3]; } } while (0)
; #define PG8_WAIT_V(n) asm volatile("s_waitcnt vmcnt(" #n ")" ::: "memory")
; #define PG8_WAIT_L(n) asm volatile("s_waitcnt lgkmcnt(" #n ")" ::: "memory")
; #define PG8_BAR __builtin_amdgcn_s_barrier()
; #define PG8_SCHED __builtin_amdgcn_sched_barrier(0)
; template <class Epi, class Sched, bool ALIGN_EPI, bool F8 = false>
; __device__ __forceinline__ void gemm_phase(LAS unsigned char* lds, const Gemm g, const Sched& S, const Epi& E) {
;     ...
;         for (int t = 0; t < nt; t += 2) {
;             const bool last = (t == nt - 2);
;             const unsigned a1 = cA + (unsigned)(t + 1) * kstep;
;             const unsigned a2 = last ? nA : cA + (unsigned)(t + 2) * kstep; const unsigned b2 = last ? nB : cB + (unsigned)(t + 2) * kstep;
;             const unsigned a3 = a2 + kstep; const unsigned b3 = b2 + kstep;
;             PG8_LDB(B0, 0, 0); PG8_LDB(B1, 0, 1); PG8_SCHED; PG8_LDA(At, 0, 0); PG8_STAGE_A(PG8_SA(1, 1), a1 + hstepA);
;             PG8_WAIT_V(8); PG8_WAIT_L(0); PG8_BAR; PG8_MMA(0, 0, At, B0); PG8_MMA(0, 1, At, B1); PG8_BAR; PG8_SCHED;
;     ...
;         for (int a = 0; a < 2; ++a)
; #pragma unroll
;             for (int b = 0; b < 2; ++b)
; #pragma unroll
;                 for (int m = 0; m < 4; ++m)
; #pragma unroll
;                     for (int n = 0; n < 2; ++n) acc[a][b][m][n] = (f32x4){0.f, 0.f, 0.f, 0.f};
.LBB0_1238:
	s_lshl_b32 s47, s46, 20
	s_and_b64 s[0:1], s[4:5], exec
	s_cselect_b32 s0, s47, s52
	s_lshl_b32 s48, s45, 20
	s_and_b64 s[54:55], s[4:5], exec
	v_mov_b32_e32 v0, 0
	s_cselect_b32 s1, s48, s51
	v_add_u32_e32 v132, s52, v153
	v_add_u32_e32 v133, s52, v154
	s_addk_i32 s51, 0x100
	s_addk_i32 s52, 0x100
	s_mov_b32 s53, -2
	s_waitcnt lgkmcnt(0)
	v_mov_b32_e32 v1, v0
	v_mov_b32_e32 v2, v0
	v_mov_b32_e32 v3, v0
	v_mov_b32_e32 v4, v0
	v_mov_b32_e32 v5, v0
	v_mov_b32_e32 v6, v0
	v_mov_b32_e32 v7, v0
	v_mov_b32_e32 v8, v0
	v_mov_b32_e32 v9, v0
	v_mov_b32_e32 v10, v0
	v_mov_b32_e32 v11, v0
	v_mov_b32_e32 v12, v0
	v_mov_b32_e32 v13, v0
	v_mov_b32_e32 v14, v0
	v_mov_b32_e32 v15, v0
	v_mov_b32_e32 v16, v0
	v_mov_b32_e32 v17, v0
	v_mov_b32_e32 v18, v0
	v_mov_b32_e32 v19, v0
	v_mov_b32_e32 v20, v0
	v_mov_b32_e32 v21, v0
	v_mov_b32_e32 v22, v0
	v_mov_b32_e32 v23, v0
	v_mov_b32_e32 v24, v0
	v_mov_b32_e32 v25, v0
	v_mov_b32_e32 v26, v0
	v_mov_b32_e32 v27, v0
	v_mov_b32_e32 v28, v0
	v_mov_b32_e32 v29, v0
	v_mov_b32_e32 v30, v0
	v_mov_b32_e32 v31, v0
	v_mov_b32_e32 v32, v0
	v_mov_b32_e32 v33, v0
	v_mov_b32_e32 v34, v0
	v_mov_b32_e32 v35, v0
	v_mov_b32_e32 v36, v0
	v_mov_b32_e32 v37, v0
	v_mov_b32_e32 v38, v0
	v_mov_b32_e32 v39, v0
	v_mov_b32_e32 v40, v0
	v_mov_b32_e32 v41, v0
	v_mov_b32_e32 v42, v0
	v_mov_b32_e32 v43, v0
	v_mov_b32_e32 v44, v0
	v_mov_b32_e32 v45, v0
	v_mov_b32_e32 v46, v0
	v_mov_b32_e32 v47, v0
	v_mov_b32_e32 v48, v0
	v_mov_b32_e32 v49, v0
	v_mov_b32_e32 v50, v0
	v_mov_b32_e32 v51, v0
	v_mov_b32_e32 v52, v0
	v_mov_b32_e32 v53, v0
	v_mov_b32_e32 v54, v0
	v_mov_b32_e32 v55, v0
	v_mov_b32_e32 v56, v0
	v_mov_b32_e32 v57, v0
	v_mov_b32_e32 v58, v0
	v_mov_b32_e32 v59, v0
	v_mov_b32_e32 v60, v0
	v_mov_b32_e32 v61, v0
	v_mov_b32_e32 v62, v0
	v_mov_b32_e32 v63, v0
	v_mov_b32_e32 v64, v0
	v_mov_b32_e32 v65, v0
	v_mov_b32_e32 v66, v0
	v_mov_b32_e32 v67, v0
	v_mov_b32_e32 v68, v0
	v_mov_b32_e32 v69, v0
	v_mov_b32_e32 v70, v0
	v_mov_b32_e32 v71, v0
	v_mov_b32_e32 v72, v0
	v_mov_b32_e32 v73, v0
	v_mov_b32_e32 v74, v0
	v_mov_b32_e32 v75, v0
	v_mov_b32_e32 v76, v0
	v_mov_b32_e32 v77, v0
	v_mov_b32_e32 v78, v0
	v_mov_b32_e32 v79, v0
	v_mov_b32_e32 v80, v0
	v_mov_b32_e32 v81, v0
	v_mov_b32_e32 v82, v0
	v_mov_b32_e32 v83, v0
	v_mov_b32_e32 v84, v0
	v_mov_b32_e32 v85, v0
	v_mov_b32_e32 v86, v0
	v_mov_b32_e32 v87, v0
	v_mov_b32_e32 v88, v0
	v_mov_b32_e32 v89, v0
	v_mov_b32_e32 v90, v0
	v_mov_b32_e32 v91, v0
	v_mov_b32_e32 v92, v0
	v_mov_b32_e32 v93, v0
	v_mov_b32_e32 v94, v0
	v_mov_b32_e32 v95, v0
	v_mov_b32_e32 v96, v0
	v_mov_b32_e32 v97, v0
	v_mov_b32_e32 v98, v0
	v_mov_b32_e32 v99, v0
	v_mov_b32_e32 v100, v0
	v_mov_b32_e32 v101, v0
	v_mov_b32_e32 v102, v0
	v_mov_b32_e32 v103, v0
	v_mov_b32_e32 v104, v0
	v_mov_b32_e32 v105, v0
	v_mov_b32_e32 v106, v0
	v_mov_b32_e32 v107, v0
	v_mov_b32_e32 v108, v0
	v_mov_b32_e32 v109, v0
	v_mov_b32_e32 v110, v0
	v_mov_b32_e32 v111, v0
	v_mov_b32_e32 v112, v0
	v_mov_b32_e32 v113, v0
	v_mov_b32_e32 v114, v0
	v_mov_b32_e32 v115, v0
	v_mov_b32_e32 v116, v0
	v_mov_b32_e32 v117, v0
	v_mov_b32_e32 v118, v0
	v_mov_b32_e32 v119, v0
	v_mov_b32_e32 v120, v0
	v_mov_b32_e32 v121, v0
	v_mov_b32_e32 v122, v0
	v_mov_b32_e32 v123, v0
	v_mov_b32_e32 v124, v0
	v_mov_b32_e32 v125, v0
	v_mov_b32_e32 v126, v0
	v_mov_b32_e32 v127, v0
	s_cmp_lg_u32 s80, 0
	s_cbranch_scc0 .LBB0_1239
	ds_read_b128 v[134:137], v155
	ds_read_b128 v[138:141], v155 offset:1024
	ds_read_b128 v[158:161], v155 offset:2048
	ds_read_b128 v[162:165], v155 offset:3072
	ds_read_b128 v[166:169], v156
	ds_read_b128 v[170:173], v156 offset:1024
	ds_read_b128 v[174:177], v156 offset:2048
	ds_read_b128 v[178:181], v156 offset:3072
	s_cmp_eq_u32 s53, 28
	s_cselect_b32 s56, s0, s52
	s_cselect_b32 s55, s1, s51
	s_or_b32 s54, s56, 0x80
	s_add_i32 m0, s19, 0xc000
	ds_read_b128 v[182:185], v157
	ds_read_b128 v[186:189], v157 offset:1024
	ds_read_b128 v[190:193], v157 offset:2048
	ds_read_b128 v[194:197], v157 offset:3072
	ds_read_b128 v[198:201], v157 offset:4096
	ds_read_b128 v[202:205], v157 offset:5120
	ds_read_b128 v[206:209], v157 offset:6144
	ds_read_b128 v[210:213], v157 offset:7168
	global_load_lds_dwordx4 v133, s[12:13]
	s_add_i32 m0, s19, 0xe000
	s_nop 0
	global_load_lds_dwordx4 v132, s[12:13]
	s_waitcnt vmcnt(56)
	s_waitcnt lgkmcnt(0)
	s_barrier
	s_setprio 1
	s_waitcnt lgkmcnt(0)
	v_mfma_f32_16x16x32_bf16 v[124:127], v[134:137], v[182:185], v[124:127]
	v_mfma_f32_16x16x32_bf16 v[120:123], v[158:161], v[182:185], v[120:123]
	v_mfma_f32_16x16x32_bf16 v[116:119], v[134:137], v[190:193], v[116:119]
	v_mfma_f32_16x16x32_bf16 v[112:115], v[158:161], v[190:193], v[112:115]
	v_mfma_f32_16x16x32_bf16 v[108:111], v[134:137], v[198:201], v[108:111]
	v_mfma_f32_16x16x32_bf16 v[104:107], v[158:161], v[198:201], v[104:107]
	v_mfma_f32_16x16x32_bf16 v[100:103], v[134:137], v[206:209], v[100:103]
	v_mfma_f32_16x16x32_bf16 v[96:99], v[158:161], v[206:209], v[96:99]
	v_mfma_f32_16x16x32_bf16 v[124:127], v[138:141], v[186:189], v[124:127]
	v_mfma_f32_16x16x32_bf16 v[120:123], v[162:165], v[186:189], v[120:123]
	v_mfma_f32_16x16x32_bf16 v[116:119], v[138:141], v[194:197], v[116:119]
	v_mfma_f32_16x16x32_bf16 v[112:115], v[162:165], v[194:197], v[112:115]
	v_mfma_f32_16x16x32_bf16 v[108:111], v[138:141], v[202:205], v[108:111]
	v_mfma_f32_16x16x32_bf16 v[104:107], v[162:165], v[202:205], v[104:107]
	v_mfma_f32_16x16x32_bf16 v[100:103], v[138:141], v[210:213], v[100:103]
	v_mfma_f32_16x16x32_bf16 v[96:99], v[162:165], v[210:213], v[96:99]
	s_setprio 0
	s_setprio 1
	v_mfma_f32_16x16x32_bf16 v[92:95], v[166:169], v[182:185], v[92:95]
	v_mfma_f32_16x16x32_bf16 v[88:91], v[174:177], v[182:185], v[88:91]
	v_mfma_f32_16x16x32_bf16 v[84:87], v[166:169], v[190:193], v[84:87]
	v_mfma_f32_16x16x32_bf16 v[80:83], v[174:177], v[190:193], v[80:83]
	v_mfma_f32_16x16x32_bf16 v[76:79], v[166:169], v[198:201], v[76:79]
	v_mfma_f32_16x16x32_bf16 v[72:75], v[174:177], v[198:201], v[72:75]
	v_mfma_f32_16x16x32_bf16 v[68:71], v[166:169], v[206:209], v[68:71]
	v_mfma_f32_16x16x32_bf16 v[64:67], v[174:177], v[206:209], v[64:67]
	v_mfma_f32_16x16x32_bf16 v[92:95], v[170:173], v[186:189], v[92:95]
	v_mfma_f32_16x16x32_bf16 v[88:91], v[178:181], v[186:189], v[88:91]
	v_mfma_f32_16x16x32_bf16 v[84:87], v[170:173], v[194:197], v[84:87]
	v_mfma_f32_16x16x32_bf16 v[80:83], v[178:181], v[194:197], v[80:83]
	v_mfma_f32_16x16x32_bf16 v[76:79], v[170:173], v[202:205], v[76:79]
	v_mfma_f32_16x16x32_bf16 v[72:75], v[178:181], v[202:205], v[72:75]
	v_mfma_f32_16x16x32_bf16 v[68:71], v[170:173], v[210:213], v[68:71]
	v_mfma_f32_16x16x32_bf16 v[64:67], v[178:181], v[210:213], v[64:67]
	s_setprio 0
	s_barrier
; #define PG8_STAGE_A(bufoff, off) PG8_STAGE_X(bufoff, rsA, g.A, off, voffA)
; #define PG8_STAGE_B(bufoff, off) PG8_STAGE_X(bufoff, rsB, g.Bt, off, voffB)
; #define PG8_LDA(dst, b, h) do { _Pragma("unroll") for (int m = 0; m < 4; ++m) _Pragma("unroll") for (int k = 0; k < 2; ++k) { const v4i_t f_ = *(const LAS v4i_t*)(lds + PG8_SA(b, h) + aoff + m * 2048 + k * KOFF); dst[m][4 * k] = f_[0]; dst[m][4 * k + 1] = f_[1]; dst[m][4 * k + 2] = f_[2]; dst[m][4 * k + 3] = f_[3]; } } while (0)
; #define PG8_LDB(dst, b, h) do { _Pragma("unroll") for (int n = 0; n < 2; ++n) _Pragma("unroll") for (int k = 0; k < 2; ++k) { const v4i_t f_ = *(const LAS v4i_t*)(lds + PG8_SB(b, h) + boff + n * 2048 + k * KOFF); dst[n][4 * k] = f_[0]; dst[n][4 * k + 1] = f_[1]; dst[n][4 * k + 2] = f_[2]; dst[n][4 * k + 3] = f_[3]; } } while (0)
; #define PG8_WAIT_V(n) asm volatile("s_waitcnt vmcnt(" #n ")" ::: "memory")
; #define PG8_WAIT_L(n) asm volatile("s_waitcnt lgkmcnt(" #n ")" ::: "memory")
; #define PG8_BAR __builtin_amdgcn_s_barrier()
; #define PG8_SCHED __builtin_amdgcn_sched_barrier(0)
; template <class Epi, class Sched, bool ALIGN_EPI, bool F8 = false>
; __device__ __forceinline__ void gemm_phase(LAS unsigned char* lds, const Gemm g, const Sched& S, const Epi& E) {
;     ...
;             PG8_LDA(At, 0, 1); PG8_STAGE_B(PG8_SB(0, 0), b2); PG8_STAGE_B(PG8_SB(0, 1), b2 + hstepB); PG8_STAGE_A(PG8_SA(0, 0), a2);
;             PG8_WAIT_V(8); PG8_WAIT_L(0); PG8_BAR; PG8_MMA(1, 0, At, B0); PG8_MMA(1, 1, At, B1); PG8_BAR; PG8_SCHED;
;             PG8_LDB(B0, 1, 0); PG8_LDB(B1, 1, 1); PG8_SCHED; PG8_LDA(At, 1, 0); PG8_STAGE_A(PG8_SA(0, 1), a2 + hstepA);
	s_add_i32 s57, s43, s18
	v_add_u32_e32 v142, s55, v147
	s_mov_b32 m0, s57
	ds_read_b128 v[182:185], v157 offset:16384
	ds_read_b128 v[186:189], v157 offset:17408
	ds_read_b128 v[190:193], v157 offset:18432
	ds_read_b128 v[194:197], v157 offset:19456
	ds_read_b128 v[198:201], v157 offset:20480
	ds_read_b128 v[202:205], v157 offset:21504
	ds_read_b128 v[206:209], v157 offset:22528
	ds_read_b128 v[210:213], v157 offset:23552
	global_load_lds_dwordx4 v142, s[14:15]
	v_add_u32_e32 v142, s55, v149
	s_add_i32 m0, s57, 0x2000
	s_add_i32 s57, s55, 0x80000
	s_add_i32 s58, s44, s18
	global_load_lds_dwordx4 v142, s[14:15]
	v_add_u32_e32 v142, s57, v147
	s_mov_b32 m0, s58
	s_nop 0
	global_load_lds_dwordx4 v142, s[14:15]
	v_add_u32_e32 v142, s57, v149
	s_add_i32 m0, s58, 0x2000
	s_nop 0
	global_load_lds_dwordx4 v142, s[14:15]
	v_add_u32_e32 v142, s56, v146
	s_mov_b32 m0, s19
	s_nop 0
	global_load_lds_dwordx4 v142, s[12:13]
	v_add_u32_e32 v142, s56, v148
	s_mov_b32 m0, s33
	s_nop 0
	global_load_lds_dwordx4 v142, s[12:13]
	s_waitcnt vmcnt(56)
	s_waitcnt lgkmcnt(0)
	s_barrier
	s_setprio 1
	s_waitcnt lgkmcnt(0)
	v_mfma_f32_16x16x32_bf16 v[60:63], v[134:137], v[182:185], v[60:63]
	v_mfma_f32_16x16x32_bf16 v[56:59], v[158:161], v[182:185], v[56:59]
	v_mfma_f32_16x16x32_bf16 v[52:55], v[134:137], v[190:193], v[52:55]
	v_mfma_f32_16x16x32_bf16 v[48:51], v[158:161], v[190:193], v[48:51]
	v_mfma_f32_16x16x32_bf16 v[44:47], v[134:137], v[198:201], v[44:47]
	v_mfma_f32_16x16x32_bf16 v[40:43], v[158:161], v[198:201], v[40:43]
	v_mfma_f32_16x16x32_bf16 v[36:39], v[134:137], v[206:209], v[36:39]
	v_mfma_f32_16x16x32_bf16 v[32:35], v[158:161], v[206:209], v[32:35]
	v_mfma_f32_16x16x32_bf16 v[60:63], v[138:141], v[186:189], v[60:63]
	v_mfma_f32_16x16x32_bf16 v[56:59], v[162:165], v[186:189], v[56:59]
	v_mfma_f32_16x16x32_bf16 v[52:55], v[138:141], v[194:197], v[52:55]
	v_mfma_f32_16x16x32_bf16 v[48:51], v[162:165], v[194:197], v[48:51]
	v_mfma_f32_16x16x32_bf16 v[44:47], v[138:141], v[202:205], v[44:47]
	v_mfma_f32_16x16x32_bf16 v[40:43], v[162:165], v[202:205], v[40:43]
	v_mfma_f32_16x16x32_bf16 v[36:39], v[138:141], v[210:213], v[36:39]
	v_mfma_f32_16x16x32_bf16 v[32:35], v[162:165], v[210:213], v[32:35]
	s_setprio 0
	s_setprio 1
	v_mfma_f32_16x16x32_bf16 v[28:31], v[166:169], v[182:185], v[28:31]
	v_mfma_f32_16x16x32_bf16 v[24:27], v[174:177], v[182:185], v[24:27]
	v_mfma_f32_16x16x32_bf16 v[20:23], v[166:169], v[190:193], v[20:23]
	v_mfma_f32_16x16x32_bf16 v[16:19], v[174:177], v[190:193], v[16:19]
	v_mfma_f32_16x16x32_bf16 v[12:15], v[166:169], v[198:201], v[12:15]
	v_mfma_f32_16x16x32_bf16 v[8:11], v[174:177], v[198:201], v[8:11]
	v_mfma_f32_16x16x32_bf16 v[4:7], v[166:169], v[206:209], v[4:7]
	v_mfma_f32_16x16x32_bf16 v[0:3], v[174:177], v[206:209], v[0:3]
	v_mfma_f32_16x16x32_bf16 v[28:31], v[170:173], v[186:189], v[28:31]
	v_mfma_f32_16x16x32_bf16 v[24:27], v[178:181], v[186:189], v[24:27]
	v_mfma_f32_16x16x32_bf16 v[20:23], v[170:173], v[194:197], v[20:23]
	v_mfma_f32_16x16x32_bf16 v[16:19], v[178:181], v[194:197], v[16:19]
	v_mfma_f32_16x16x32_bf16 v[12:15], v[170:173], v[202:205], v[12:15]
	v_mfma_f32_16x16x32_bf16 v[8:11], v[178:181], v[202:205], v[8:11]
	v_mfma_f32_16x16x32_bf16 v[4:7], v[170:173], v[210:213], v[4:7]
	v_mfma_f32_16x16x32_bf16 v[0:3], v[178:181], v[210:213], v[0:3]
	s_setprio 0
	s_barrier
	s_add_i32 s57, 0, 0x18000
	v_add_u32_e32 v142, s57, v150
	s_add_i32 s58, 0, 0x1c000
	ds_read_b128 v[134:137], v142
	ds_read_b128 v[138:141], v142 offset:1024
	ds_read_b128 v[158:161], v142 offset:2048
	ds_read_b128 v[162:165], v142 offset:3072
	v_add_u32_e32 v142, s58, v150
	ds_read_b128 v[166:169], v142
	ds_read_b128 v[170:173], v142 offset:1024
	ds_read_b128 v[174:177], v142 offset:2048
	ds_read_b128 v[178:181], v142 offset:3072
	s_add_i32 s56, s56, 0x80000
	s_mov_b32 m0, s34
	v_add_u32_e32 v142, s56, v146
	ds_read_b128 v[182:185], v157 offset:32768
	ds_read_b128 v[186:189], v157 offset:33792
	ds_read_b128 v[190:193], v157 offset:34816
	ds_read_b128 v[194:197], v157 offset:35840
	ds_read_b128 v[198:201], v157 offset:36864
	ds_read_b128 v[202:205], v157 offset:37888
	ds_read_b128 v[206:209], v157 offset:38912
	ds_read_b128 v[210:213], v157 offset:39936
	global_load_lds_dwordx4 v142, s[12:13]
	v_add_u32_e32 v142, s56, v148
	s_mov_b32 m0, s35
	s_nop 0
	global_load_lds_dwordx4 v142, s[12:13]
	s_waitcnt vmcnt(8)
	s_waitcnt lgkmcnt(0)
	s_barrier
; #define PG8_STAGE_A(bufoff, off) PG8_STAGE_X(bufoff, rsA, g.A, off, voffA)
; #define PG8_STAGE_B(bufoff, off) PG8_STAGE_X(bufoff, rsB, g.Bt, off, voffB)
; #define PG8_LDA(dst, b, h) do { _Pragma("unroll") for (int m = 0; m < 4; ++m) _Pragma("unroll") for (int k = 0; k < 2; ++k) { const v4i_t f_ = *(const LAS v4i_t*)(lds + PG8_SA(b, h) + aoff + m * 2048 + k * KOFF); dst[m][4 * k] = f_[0]; dst[m][4 * k + 1] = f_[1]; dst[m][4 * k + 2] = f_[2]; dst[m][4 * k + 3] = f_[3]; } } while (0)
; #define PG8_LDB(dst, b, h) do { _Pragma("unroll") for (int n = 0; n < 2; ++n) _Pragma("unroll") for (int k = 0; k < 2; ++k) { const v4i_t f_ = *(const LAS v4i_t*)(lds + PG8_SB(b, h) + boff + n * 2048 + k * KOFF); dst[n][4 * k] = f_[0]; dst[n][4 * k + 1] = f_[1]; dst[n][4 * k + 2] = f_[2]; dst[n][4 * k + 3] = f_[3]; } } while (0)
; #define PG8_WAIT_V(n) asm volatile("s_waitcnt vmcnt(" #n ")" ::: "memory")
; #define PG8_WAIT_L(n) asm volatile("s_waitcnt lgkmcnt(" #n ")" ::: "memory")
; #define PG8_BAR __builtin_amdgcn_s_barrier()
; #define PG8_SCHED __builtin_amdgcn_sched_barrier(0)
; template <class Epi, class Sched, bool ALIGN_EPI, bool F8 = false>
; __device__ __forceinline__ void gemm_phase(LAS unsigned char* lds, const Gemm g, const Sched& S, const Epi& E) {
;     ...
;             PG8_LDB(B0, 1, 0); PG8_LDB(B1, 1, 1); PG8_SCHED; PG8_LDA(At, 1, 0); PG8_STAGE_A(PG8_SA(0, 1), a2 + hstepA);
;             PG8_WAIT_V(8); PG8_WAIT_L(0); PG8_BAR; PG8_MMA(0, 0, At, B0); PG8_MMA(0, 1, At, B1); PG8_BAR; PG8_SCHED;
;             PG8_LDA(At, 1, 1); PG8_STAGE_B(PG8_SB(1, 0), b3); PG8_STAGE_B(PG8_SB(1, 1), b3 + hstepB); PG8_STAGE_A(PG8_SA(1, 0), a3);
;             PG8_WAIT_V(8); PG8_WAIT_L(0); PG8_BAR; PG8_MMA(1, 0, At, B0); PG8_MMA(1, 1, At, B1); PG8_BAR; PG8_SCHED;
	s_setprio 1
	s_waitcnt lgkmcnt(0)
	v_mfma_f32_16x16x32_bf16 v[124:127], v[134:137], v[182:185], v[124:127]
	v_mfma_f32_16x16x32_bf16 v[120:123], v[158:161], v[182:185], v[120:123]
	v_mfma_f32_16x16x32_bf16 v[116:119], v[134:137], v[190:193], v[116:119]
	v_mfma_f32_16x16x32_bf16 v[112:115], v[158:161], v[190:193], v[112:115]
	v_mfma_f32_16x16x32_bf16 v[108:111], v[134:137], v[198:201], v[108:111]
	v_mfma_f32_16x16x32_bf16 v[104:107], v[158:161], v[198:201], v[104:107]
	v_mfma_f32_16x16x32_bf16 v[100:103], v[134:137], v[206:209], v[100:103]
	v_mfma_f32_16x16x32_bf16 v[96:99], v[158:161], v[206:209], v[96:99]
	v_mfma_f32_16x16x32_bf16 v[124:127], v[138:141], v[186:189], v[124:127]
	v_mfma_f32_16x16x32_bf16 v[120:123], v[162:165], v[186:189], v[120:123]
	v_mfma_f32_16x16x32_bf16 v[116:119], v[138:141], v[194:197], v[116:119]
	v_mfma_f32_16x16x32_bf16 v[112:115], v[162:165], v[194:197], v[112:115]
	v_mfma_f32_16x16x32_bf16 v[108:111], v[138:141], v[202:205], v[108:111]
	v_mfma_f32_16x16x32_bf16 v[104:107], v[162:165], v[202:205], v[104:107]
	v_mfma_f32_16x16x32_bf16 v[100:103], v[138:141], v[210:213], v[100:103]
	v_mfma_f32_16x16x32_bf16 v[96:99], v[162:165], v[210:213], v[96:99]
	s_setprio 0
	s_setprio 1
	v_mfma_f32_16x16x32_bf16 v[92:95], v[166:169], v[182:185], v[92:95]
	v_mfma_f32_16x16x32_bf16 v[88:91], v[174:177], v[182:185], v[88:91]
	v_mfma_f32_16x16x32_bf16 v[84:87], v[166:169], v[190:193], v[84:87]
	v_mfma_f32_16x16x32_bf16 v[80:83], v[174:177], v[190:193], v[80:83]
	v_mfma_f32_16x16x32_bf16 v[76:79], v[166:169], v[198:201], v[76:79]
	v_mfma_f32_16x16x32_bf16 v[72:75], v[174:177], v[198:201], v[72:75]
	v_mfma_f32_16x16x32_bf16 v[68:71], v[166:169], v[206:209], v[68:71]
	v_mfma_f32_16x16x32_bf16 v[64:67], v[174:177], v[206:209], v[64:67]
	v_mfma_f32_16x16x32_bf16 v[92:95], v[170:173], v[186:189], v[92:95]
	v_mfma_f32_16x16x32_bf16 v[88:91], v[178:181], v[186:189], v[88:91]
	v_mfma_f32_16x16x32_bf16 v[84:87], v[170:173], v[194:197], v[84:87]
	v_mfma_f32_16x16x32_bf16 v[80:83], v[178:181], v[194:197], v[80:83]
	v_mfma_f32_16x16x32_bf16 v[76:79], v[170:173], v[202:205], v[76:79]
	v_mfma_f32_16x16x32_bf16 v[72:75], v[178:181], v[202:205], v[72:75]
	v_mfma_f32_16x16x32_bf16 v[68:71], v[170:173], v[210:213], v[68:71]
	v_mfma_f32_16x16x32_bf16 v[64:67], v[178:181], v[210:213], v[64:67]
	s_setprio 0
	s_barrier
	s_or_b32 s56, s55, 0x80
	s_add_i32 s57, s57, s18
	v_add_u32_e32 v142, s56, v147
	s_mov_b32 m0, s57
	ds_read_b128 v[182:185], v157 offset:49152
	ds_read_b128 v[186:189], v157 offset:50176
	ds_read_b128 v[190:193], v157 offset:51200
	ds_read_b128 v[194:197], v157 offset:52224
	ds_read_b128 v[198:201], v157 offset:53248
	ds_read_b128 v[202:205], v157 offset:54272
	ds_read_b128 v[206:209], v157 offset:55296
	ds_read_b128 v[210:213], v157 offset:56320
	global_load_lds_dwordx4 v142, s[14:15]
	v_add_u32_e32 v142, s56, v149
	s_add_i32 m0, s57, 0x2000
	s_add_i32 s55, s55, 0x80080
	s_add_i32 s56, s58, s18
	global_load_lds_dwordx4 v142, s[14:15]
	v_add_u32_e32 v142, s55, v147
	s_mov_b32 m0, s56
	s_nop 0
	global_load_lds_dwordx4 v142, s[14:15]
	v_add_u32_e32 v142, s55, v149
	s_add_i32 m0, s56, 0x2000
	s_nop 0
	global_load_lds_dwordx4 v142, s[14:15]
	v_add_u32_e32 v142, s54, v146
	s_mov_b32 m0, s37
	s_nop 0
	global_load_lds_dwordx4 v142, s[12:13]
	v_add_u32_e32 v142, s54, v148
	s_mov_b32 m0, s38
	s_nop 0
	global_load_lds_dwordx4 v142, s[12:13]
	s_waitcnt vmcnt(8)
	s_waitcnt lgkmcnt(0)
	s_barrier
	s_setprio 1
	s_waitcnt lgkmcnt(0)
	v_mfma_f32_16x16x32_bf16 v[60:63], v[134:137], v[182:185], v[60:63]
	v_mfma_f32_16x16x32_bf16 v[56:59], v[158:161], v[182:185], v[56:59]
	v_mfma_f32_16x16x32_bf16 v[52:55], v[134:137], v[190:193], v[52:55]
	v_mfma_f32_16x16x32_bf16 v[48:51], v[158:161], v[190:193], v[48:51]
	v_mfma_f32_16x16x32_bf16 v[44:47], v[134:137], v[198:201], v[44:47]
	v_mfma_f32_16x16x32_bf16 v[40:43], v[158:161], v[198:201], v[40:43]
	v_mfma_f32_16x16x32_bf16 v[36:39], v[134:137], v[206:209], v[36:39]
	v_mfma_f32_16x16x32_bf16 v[32:35], v[158:161], v[206:209], v[32:35]
	v_mfma_f32_16x16x32_bf16 v[60:63], v[138:141], v[186:189], v[60:63]
	v_mfma_f32_16x16x32_bf16 v[56:59], v[162:165], v[186:189], v[56:59]
	v_mfma_f32_16x16x32_bf16 v[52:55], v[138:141], v[194:197], v[52:55]
	v_mfma_f32_16x16x32_bf16 v[48:51], v[162:165], v[194:197], v[48:51]
	v_mfma_f32_16x16x32_bf16 v[44:47], v[138:141], v[202:205], v[44:47]
	v_mfma_f32_16x16x32_bf16 v[40:43], v[162:165], v[202:205], v[40:43]
	v_mfma_f32_16x16x32_bf16 v[36:39], v[138:141], v[210:213], v[36:39]
	v_mfma_f32_16x16x32_bf16 v[32:35], v[162:165], v[210:213], v[32:35]
	s_setprio 0
	s_setprio 1
	v_mfma_f32_16x16x32_bf16 v[28:31], v[166:169], v[182:185], v[28:31]
	v_mfma_f32_16x16x32_bf16 v[24:27], v[174:177], v[182:185], v[24:27]
	v_mfma_f32_16x16x32_bf16 v[20:23], v[166:169], v[190:193], v[20:23]
	v_mfma_f32_16x16x32_bf16 v[16:19], v[174:177], v[190:193], v[16:19]
	v_mfma_f32_16x16x32_bf16 v[12:15], v[166:169], v[198:201], v[12:15]
	v_mfma_f32_16x16x32_bf16 v[8:11], v[174:177], v[198:201], v[8:11]
	v_mfma_f32_16x16x32_bf16 v[4:7], v[166:169], v[206:209], v[4:7]
	v_mfma_f32_16x16x32_bf16 v[0:3], v[174:177], v[206:209], v[0:3]
	v_mfma_f32_16x16x32_bf16 v[28:31], v[170:173], v[186:189], v[28:31]
	v_mfma_f32_16x16x32_bf16 v[24:27], v[178:181], v[186:189], v[24:27]
	v_mfma_f32_16x16x32_bf16 v[20:23], v[170:173], v[194:197], v[20:23]
	v_mfma_f32_16x16x32_bf16 v[16:19], v[178:181], v[194:197], v[16:19]
	v_mfma_f32_16x16x32_bf16 v[12:15], v[170:173], v[202:205], v[12:15]
	v_mfma_f32_16x16x32_bf16 v[8:11], v[178:181], v[202:205], v[8:11]
	v_mfma_f32_16x16x32_bf16 v[4:7], v[170:173], v[210:213], v[4:7]
	v_mfma_f32_16x16x32_bf16 v[0:3], v[178:181], v[210:213], v[0:3]
	s_setprio 0
	s_barrier
	s_add_i32 s53, s53, 2
	s_addk_i32 s51, 0x100
	s_addk_i32 s52, 0x100
	v_add_u32_e32 v132, 0x100, v132
	s_cmp_gt_u32 s53, 29
	v_add_u32_e32 v133, 0x100, v133
	s_cbranch_scc0 .LBB0_1239
	s_branch .Lpeel_after_pl4

; #define PG8_STAGE_A(bufoff, off) PG8_STAGE_X(bufoff, rsA, g.A, off, voffA)
; #define PG8_STAGE_B(bufoff, off) PG8_STAGE_X(bufoff, rsB, g.Bt, off, voffB)
; #define PG8_WAIT_V(n) asm volatile("s_waitcnt vmcnt(" #n ")" ::: "memory")
; #define PG8_BAR __builtin_amdgcn_s_barrier()
; template <class Epi, class Sched, bool ALIGN_EPI, bool F8 = false>
; __device__ __forceinline__ void gemm_phase(LAS unsigned char* lds, const Gemm g, const Sched& S, const Epi& E) {
;     ...
;     const unsigned lds_w32 = (unsigned)__builtin_amdgcn_readfirstlane((int)((unsigned)(uintptr_t)lds + ldsw));
;     constexpr int KOFF = F8 ? 16 : 1024;
;     const int aoff = lds_byte(wr * 64 + fr, F8 ? fq * 16 : fq * 8), boff = lds_byte(wc * 32 + fr, F8 ? fq * 16 : fq * 8);
;     ...
;     PG8_STAGE_B(PG8_SB(0, 0), cB); PG8_STAGE_B(PG8_SB(0, 1), cB + hstepB); PG8_STAGE_A(PG8_SA(0, 0), cA); PG8_STAGE_A(PG8_SA(0, 1), cA + hstepA);
;     if (wr == 1) PG8_BAR;
;     PG8_WAIT_V(2); PG8_BAR;
;     PG8_STAGE_B(PG8_SB(1, 0), cB + kstep); PG8_STAGE_A(PG8_SA(1, 0), cA + kstep); PG8_STAGE_B(PG8_SB(1, 1), cB + hstepB + kstep);
;     PG8_WAIT_V(6); PG8_BAR;
.LBB0_1344:
	s_add_u32 s20, s10, 0xef00000
	s_addc_u32 s21, s11, 0
	s_add_u32 s22, s10, 0x2bf00000
	s_addc_u32 s23, s11, 0
	s_add_u32 s24, s10, 0x32f10000
	s_addc_u32 s25, s11, 0
	s_add_u32 s26, s10, 0xaf00000
	s_addc_u32 s27, s11, 0
	s_add_u32 s28, s10, 0x4a00000
	s_addc_u32 s29, s11, 0
	s_add_u32 s10, s10, 0x32f20000
	s_addc_u32 s11, s11, 0
	s_or_b32 s1, s54, 0x80
	s_add_i32 m0, s36, 0x18000
	v_add_u32_e32 v7, s1, v164
	s_waitcnt vmcnt(2)
	s_barrier
	global_load_lds_dwordx4 v7, s[14:15]
	v_add_u32_e32 v7, s1, v166
	s_add_i32 m0, s36, 0x1a000
	s_or_b32 s1, s55, 0x80
	s_add_i32 s41, s36, 0x8000
	global_load_lds_dwordx4 v7, s[14:15]
	v_add_u32_e32 v7, s1, v163
	s_mov_b32 m0, s41
	s_add_i32 s42, s36, 0xa000
	global_load_lds_dwordx4 v7, s[12:13]
	v_add_u32_e32 v7, s1, v165
	s_mov_b32 m0, s42
	s_or_b32 s1, s54, 0x80080
	global_load_lds_dwordx4 v7, s[12:13]
	s_add_i32 m0, s36, 0x1c000
	v_add_u32_e32 v7, s1, v164
	global_load_lds_dwordx4 v7, s[14:15]
	v_add_u32_e32 v7, s1, v166
	s_add_i32 m0, s36, 0x1e000
	v_lshlrev_b32_e32 v8, 6, v0
	global_load_lds_dwordx4 v7, s[14:15]
	v_and_b32_e32 v7, 48, v0
	s_movk_i32 s1, 0x3c0
	v_lshlrev_b32_e32 v0, 2, v0
	s_lshl_b32 s43, s0, 6
	s_lshl_b32 s0, s0, 13
	v_and_or_b32 v7, v8, s1, v7
	v_and_b32_e32 v0, 32, v0
	v_readlane_b32 s1, v254, 15
	v_bitop3_b32 v8, v7, s0, v0 bitop3:0xde
	s_lshl_b32 s0, s1, 5
	s_and_b32 s44, s0, 0x60
	s_lshl_b32 s0, s44, 7
	v_bitop3_b32 v167, v7, s0, v0 bitop3:0xde
	v_and_b32_e32 v7, 64, v162
	v_xor_b32_e32 v0, 16, v162
	v_add_u32_e32 v7, 64, v7
	v_cmp_lt_i32_e32 vcc, v0, v7
	s_mov_b32 s0, 0x80080
	s_waitcnt vmcnt(6)
	s_cmp_lt_u32 s1, 4
	v_cndmask_b32_e32 v0, v162, v0, vcc
	v_lshlrev_b32_e32 v168, 2, v0
	v_xor_b32_e32 v0, 32, v162
	v_cmp_lt_i32_e32 vcc, v0, v7
	s_cselect_b64 s[30:31], -1, 0
	s_add_i32 s47, 0, 0x10000
	v_cndmask_b32_e32 v0, v162, v0, vcc
	v_lshlrev_b32_e32 v169, 2, v0
	v_lshlrev_b32_e32 v0, 15, v4
	v_and_b32_e32 v0, 0xffff0000, v0
	v_lshl_add_u32 v0, v5, 12, v0
	v_and_b32_e32 v4, 1, v4
	v_lshl_or_b32 v0, v4, 6, v0
	v_lshlrev_b32_e32 v4, 1, v6
	v_add3_u32 v170, v0, v4, s0
	v_lshlrev_b32_e32 v0, 15, v1
	v_and_b32_e32 v0, 0xffff0000, v0
	v_lshl_add_u32 v0, v2, 12, v0
	v_and_b32_e32 v1, 1, v1
	v_lshl_or_b32 v0, v1, 6, v0
	v_lshlrev_b32_e32 v1, 1, v3
	s_add_i32 s48, 0, 0x14000
	s_ashr_i32 s45, s18, 31
	s_ashr_i32 s46, s19, 31
	v_add3_u32 v171, v0, v1, s0
	v_mov_b64_e32 v[136:137], 0x200
	v_mov_b64_e32 v[138:139], 0x1ff
	v_add_u32_e32 v172, s47, v167
	v_add_u32_e32 v173, s48, v167
	v_add_u32_e32 v174, 0, v8
	v_mov_b32_e32 v175, 0x358637bd
	s_mov_b32 s49, 0x800000
	s_mov_b64 s[34:35], 0x80
	s_barrier
	s_mov_b32 s80, 0
	s_branch .LBB0_1347

; template <class Epi, class Sched, bool ALIGN_EPI, bool F8 = false>
; __device__ __forceinline__ void gemm_phase(LAS unsigned char* lds, const Gemm g, const Sched& S, const Epi& E) {
;     ...
;         if (!has_next) break;
; #pragma unroll
;         for (int a = 0; a < 2; ++a)
; #pragma unroll
;             for (int b = 0; b < 2; ++b)
; #pragma unroll
;                 for (int m = 0; m < 4; ++m)
; #pragma unroll
;                     for (int n = 0; n < 2; ++n) acc[a][b][m][n] = (f32x4){0.f, 0.f, 0.f, 0.f};
;         cur = nxt; cA = nA; cB = nB; ++ui;
.LBB0_1346:
	s_mov_b32 s80, 1
	s_andn2_b64 vcc, exec, s[0:1]
	s_mov_b32 s4, s50
	s_mov_b32 s5, s51
	s_mov_b32 s54, s53
	s_mov_b32 s55, s52
	s_cbranch_vccz .LBB0_1376

; #define PG8_STAGE_A(bufoff, off) PG8_STAGE_X(bufoff, rsA, g.A, off, voffA)
; #define PG8_LDA(dst, b, h) do { _Pragma("unroll") for (int m = 0; m < 4; ++m) _Pragma("unroll") for (int k = 0; k < 2; ++k) { const v4i_t f_ = *(const LAS v4i_t*)(lds + PG8_SA(b, h) + aoff + m * 2048 + k * KOFF); dst[m][4 * k] = f_[0]; dst[m][4 * k + 1] = f_[1]; dst[m][4 * k + 2] = f_[2]; dst[m][4 * k + 3] = f_[3]; } } while (0)
; #define PG8_LDB(dst, b, h) do { _Pragma("unroll") for (int n = 0; n < 2; ++n) _Pragma("unroll") for (int k = 0; k < 2; ++k) { const v4i_t f_ = *(const LAS v4i_t*)(lds + PG8_SB(b, h) + boff + n * 2048 + k * KOFF); dst[n][4 * k] = f_[0]; dst[n][4 * k + 1] = f_[1]; dst[n][4 * k + 2] = f_[2]; dst[n][4 * k + 3] = f_[3]; } } while (0)
; #define PG8_WAIT_V(n) asm volatile("s_waitcnt vmcnt(" #n ")" ::: "memory")
; #define PG8_WAIT_L(n) asm volatile("s_waitcnt lgkmcnt(" #n ")" ::: "memory")
; #define PG8_BAR __builtin_amdgcn_s_barrier()
; #define PG8_SCHED __builtin_amdgcn_sched_barrier(0)
; template <class Epi, class Sched, bool ALIGN_EPI, bool F8 = false>
; __device__ __forceinline__ void gemm_phase(LAS unsigned char* lds, const Gemm g, const Sched& S, const Epi& E) {
;     ...
;         for (int t = 0; t < nt; t += 2) {
;             const bool last = (t == nt - 2);
;             const unsigned a1 = cA + (unsigned)(t + 1) * kstep;
;             const unsigned a2 = last ? nA : cA + (unsigned)(t + 2) * kstep; const unsigned b2 = last ? nB : cB + (unsigned)(t + 2) * kstep;
;             const unsigned a3 = a2 + kstep; const unsigned b3 = b2 + kstep;
;             PG8_LDB(B0, 0, 0); PG8_LDB(B1, 0, 1); PG8_SCHED; PG8_LDA(At, 0, 0); PG8_STAGE_A(PG8_SA(1, 1), a1 + hstepA);
;             PG8_WAIT_V(8); PG8_WAIT_L(0); PG8_BAR; PG8_MMA(0, 0, At, B0); PG8_MMA(0, 1, At, B1); PG8_BAR; PG8_SCHED;
;     ...
; #pragma unroll
;         for (int a = 0; a < 2; ++a)
; #pragma unroll
;             for (int b = 0; b < 2; ++b)
; #pragma unroll
;                 for (int m = 0; m < 4; ++m)
; #pragma unroll
;                     for (int n = 0; n < 2; ++n) acc[a][b][m][n] = (f32x4){0.f, 0.f, 0.f, 0.f};
;         cur = nxt; cA = nA; cB = nB; ++ui;
.LBB0_1353:
	s_lshl_b32 s52, s51, 20
	s_and_b64 s[0:1], s[2:3], exec
	s_cselect_b32 s0, s52, s55
	s_lshl_b32 s53, s50, 20
	s_and_b64 s[56:57], s[2:3], exec
	v_mov_b32_e32 v0, 0
	s_cselect_b32 s1, s53, s54
	v_add_u32_e32 v128, s55, v170
	v_add_u32_e32 v129, s55, v171
	s_addk_i32 s54, 0x100
	s_addk_i32 s55, 0x100
	s_mov_b32 s56, -2
	s_waitcnt lgkmcnt(0)
	v_mov_b32_e32 v1, v0
	v_mov_b32_e32 v2, v0
	v_mov_b32_e32 v3, v0
	v_mov_b32_e32 v4, v0
	v_mov_b32_e32 v5, v0
	v_mov_b32_e32 v6, v0
	v_mov_b32_e32 v7, v0
	v_mov_b32_e32 v8, v0
	v_mov_b32_e32 v9, v0
	v_mov_b32_e32 v10, v0
	v_mov_b32_e32 v11, v0
	v_mov_b32_e32 v12, v0
	v_mov_b32_e32 v13, v0
	v_mov_b32_e32 v14, v0
	v_mov_b32_e32 v15, v0
	v_mov_b32_e32 v16, v0
	v_mov_b32_e32 v17, v0
	v_mov_b32_e32 v18, v0
	v_mov_b32_e32 v19, v0
	v_mov_b32_e32 v20, v0
	v_mov_b32_e32 v21, v0
	v_mov_b32_e32 v22, v0
	v_mov_b32_e32 v23, v0
	v_mov_b32_e32 v24, v0
	v_mov_b32_e32 v25, v0
	v_mov_b32_e32 v26, v0
	v_mov_b32_e32 v27, v0
	v_mov_b32_e32 v28, v0
	v_mov_b32_e32 v29, v0
	v_mov_b32_e32 v30, v0
	v_mov_b32_e32 v31, v0
	v_mov_b32_e32 v32, v0
	v_mov_b32_e32 v33, v0
	v_mov_b32_e32 v34, v0
	v_mov_b32_e32 v35, v0
	v_mov_b32_e32 v36, v0
	v_mov_b32_e32 v37, v0
	v_mov_b32_e32 v38, v0
	v_mov_b32_e32 v39, v0
	v_mov_b32_e32 v40, v0
	v_mov_b32_e32 v41, v0
	v_mov_b32_e32 v42, v0
	v_mov_b32_e32 v43, v0
	v_mov_b32_e32 v44, v0
	v_mov_b32_e32 v45, v0
	v_mov_b32_e32 v46, v0
	v_mov_b32_e32 v47, v0
	v_mov_b32_e32 v48, v0
	v_mov_b32_e32 v49, v0
	v_mov_b32_e32 v50, v0
	v_mov_b32_e32 v51, v0
	v_mov_b32_e32 v52, v0
	v_mov_b32_e32 v53, v0
	v_mov_b32_e32 v54, v0
	v_mov_b32_e32 v55, v0
	v_mov_b32_e32 v56, v0
	v_mov_b32_e32 v57, v0
	v_mov_b32_e32 v58, v0
	v_mov_b32_e32 v59, v0
	v_mov_b32_e32 v60, v0
	v_mov_b32_e32 v61, v0
	v_mov_b32_e32 v62, v0
	v_mov_b32_e32 v63, v0
	v_mov_b32_e32 v64, v0
	v_mov_b32_e32 v65, v0
	v_mov_b32_e32 v66, v0
	v_mov_b32_e32 v67, v0
	v_mov_b32_e32 v68, v0
	v_mov_b32_e32 v69, v0
	v_mov_b32_e32 v70, v0
	v_mov_b32_e32 v71, v0
	v_mov_b32_e32 v72, v0
	v_mov_b32_e32 v73, v0
	v_mov_b32_e32 v74, v0
	v_mov_b32_e32 v75, v0
	v_mov_b32_e32 v76, v0
	v_mov_b32_e32 v77, v0
	v_mov_b32_e32 v78, v0
	v_mov_b32_e32 v79, v0
	v_mov_b32_e32 v80, v0
	v_mov_b32_e32 v81, v0
	v_mov_b32_e32 v82, v0
	v_mov_b32_e32 v83, v0
	v_mov_b32_e32 v84, v0
	v_mov_b32_e32 v85, v0
	v_mov_b32_e32 v86, v0
	v_mov_b32_e32 v87, v0
	v_mov_b32_e32 v88, v0
	v_mov_b32_e32 v89, v0
	v_mov_b32_e32 v90, v0
	v_mov_b32_e32 v91, v0
	v_mov_b32_e32 v92, v0
	v_mov_b32_e32 v93, v0
	v_mov_b32_e32 v94, v0
	v_mov_b32_e32 v95, v0
	v_mov_b32_e32 v96, v0
	v_mov_b32_e32 v97, v0
	v_mov_b32_e32 v98, v0
	v_mov_b32_e32 v99, v0
	v_mov_b32_e32 v100, v0
	v_mov_b32_e32 v101, v0
	v_mov_b32_e32 v102, v0
	v_mov_b32_e32 v103, v0
	v_mov_b32_e32 v104, v0
	v_mov_b32_e32 v105, v0
	v_mov_b32_e32 v106, v0
	v_mov_b32_e32 v107, v0
	v_mov_b32_e32 v108, v0
	v_mov_b32_e32 v109, v0
	v_mov_b32_e32 v110, v0
	v_mov_b32_e32 v111, v0
	v_mov_b32_e32 v112, v0
	v_mov_b32_e32 v113, v0
	v_mov_b32_e32 v114, v0
	v_mov_b32_e32 v115, v0
	v_mov_b32_e32 v116, v0
	v_mov_b32_e32 v117, v0
	v_mov_b32_e32 v118, v0
	v_mov_b32_e32 v119, v0
	v_mov_b32_e32 v120, v0
	v_mov_b32_e32 v121, v0
	v_mov_b32_e32 v122, v0
	v_mov_b32_e32 v123, v0
	v_mov_b32_e32 v124, v0
	v_mov_b32_e32 v125, v0
	v_mov_b32_e32 v126, v0
	v_mov_b32_e32 v127, v0
	s_cmp_lg_u32 s80, 0
	s_cbranch_scc0 .LBB0_1354
	ds_read_b128 v[130:133], v172
	ds_read_b128 v[140:143], v172 offset:1024
	ds_read_b128 v[144:147], v172 offset:2048
	ds_read_b128 v[148:151], v172 offset:3072
	ds_read_b128 v[152:155], v173
	ds_read_b128 v[156:159], v173 offset:1024
	ds_read_b128 v[176:179], v173 offset:2048
	ds_read_b128 v[180:183], v173 offset:3072
	s_cmp_eq_u32 s56, 28
	s_cselect_b32 s59, s0, s55
	s_cselect_b32 s58, s1, s54
	s_or_b32 s57, s59, 0x80
	s_add_i32 m0, s36, 0xc000
	ds_read_b128 v[184:187], v174
	ds_read_b128 v[188:191], v174 offset:1024
	ds_read_b128 v[192:195], v174 offset:2048
	ds_read_b128 v[196:199], v174 offset:3072
	ds_read_b128 v[200:203], v174 offset:4096
	ds_read_b128 v[204:207], v174 offset:5120
	ds_read_b128 v[208:211], v174 offset:6144
	ds_read_b128 v[212:215], v174 offset:7168
	global_load_lds_dwordx4 v129, s[12:13]
	s_add_i32 m0, s36, 0xe000
	s_nop 0
	global_load_lds_dwordx4 v128, s[12:13]
	s_waitcnt vmcnt(63)
	s_waitcnt lgkmcnt(0)
	s_barrier
	s_setprio 1
	s_waitcnt lgkmcnt(0)
	v_mfma_f32_16x16x32_bf16 v[124:127], v[130:133], v[184:187], v[124:127]
	v_mfma_f32_16x16x32_bf16 v[120:123], v[144:147], v[184:187], v[120:123]
	v_mfma_f32_16x16x32_bf16 v[116:119], v[130:133], v[192:195], v[116:119]
	v_mfma_f32_16x16x32_bf16 v[112:115], v[144:147], v[192:195], v[112:115]
	v_mfma_f32_16x16x32_bf16 v[108:111], v[130:133], v[200:203], v[108:111]
	v_mfma_f32_16x16x32_bf16 v[104:107], v[144:147], v[200:203], v[104:107]
	v_mfma_f32_16x16x32_bf16 v[100:103], v[130:133], v[208:211], v[100:103]
	v_mfma_f32_16x16x32_bf16 v[96:99], v[144:147], v[208:211], v[96:99]
	v_mfma_f32_16x16x32_bf16 v[124:127], v[140:143], v[188:191], v[124:127]
	v_mfma_f32_16x16x32_bf16 v[120:123], v[148:151], v[188:191], v[120:123]
	v_mfma_f32_16x16x32_bf16 v[116:119], v[140:143], v[196:199], v[116:119]
	v_mfma_f32_16x16x32_bf16 v[112:115], v[148:151], v[196:199], v[112:115]
	v_mfma_f32_16x16x32_bf16 v[108:111], v[140:143], v[204:207], v[108:111]
	v_mfma_f32_16x16x32_bf16 v[104:107], v[148:151], v[204:207], v[104:107]
	v_mfma_f32_16x16x32_bf16 v[100:103], v[140:143], v[212:215], v[100:103]
	v_mfma_f32_16x16x32_bf16 v[96:99], v[148:151], v[212:215], v[96:99]
	s_setprio 0
	s_setprio 1
	v_mfma_f32_16x16x32_bf16 v[92:95], v[152:155], v[184:187], v[92:95]
	v_mfma_f32_16x16x32_bf16 v[88:91], v[176:179], v[184:187], v[88:91]
	v_mfma_f32_16x16x32_bf16 v[84:87], v[152:155], v[192:195], v[84:87]
	v_mfma_f32_16x16x32_bf16 v[80:83], v[176:179], v[192:195], v[80:83]
	v_mfma_f32_16x16x32_bf16 v[76:79], v[152:155], v[200:203], v[76:79]
	v_mfma_f32_16x16x32_bf16 v[72:75], v[176:179], v[200:203], v[72:75]
	v_mfma_f32_16x16x32_bf16 v[68:71], v[152:155], v[208:211], v[68:71]
	v_mfma_f32_16x16x32_bf16 v[64:67], v[176:179], v[208:211], v[64:67]
	v_mfma_f32_16x16x32_bf16 v[92:95], v[156:159], v[188:191], v[92:95]
	v_mfma_f32_16x16x32_bf16 v[88:91], v[180:183], v[188:191], v[88:91]
	v_mfma_f32_16x16x32_bf16 v[84:87], v[156:159], v[196:199], v[84:87]
	v_mfma_f32_16x16x32_bf16 v[80:83], v[180:183], v[196:199], v[80:83]
	v_mfma_f32_16x16x32_bf16 v[76:79], v[156:159], v[204:207], v[76:79]
	v_mfma_f32_16x16x32_bf16 v[72:75], v[180:183], v[204:207], v[72:75]
	v_mfma_f32_16x16x32_bf16 v[68:71], v[156:159], v[212:215], v[68:71]
	v_mfma_f32_16x16x32_bf16 v[64:67], v[180:183], v[212:215], v[64:67]
	s_setprio 0
	s_barrier
; #define PG8_STAGE_A(bufoff, off) PG8_STAGE_X(bufoff, rsA, g.A, off, voffA)
; #define PG8_STAGE_B(bufoff, off) PG8_STAGE_X(bufoff, rsB, g.Bt, off, voffB)
; #define PG8_LDA(dst, b, h) do { _Pragma("unroll") for (int m = 0; m < 4; ++m) _Pragma("unroll") for (int k = 0; k < 2; ++k) { const v4i_t f_ = *(const LAS v4i_t*)(lds + PG8_SA(b, h) + aoff + m * 2048 + k * KOFF); dst[m][4 * k] = f_[0]; dst[m][4 * k + 1] = f_[1]; dst[m][4 * k + 2] = f_[2]; dst[m][4 * k + 3] = f_[3]; } } while (0)
; #define PG8_LDB(dst, b, h) do { _Pragma("unroll") for (int n = 0; n < 2; ++n) _Pragma("unroll") for (int k = 0; k < 2; ++k) { const v4i_t f_ = *(const LAS v4i_t*)(lds + PG8_SB(b, h) + boff + n * 2048 + k * KOFF); dst[n][4 * k] = f_[0]; dst[n][4 * k + 1] = f_[1]; dst[n][4 * k + 2] = f_[2]; dst[n][4 * k + 3] = f_[3]; } } while (0)
; #define PG8_WAIT_V(n) asm volatile("s_waitcnt vmcnt(" #n ")" ::: "memory")
; #define PG8_WAIT_L(n) asm volatile("s_waitcnt lgkmcnt(" #n ")" ::: "memory")
; #define PG8_BAR __builtin_amdgcn_s_barrier()
; #define PG8_SCHED __builtin_amdgcn_sched_barrier(0)
; template <class Epi, class Sched, bool ALIGN_EPI, bool F8 = false>
; __device__ __forceinline__ void gemm_phase(LAS unsigned char* lds, const Gemm g, const Sched& S, const Epi& E) {
;     ...
;             PG8_LDB(B0, 0, 0); PG8_LDB(B1, 0, 1); PG8_SCHED; PG8_LDA(At, 0, 0); PG8_STAGE_A(PG8_SA(1, 1), a1 + hstepA);
;             PG8_WAIT_V(8); PG8_WAIT_L(0); PG8_BAR; PG8_MMA(0, 0, At, B0); PG8_MMA(0, 1, At, B1); PG8_BAR; PG8_SCHED;
;             PG8_LDA(At, 0, 1); PG8_STAGE_B(PG8_SB(0, 0), b2); PG8_STAGE_B(PG8_SB(0, 1), b2 + hstepB); PG8_STAGE_A(PG8_SA(0, 0), a2);
;             PG8_WAIT_V(8); PG8_WAIT_L(0); PG8_BAR; PG8_MMA(1, 0, At, B0); PG8_MMA(1, 1, At, B1); PG8_BAR; PG8_SCHED;
;             PG8_LDB(B0, 1, 0); PG8_LDB(B1, 1, 1); PG8_SCHED; PG8_LDA(At, 1, 0); PG8_STAGE_A(PG8_SA(0, 1), a2 + hstepA);
;             PG8_WAIT_V(8); PG8_WAIT_L(0); PG8_BAR; PG8_MMA(0, 0, At, B0); PG8_MMA(0, 1, At, B1); PG8_BAR; PG8_SCHED;
	s_add_i32 s60, s47, s33
	v_add_u32_e32 v134, s58, v164
	s_mov_b32 m0, s60
	ds_read_b128 v[184:187], v174 offset:16384
	ds_read_b128 v[188:191], v174 offset:17408
	ds_read_b128 v[192:195], v174 offset:18432
	ds_read_b128 v[196:199], v174 offset:19456
	ds_read_b128 v[200:203], v174 offset:20480
	ds_read_b128 v[204:207], v174 offset:21504
	ds_read_b128 v[208:211], v174 offset:22528
	ds_read_b128 v[212:215], v174 offset:23552
	global_load_lds_dwordx4 v134, s[14:15]
	v_add_u32_e32 v134, s58, v166
	s_add_i32 m0, s60, 0x2000
	s_add_i32 s60, s58, 0x80000
	s_add_i32 s61, s48, s33
	global_load_lds_dwordx4 v134, s[14:15]
	v_add_u32_e32 v134, s60, v164
	s_mov_b32 m0, s61
	s_nop 0
	global_load_lds_dwordx4 v134, s[14:15]
	v_add_u32_e32 v134, s60, v166
	s_add_i32 m0, s61, 0x2000
	s_nop 0
	global_load_lds_dwordx4 v134, s[14:15]
	v_add_u32_e32 v134, s59, v163
	s_mov_b32 m0, s36
	s_nop 0
	global_load_lds_dwordx4 v134, s[12:13]
	v_add_u32_e32 v134, s59, v165
	s_mov_b32 m0, s37
	s_nop 0
	global_load_lds_dwordx4 v134, s[12:13]
	s_waitcnt vmcnt(63)
	s_waitcnt lgkmcnt(0)
	s_barrier
	s_setprio 1
	s_waitcnt lgkmcnt(0)
	v_mfma_f32_16x16x32_bf16 v[60:63], v[130:133], v[184:187], v[60:63]
	v_mfma_f32_16x16x32_bf16 v[56:59], v[144:147], v[184:187], v[56:59]
	v_mfma_f32_16x16x32_bf16 v[52:55], v[130:133], v[192:195], v[52:55]
	v_mfma_f32_16x16x32_bf16 v[48:51], v[144:147], v[192:195], v[48:51]
	v_mfma_f32_16x16x32_bf16 v[44:47], v[130:133], v[200:203], v[44:47]
	v_mfma_f32_16x16x32_bf16 v[40:43], v[144:147], v[200:203], v[40:43]
	v_mfma_f32_16x16x32_bf16 v[36:39], v[130:133], v[208:211], v[36:39]
	v_mfma_f32_16x16x32_bf16 v[32:35], v[144:147], v[208:211], v[32:35]
	v_mfma_f32_16x16x32_bf16 v[60:63], v[140:143], v[188:191], v[60:63]
	v_mfma_f32_16x16x32_bf16 v[56:59], v[148:151], v[188:191], v[56:59]
	v_mfma_f32_16x16x32_bf16 v[52:55], v[140:143], v[196:199], v[52:55]
	v_mfma_f32_16x16x32_bf16 v[48:51], v[148:151], v[196:199], v[48:51]
	v_mfma_f32_16x16x32_bf16 v[44:47], v[140:143], v[204:207], v[44:47]
	v_mfma_f32_16x16x32_bf16 v[40:43], v[148:151], v[204:207], v[40:43]
	v_mfma_f32_16x16x32_bf16 v[36:39], v[140:143], v[212:215], v[36:39]
	v_mfma_f32_16x16x32_bf16 v[32:35], v[148:151], v[212:215], v[32:35]
	s_setprio 0
	s_setprio 1
	v_mfma_f32_16x16x32_bf16 v[28:31], v[152:155], v[184:187], v[28:31]
	v_mfma_f32_16x16x32_bf16 v[24:27], v[176:179], v[184:187], v[24:27]
	v_mfma_f32_16x16x32_bf16 v[20:23], v[152:155], v[192:195], v[20:23]
	v_mfma_f32_16x16x32_bf16 v[16:19], v[176:179], v[192:195], v[16:19]
	v_mfma_f32_16x16x32_bf16 v[12:15], v[152:155], v[200:203], v[12:15]
	v_mfma_f32_16x16x32_bf16 v[8:11], v[176:179], v[200:203], v[8:11]
	v_mfma_f32_16x16x32_bf16 v[4:7], v[152:155], v[208:211], v[4:7]
	v_mfma_f32_16x16x32_bf16 v[0:3], v[176:179], v[208:211], v[0:3]
	v_mfma_f32_16x16x32_bf16 v[28:31], v[156:159], v[188:191], v[28:31]
	v_mfma_f32_16x16x32_bf16 v[24:27], v[180:183], v[188:191], v[24:27]
	v_mfma_f32_16x16x32_bf16 v[20:23], v[156:159], v[196:199], v[20:23]
	v_mfma_f32_16x16x32_bf16 v[16:19], v[180:183], v[196:199], v[16:19]
	v_mfma_f32_16x16x32_bf16 v[12:15], v[156:159], v[204:207], v[12:15]
	v_mfma_f32_16x16x32_bf16 v[8:11], v[180:183], v[204:207], v[8:11]
	v_mfma_f32_16x16x32_bf16 v[4:7], v[156:159], v[212:215], v[4:7]
	v_mfma_f32_16x16x32_bf16 v[0:3], v[180:183], v[212:215], v[0:3]
	s_setprio 0
	s_barrier
	s_add_i32 s60, 0, 0x18000
	v_add_u32_e32 v134, s60, v167
	s_add_i32 s61, 0, 0x1c000
	ds_read_b128 v[130:133], v134
	ds_read_b128 v[140:143], v134 offset:1024
	ds_read_b128 v[144:147], v134 offset:2048
	ds_read_b128 v[148:151], v134 offset:3072
	v_add_u32_e32 v134, s61, v167
	ds_read_b128 v[152:155], v134
	ds_read_b128 v[156:159], v134 offset:1024
	ds_read_b128 v[176:179], v134 offset:2048
	ds_read_b128 v[180:183], v134 offset:3072
	s_add_i32 s59, s59, 0x80000
	s_mov_b32 m0, s38
	v_add_u32_e32 v134, s59, v163
	ds_read_b128 v[184:187], v174 offset:32768
	ds_read_b128 v[188:191], v174 offset:33792
	ds_read_b128 v[192:195], v174 offset:34816
	ds_read_b128 v[196:199], v174 offset:35840
	ds_read_b128 v[200:203], v174 offset:36864
	ds_read_b128 v[204:207], v174 offset:37888
	ds_read_b128 v[208:211], v174 offset:38912
	ds_read_b128 v[212:215], v174 offset:39936
	global_load_lds_dwordx4 v134, s[12:13]
	v_add_u32_e32 v134, s59, v165
	s_mov_b32 m0, s39
	s_nop 0
	global_load_lds_dwordx4 v134, s[12:13]
	s_waitcnt vmcnt(8)
	s_waitcnt lgkmcnt(0)
	s_barrier
; #define PG8_STAGE_A(bufoff, off) PG8_STAGE_X(bufoff, rsA, g.A, off, voffA)
; #define PG8_STAGE_B(bufoff, off) PG8_STAGE_X(bufoff, rsB, g.Bt, off, voffB)
; #define PG8_LDA(dst, b, h) do { _Pragma("unroll") for (int m = 0; m < 4; ++m) _Pragma("unroll") for (int k = 0; k < 2; ++k) { const v4i_t f_ = *(const LAS v4i_t*)(lds + PG8_SA(b, h) + aoff + m * 2048 + k * KOFF); dst[m][4 * k] = f_[0]; dst[m][4 * k + 1] = f_[1]; dst[m][4 * k + 2] = f_[2]; dst[m][4 * k + 3] = f_[3]; } } while (0)
; #define PG8_WAIT_V(n) asm volatile("s_waitcnt vmcnt(" #n ")" ::: "memory")
; #define PG8_WAIT_L(n) asm volatile("s_waitcnt lgkmcnt(" #n ")" ::: "memory")
; #define PG8_BAR __builtin_amdgcn_s_barrier()
; #define PG8_SCHED __builtin_amdgcn_sched_barrier(0)
; template <class Epi, class Sched, bool ALIGN_EPI, bool F8 = false>
; __device__ __forceinline__ void gemm_phase(LAS unsigned char* lds, const Gemm g, const Sched& S, const Epi& E) {
;     ...
;             PG8_WAIT_V(8); PG8_WAIT_L(0); PG8_BAR; PG8_MMA(0, 0, At, B0); PG8_MMA(0, 1, At, B1); PG8_BAR; PG8_SCHED;
;             PG8_LDA(At, 1, 1); PG8_STAGE_B(PG8_SB(1, 0), b3); PG8_STAGE_B(PG8_SB(1, 1), b3 + hstepB); PG8_STAGE_A(PG8_SA(1, 0), a3);
;             PG8_WAIT_V(8); PG8_WAIT_L(0); PG8_BAR; PG8_MMA(1, 0, At, B0); PG8_MMA(1, 1, At, B1); PG8_BAR; PG8_SCHED;
	s_setprio 1
	s_waitcnt lgkmcnt(0)
	v_mfma_f32_16x16x32_bf16 v[124:127], v[130:133], v[184:187], v[124:127]
	v_mfma_f32_16x16x32_bf16 v[120:123], v[144:147], v[184:187], v[120:123]
	v_mfma_f32_16x16x32_bf16 v[116:119], v[130:133], v[192:195], v[116:119]
	v_mfma_f32_16x16x32_bf16 v[112:115], v[144:147], v[192:195], v[112:115]
	v_mfma_f32_16x16x32_bf16 v[108:111], v[130:133], v[200:203], v[108:111]
	v_mfma_f32_16x16x32_bf16 v[104:107], v[144:147], v[200:203], v[104:107]
	v_mfma_f32_16x16x32_bf16 v[100:103], v[130:133], v[208:211], v[100:103]
	v_mfma_f32_16x16x32_bf16 v[96:99], v[144:147], v[208:211], v[96:99]
	v_mfma_f32_16x16x32_bf16 v[124:127], v[140:143], v[188:191], v[124:127]
	v_mfma_f32_16x16x32_bf16 v[120:123], v[148:151], v[188:191], v[120:123]
	v_mfma_f32_16x16x32_bf16 v[116:119], v[140:143], v[196:199], v[116:119]
	v_mfma_f32_16x16x32_bf16 v[112:115], v[148:151], v[196:199], v[112:115]
	v_mfma_f32_16x16x32_bf16 v[108:111], v[140:143], v[204:207], v[108:111]
	v_mfma_f32_16x16x32_bf16 v[104:107], v[148:151], v[204:207], v[104:107]
	v_mfma_f32_16x16x32_bf16 v[100:103], v[140:143], v[212:215], v[100:103]
	v_mfma_f32_16x16x32_bf16 v[96:99], v[148:151], v[212:215], v[96:99]
	s_setprio 0
	s_setprio 1
	v_mfma_f32_16x16x32_bf16 v[92:95], v[152:155], v[184:187], v[92:95]
	v_mfma_f32_16x16x32_bf16 v[88:91], v[176:179], v[184:187], v[88:91]
	v_mfma_f32_16x16x32_bf16 v[84:87], v[152:155], v[192:195], v[84:87]
	v_mfma_f32_16x16x32_bf16 v[80:83], v[176:179], v[192:195], v[80:83]
	v_mfma_f32_16x16x32_bf16 v[76:79], v[152:155], v[200:203], v[76:79]
	v_mfma_f32_16x16x32_bf16 v[72:75], v[176:179], v[200:203], v[72:75]
	v_mfma_f32_16x16x32_bf16 v[68:71], v[152:155], v[208:211], v[68:71]
	v_mfma_f32_16x16x32_bf16 v[64:67], v[176:179], v[208:211], v[64:67]
	v_mfma_f32_16x16x32_bf16 v[92:95], v[156:159], v[188:191], v[92:95]
	v_mfma_f32_16x16x32_bf16 v[88:91], v[180:183], v[188:191], v[88:91]
	v_mfma_f32_16x16x32_bf16 v[84:87], v[156:159], v[196:199], v[84:87]
	v_mfma_f32_16x16x32_bf16 v[80:83], v[180:183], v[196:199], v[80:83]
	v_mfma_f32_16x16x32_bf16 v[76:79], v[156:159], v[204:207], v[76:79]
	v_mfma_f32_16x16x32_bf16 v[72:75], v[180:183], v[204:207], v[72:75]
	v_mfma_f32_16x16x32_bf16 v[68:71], v[156:159], v[212:215], v[68:71]
	v_mfma_f32_16x16x32_bf16 v[64:67], v[180:183], v[212:215], v[64:67]
	s_setprio 0
	s_barrier
	s_or_b32 s59, s58, 0x80
	s_add_i32 s60, s60, s33
	v_add_u32_e32 v134, s59, v164
	s_mov_b32 m0, s60
	ds_read_b128 v[184:187], v174 offset:49152
	ds_read_b128 v[188:191], v174 offset:50176
	ds_read_b128 v[192:195], v174 offset:51200
	ds_read_b128 v[196:199], v174 offset:52224
	ds_read_b128 v[200:203], v174 offset:53248
	ds_read_b128 v[204:207], v174 offset:54272
	ds_read_b128 v[208:211], v174 offset:55296
	ds_read_b128 v[212:215], v174 offset:56320
	global_load_lds_dwordx4 v134, s[14:15]
	v_add_u32_e32 v134, s59, v166
	s_add_i32 m0, s60, 0x2000
	s_add_i32 s58, s58, 0x80080
	s_add_i32 s59, s61, s33
	global_load_lds_dwordx4 v134, s[14:15]
	v_add_u32_e32 v134, s58, v164
	s_mov_b32 m0, s59
	s_nop 0
	global_load_lds_dwordx4 v134, s[14:15]
	v_add_u32_e32 v134, s58, v166
	s_add_i32 m0, s59, 0x2000
	s_nop 0
	global_load_lds_dwordx4 v134, s[14:15]
	v_add_u32_e32 v134, s57, v163
	s_mov_b32 m0, s41
	s_nop 0
	global_load_lds_dwordx4 v134, s[12:13]
	v_add_u32_e32 v134, s57, v165
	s_mov_b32 m0, s42
	s_nop 0
	global_load_lds_dwordx4 v134, s[12:13]
	s_waitcnt vmcnt(8)
	s_waitcnt lgkmcnt(0)
	s_barrier
	s_setprio 1
	s_waitcnt lgkmcnt(0)
	v_mfma_f32_16x16x32_bf16 v[60:63], v[130:133], v[184:187], v[60:63]
	v_mfma_f32_16x16x32_bf16 v[56:59], v[144:147], v[184:187], v[56:59]
	v_mfma_f32_16x16x32_bf16 v[52:55], v[130:133], v[192:195], v[52:55]
	v_mfma_f32_16x16x32_bf16 v[48:51], v[144:147], v[192:195], v[48:51]
	v_mfma_f32_16x16x32_bf16 v[44:47], v[130:133], v[200:203], v[44:47]
	v_mfma_f32_16x16x32_bf16 v[40:43], v[144:147], v[200:203], v[40:43]
	v_mfma_f32_16x16x32_bf16 v[36:39], v[130:133], v[208:211], v[36:39]
	v_mfma_f32_16x16x32_bf16 v[32:35], v[144:147], v[208:211], v[32:35]
	v_mfma_f32_16x16x32_bf16 v[60:63], v[140:143], v[188:191], v[60:63]
	v_mfma_f32_16x16x32_bf16 v[56:59], v[148:151], v[188:191], v[56:59]
	v_mfma_f32_16x16x32_bf16 v[52:55], v[140:143], v[196:199], v[52:55]
	v_mfma_f32_16x16x32_bf16 v[48:51], v[148:151], v[196:199], v[48:51]
	v_mfma_f32_16x16x32_bf16 v[44:47], v[140:143], v[204:207], v[44:47]
	v_mfma_f32_16x16x32_bf16 v[40:43], v[148:151], v[204:207], v[40:43]
	v_mfma_f32_16x16x32_bf16 v[36:39], v[140:143], v[212:215], v[36:39]
	v_mfma_f32_16x16x32_bf16 v[32:35], v[148:151], v[212:215], v[32:35]
	s_setprio 0
	s_setprio 1
	v_mfma_f32_16x16x32_bf16 v[28:31], v[152:155], v[184:187], v[28:31]
	v_mfma_f32_16x16x32_bf16 v[24:27], v[176:179], v[184:187], v[24:27]
	v_mfma_f32_16x16x32_bf16 v[20:23], v[152:155], v[192:195], v[20:23]
	v_mfma_f32_16x16x32_bf16 v[16:19], v[176:179], v[192:195], v[16:19]
	v_mfma_f32_16x16x32_bf16 v[12:15], v[152:155], v[200:203], v[12:15]
	v_mfma_f32_16x16x32_bf16 v[8:11], v[176:179], v[200:203], v[8:11]
	v_mfma_f32_16x16x32_bf16 v[4:7], v[152:155], v[208:211], v[4:7]
	v_mfma_f32_16x16x32_bf16 v[0:3], v[176:179], v[208:211], v[0:3]
	v_mfma_f32_16x16x32_bf16 v[28:31], v[156:159], v[188:191], v[28:31]
	v_mfma_f32_16x16x32_bf16 v[24:27], v[180:183], v[188:191], v[24:27]
	v_mfma_f32_16x16x32_bf16 v[20:23], v[156:159], v[196:199], v[20:23]
	v_mfma_f32_16x16x32_bf16 v[16:19], v[180:183], v[196:199], v[16:19]
	v_mfma_f32_16x16x32_bf16 v[12:15], v[156:159], v[204:207], v[12:15]
	v_mfma_f32_16x16x32_bf16 v[8:11], v[180:183], v[204:207], v[8:11]
	v_mfma_f32_16x16x32_bf16 v[4:7], v[156:159], v[212:215], v[4:7]
	v_mfma_f32_16x16x32_bf16 v[0:3], v[180:183], v[212:215], v[0:3]
	s_setprio 0
	s_barrier
	s_add_i32 s56, s56, 2
	s_addk_i32 s54, 0x100
	s_addk_i32 s55, 0x100
	v_add_u32_e32 v128, 0x100, v128
	s_cmp_gt_u32 s56, 29
	v_add_u32_e32 v129, 0x100, v129
	s_cbranch_scc0 .LBB0_1354
	s_branch .Lpeel_after_pl5

;     __device__ bool next(int i, Unit& u) const { if (!S.next(i >> 1, u)) return false; u.z = i & 1; return true; }
;     __device__ bool next(int i, Unit& u) const { if (!S.next(i, u)) return false; u.z = z; return true; }
; #define PG8_STAGE_A(bufoff, off) PG8_STAGE_X(bufoff, rsA, g.A, off, voffA)
; template <class Epi, class Sched, bool ALIGN_EPI, bool F8 = false>
; __device__ __forceinline__ void gemm_phase(LAS unsigned char* lds, const Gemm g, const Sched& S, const Epi& E) {
;     ...
;     for (int i = 0; i < 2; ++i) { int R, C; stage_rc(tid * 16 + i * 8192, R, C); const int Rb = (R & ~31) + perm32(R & 31);
;         voffA[i] = (unsigned)(R * g.lda + C) * 2u; voffB[i] = (unsigned)(Rb * g.ldb + C) * 2u; }
;     const unsigned kstep = (unsigned)(BK * 2);
;     const unsigned hstepA = (unsigned)HALF * g.lda * 2u, hstepB = (unsigned)HALF * g.ldb * 2u;
;     const unsigned tstepA = 2u * hstepA, tstepB = 2u * hstepB;
;     const unsigned ldsw = (unsigned)wid * 1024u;
;     const unsigned lds_w32 = (unsigned)__builtin_amdgcn_readfirstlane((int)((unsigned)(uintptr_t)lds + ldsw));
;     constexpr int KOFF = F8 ? 16 : 1024;
;     const int aoff = lds_byte(wr * 64 + fr, F8 ? fq * 16 : fq * 8), boff = lds_byte(wc * 32 + fr, F8 ? fq * 16 : fq * 8);
;     ...
;     Unit cur, nxt; int ui = 0;
;     if (!S.next(0, cur)) return;
;     f32x4 acc[2][2][4][2];
; #pragma unroll
;     for (int a = 0; a < 2; ++a)
; #pragma unroll
;         for (int b = 0; b < 2; ++b)
; #pragma unroll
;             for (int m = 0; m < 4; ++m)
; #pragma unroll
;                 for (int n = 0; n < 2; ++n) acc[a][b][m][n] = (f32x4){0.f, 0.f, 0.f, 0.f};
;     v8i_t At[4], B0[2], B1[2];
;     unsigned cA = (unsigned)cur.pm * tstepA + (unsigned)cur.z * (unsigned)g.zA, cB = (unsigned)cur.pn * tstepB + (unsigned)cur.z * (unsigned)g.zB;
;     __amdgpu_buffer_rsrc_t rsA = __builtin_amdgcn_make_buffer_rsrc((void*)g.A, 0, 0x7fffffff, 0x00020000), rsB = __builtin_amdgcn_make_buffer_rsrc((void*)g.Bt, 0, 0x7fffffff, 0x00020000); (void)rsA; (void)rsB;
;     PG8_STAGE_B(PG8_SB(0, 0), cB); PG8_STAGE_B(PG8_SB(0, 1), cB + hstepB); PG8_STAGE_A(PG8_SA(0, 0), cA); PG8_STAGE_A(PG8_SA(0, 1), cA + hstepA);
;     if (wr == 1) PG8_BAR;
;     PG8_WAIT_V(2); PG8_BAR;
;     PG8_STAGE_B(PG8_SB(1, 0), cB + kstep); PG8_STAGE_A(PG8_SA(1, 0), cA + kstep); PG8_STAGE_B(PG8_SB(1, 1), cB + hstepB + kstep);
;     PG8_WAIT_V(6); PG8_BAR;
.LBB0_2081:
	s_add_u32 s20, s10, 0xef00000
	s_addc_u32 s21, s11, 0
	s_add_u32 s22, s10, 0x1af00000
	s_addc_u32 s23, s11, 0
	s_add_u32 s24, s10, 0x32f30000
	s_addc_u32 s25, s11, 0
	s_or_b32 s1, s51, 0x80
	s_add_i32 m0, s19, 0x18000
	v_add_u32_e32 v7, s1, v147
	s_waitcnt vmcnt(2)
	s_barrier
	global_load_lds_dwordx4 v7, s[14:15]
	v_add_u32_e32 v7, s1, v149
	s_add_i32 m0, s19, 0x1a000
	s_or_b32 s1, s52, 0x80
	s_add_i32 s37, s19, 0x8000
	global_load_lds_dwordx4 v7, s[14:15]
	v_add_u32_e32 v7, s1, v146
	s_mov_b32 m0, s37
	s_add_i32 s38, s19, 0xa000
	global_load_lds_dwordx4 v7, s[12:13]
	v_add_u32_e32 v7, s1, v148
	s_mov_b32 m0, s38
	s_or_b32 s1, s51, 0x80080
	global_load_lds_dwordx4 v7, s[12:13]
	s_add_i32 m0, s19, 0x1c000
	v_add_u32_e32 v7, s1, v147
	global_load_lds_dwordx4 v7, s[14:15]
	v_add_u32_e32 v7, s1, v149
	s_add_i32 m0, s19, 0x1e000
	v_lshlrev_b32_e32 v8, 6, v0
	global_load_lds_dwordx4 v7, s[14:15]
	v_and_b32_e32 v7, 48, v0
	s_movk_i32 s1, 0x3c0
	v_lshlrev_b32_e32 v0, 2, v0
	s_lshl_b32 s39, s0, 6
	s_lshl_b32 s0, s0, 13
	v_and_or_b32 v7, v8, s1, v7
	v_and_b32_e32 v0, 32, v0
	v_readlane_b32 s1, v254, 15
	v_bitop3_b32 v8, v7, s0, v0 bitop3:0xde
	s_lshl_b32 s0, s1, 5
	s_and_b32 s40, s0, 0x60
	s_lshl_b32 s0, s40, 7
	v_bitop3_b32 v150, v7, s0, v0 bitop3:0xde
	v_and_b32_e32 v7, 64, v144
	v_xor_b32_e32 v0, 16, v144
	v_add_u32_e32 v7, 64, v7
	v_cmp_lt_i32_e32 vcc, v0, v7
	s_mov_b32 s0, 0x80080
	s_waitcnt vmcnt(6)
	s_cmp_lt_u32 s1, 4
	v_cndmask_b32_e32 v0, v144, v0, vcc
	v_lshlrev_b32_e32 v151, 2, v0
	v_xor_b32_e32 v0, 32, v144
	v_cmp_lt_i32_e32 vcc, v0, v7
	s_cselect_b64 s[26:27], -1, 0
	s_add_i32 s43, 0, 0x10000
	v_cndmask_b32_e32 v0, v144, v0, vcc
	v_lshlrev_b32_e32 v152, 2, v0
	v_lshlrev_b32_e32 v0, 15, v4
	v_and_b32_e32 v0, 0xffff0000, v0
	v_lshl_add_u32 v0, v5, 12, v0
	v_and_b32_e32 v4, 1, v4
	v_lshl_or_b32 v0, v4, 6, v0
	v_lshlrev_b32_e32 v4, 1, v6
	v_add3_u32 v153, v0, v4, s0
	v_lshlrev_b32_e32 v0, 15, v1
	v_and_b32_e32 v0, 0xffff0000, v0
	v_lshl_add_u32 v0, v2, 12, v0
	v_and_b32_e32 v1, 1, v1
	v_lshl_or_b32 v0, v1, 6, v0
	v_lshlrev_b32_e32 v1, 1, v3
	s_add_i32 s44, 0, 0x14000
	s_ashr_i32 s41, s30, 31
	s_ashr_i32 s42, s31, 31
	v_add3_u32 v154, v0, v1, s0
	v_mov_b64_e32 v[128:129], 0x200
	v_mov_b64_e32 v[130:131], 0x1ff
	v_add_u32_e32 v155, s43, v150
	v_add_u32_e32 v156, s44, v150
	v_add_u32_e32 v157, 0, v8
	s_mov_b64 s[28:29], 0x80
	s_barrier
	s_mov_b32 s80, 0
	s_branch .LBB0_2084

;     __device__ bool next(int i, Unit& u) const { if (!S.next(i >> 1, u)) return false; u.z = i & 1; return true; }
;     __device__ bool next(int i, Unit& u) const { if (!S.next(i, u)) return false; u.z = z; return true; }
; #define PG8_STAGE_A(bufoff, off) PG8_STAGE_X(bufoff, rsA, g.A, off, voffA)
; template <class Epi, class Sched, bool ALIGN_EPI, bool F8 = false>
; __device__ __forceinline__ void gemm_phase(LAS unsigned char* lds, const Gemm g, const Sched& S, const Epi& E) {
;     ...
;     for (int i = 0; i < 2; ++i) { int R, C; stage_rc(tid * 16 + i * 8192, R, C); const int Rb = (R & ~31) + perm32(R & 31);
;         voffA[i] = (unsigned)(R * g.lda + C) * 2u; voffB[i] = (unsigned)(Rb * g.ldb + C) * 2u; }
;     const unsigned kstep = (unsigned)(BK * 2);
;     const unsigned hstepA = (unsigned)HALF * g.lda * 2u, hstepB = (unsigned)HALF * g.ldb * 2u;
;     const unsigned tstepA = 2u * hstepA, tstepB = 2u * hstepB;
;     const unsigned ldsw = (unsigned)wid * 1024u;
;     const unsigned lds_w32 = (unsigned)__builtin_amdgcn_readfirstlane((int)((unsigned)(uintptr_t)lds + ldsw));
;     constexpr int KOFF = F8 ? 16 : 1024;
;     const int aoff = lds_byte(wr * 64 + fr, F8 ? fq * 16 : fq * 8), boff = lds_byte(wc * 32 + fr, F8 ? fq * 16 : fq * 8);
;     ...
;     Unit cur, nxt; int ui = 0;
;     if (!S.next(0, cur)) return;
;     f32x4 acc[2][2][4][2];
; #pragma unroll
;     for (int a = 0; a < 2; ++a)
; #pragma unroll
;         for (int b = 0; b < 2; ++b)
; #pragma unroll
;             for (int m = 0; m < 4; ++m)
; #pragma unroll
;                 for (int n = 0; n < 2; ++n) acc[a][b][m][n] = (f32x4){0.f, 0.f, 0.f, 0.f};
;     v8i_t At[4], B0[2], B1[2];
;     unsigned cA = (unsigned)cur.pm * tstepA + (unsigned)cur.z * (unsigned)g.zA, cB = (unsigned)cur.pn * tstepB + (unsigned)cur.z * (unsigned)g.zB;
;     __amdgpu_buffer_rsrc_t rsA = __builtin_amdgcn_make_buffer_rsrc((void*)g.A, 0, 0x7fffffff, 0x00020000), rsB = __builtin_amdgcn_make_buffer_rsrc((void*)g.Bt, 0, 0x7fffffff, 0x00020000); (void)rsA; (void)rsB;
;     PG8_STAGE_B(PG8_SB(0, 0), cB); PG8_STAGE_B(PG8_SB(0, 1), cB + hstepB); PG8_STAGE_A(PG8_SA(0, 0), cA); PG8_STAGE_A(PG8_SA(0, 1), cA + hstepA);
;     if (wr == 1) PG8_BAR;
;     PG8_WAIT_V(2); PG8_BAR;
;     PG8_STAGE_B(PG8_SB(1, 0), cB + kstep); PG8_STAGE_A(PG8_SA(1, 0), cA + kstep); PG8_STAGE_B(PG8_SB(1, 1), cB + hstepB + kstep);
;     PG8_WAIT_V(6); PG8_BAR;
.LBB0_2196:
	s_add_u32 s22, s10, 0xef00000
	s_addc_u32 s23, s11, 0
	s_add_u32 s24, s10, 0x2bf00000
	s_addc_u32 s25, s11, 0
	s_add_u32 s26, s10, 0x32f30000
	s_addc_u32 s27, s11, 0
	s_add_u32 s10, s10, 0x32f40000
	s_addc_u32 s11, s11, 0
	s_or_b32 s1, s6, 0x80
	s_add_i32 m0, s34, 0x18000
	v_add_u32_e32 v7, s1, v162
	s_waitcnt vmcnt(2)
	s_barrier
	global_load_lds_dwordx4 v7, s[16:17]
	v_add_u32_e32 v7, s1, v164
	s_add_i32 m0, s34, 0x1a000
	s_or_b32 s1, s7, 0x80
	s_add_i32 s39, s34, 0x8000
	global_load_lds_dwordx4 v7, s[16:17]
	v_add_u32_e32 v7, s1, v161
	s_mov_b32 m0, s39
	s_add_i32 s40, s34, 0xa000
	global_load_lds_dwordx4 v7, s[14:15]
	v_add_u32_e32 v7, s1, v163
	s_mov_b32 m0, s40
	s_or_b32 s1, s6, 0x80080
	global_load_lds_dwordx4 v7, s[14:15]
	s_add_i32 m0, s34, 0x1c000
	v_add_u32_e32 v7, s1, v162
	global_load_lds_dwordx4 v7, s[16:17]
	v_add_u32_e32 v7, s1, v164
	s_add_i32 m0, s34, 0x1e000
	v_lshlrev_b32_e32 v8, 6, v0
	global_load_lds_dwordx4 v7, s[16:17]
	v_and_b32_e32 v7, 48, v0
	s_movk_i32 s1, 0x3c0
	v_lshlrev_b32_e32 v0, 2, v0
	s_lshl_b32 s41, s0, 6
	s_lshl_b32 s0, s0, 13
	v_and_or_b32 v7, v8, s1, v7
	v_and_b32_e32 v0, 32, v0
	v_readlane_b32 s1, v254, 15
	v_bitop3_b32 v8, v7, s0, v0 bitop3:0xde
	s_lshl_b32 s0, s1, 5
	s_and_b32 s42, s0, 0x60
	s_lshl_b32 s0, s42, 7
	v_bitop3_b32 v165, v7, s0, v0 bitop3:0xde
	v_and_b32_e32 v7, 64, v160
	v_xor_b32_e32 v0, 16, v160
	v_add_u32_e32 v7, 64, v7
	v_cmp_lt_i32_e32 vcc, v0, v7
	s_mov_b32 s0, 0x80080
	s_waitcnt vmcnt(6)
	s_cmp_lt_u32 s1, 4
	v_cndmask_b32_e32 v0, v160, v0, vcc
	v_lshlrev_b32_e32 v166, 2, v0
	v_xor_b32_e32 v0, 32, v160
	v_cmp_lt_i32_e32 vcc, v0, v7
	s_cselect_b64 s[28:29], -1, 0
	s_add_i32 s45, 0, 0x10000
	v_cndmask_b32_e32 v0, v160, v0, vcc
	v_lshlrev_b32_e32 v167, 2, v0
	v_lshlrev_b32_e32 v0, 15, v4
	v_and_b32_e32 v0, 0xffff0000, v0
	v_lshl_add_u32 v0, v5, 12, v0
	v_and_b32_e32 v4, 1, v4
	v_lshl_or_b32 v0, v4, 6, v0
	v_lshlrev_b32_e32 v4, 1, v6
	v_add3_u32 v168, v0, v4, s0
	v_lshlrev_b32_e32 v0, 15, v1
	v_and_b32_e32 v0, 0xffff0000, v0
	v_lshl_add_u32 v0, v2, 12, v0
	v_and_b32_e32 v1, 1, v1
	v_lshl_or_b32 v0, v1, 6, v0
	v_lshlrev_b32_e32 v1, 1, v3
	s_add_i32 s46, 0, 0x14000
	s_ashr_i32 s43, s18, 31
	s_ashr_i32 s44, s19, 31
	v_add3_u32 v169, v0, v1, s0
	v_mov_b64_e32 v[128:129], 0x200
	v_mov_b64_e32 v[130:131], 0x1ff
	v_add_u32_e32 v170, s45, v165
	v_add_u32_e32 v171, s46, v165
	v_add_u32_e32 v172, 0, v8
	v_mov_b32_e32 v173, 0x358637bd
	s_mov_b32 s47, 0x800000
	s_mov_b64 s[30:31], 0x80
	s_barrier
	s_mov_b32 s80, 0
	s_branch .LBB0_2199

; #define PG8_BAR __builtin_amdgcn_s_barrier()
; template <class Epi, class Sched, bool ALIGN_EPI, bool F8 = false>
; __device__ __forceinline__ void gemm_phase(LAS unsigned char* lds, const Gemm g, const Sched& S, const Epi& E) {
;     ...
;         if (!has_next) break;
; #pragma unroll
;         for (int a = 0; a < 2; ++a)
; #pragma unroll
;             for (int b = 0; b < 2; ++b)
; #pragma unroll
;                 for (int m = 0; m < 4; ++m)
; #pragma unroll
;                     for (int n = 0; n < 2; ++n) acc[a][b][m][n] = (f32x4){0.f, 0.f, 0.f, 0.f};
;         cur = nxt; cA = nA; cB = nB; ++ui;
;         if constexpr (ALIGN_EPI) { if (wr == 1) PG8_BAR; }
.LBB0_2198:
	s_mov_b32 s80, 1
	s_andn2_b64 vcc, exec, s[0:1]
	s_mov_b32 s4, s48
	s_mov_b32 s5, s49
	s_mov_b32 s6, s51
	s_mov_b32 s7, s50
	s_cbranch_vccz .LBB0_2228

; #define PG8_STAGE_A(bufoff, off) PG8_STAGE_X(bufoff, rsA, g.A, off, voffA)
; #define PG8_LDA(dst, b, h) do { _Pragma("unroll") for (int m = 0; m < 4; ++m) _Pragma("unroll") for (int k = 0; k < 2; ++k) { const v4i_t f_ = *(const LAS v4i_t*)(lds + PG8_SA(b, h) + aoff + m * 2048 + k * KOFF); dst[m][4 * k] = f_[0]; dst[m][4 * k + 1] = f_[1]; dst[m][4 * k + 2] = f_[2]; dst[m][4 * k + 3] = f_[3]; } } while (0)
; #define PG8_LDB(dst, b, h) do { _Pragma("unroll") for (int n = 0; n < 2; ++n) _Pragma("unroll") for (int k = 0; k < 2; ++k) { const v4i_t f_ = *(const LAS v4i_t*)(lds + PG8_SB(b, h) + boff + n * 2048 + k * KOFF); dst[n][4 * k] = f_[0]; dst[n][4 * k + 1] = f_[1]; dst[n][4 * k + 2] = f_[2]; dst[n][4 * k + 3] = f_[3]; } } while (0)
; #define PG8_WAIT_V(n) asm volatile("s_waitcnt vmcnt(" #n ")" ::: "memory")
; #define PG8_WAIT_L(n) asm volatile("s_waitcnt lgkmcnt(" #n ")" ::: "memory")
; #define PG8_BAR __builtin_amdgcn_s_barrier()
; #define PG8_SCHED __builtin_amdgcn_sched_barrier(0)
; template <class Epi, class Sched, bool ALIGN_EPI, bool F8 = false>
; __device__ __forceinline__ void gemm_phase(LAS unsigned char* lds, const Gemm g, const Sched& S, const Epi& E) {
;     ...
;         for (int t = 0; t < nt; t += 2) {
;             const bool last = (t == nt - 2);
;             const unsigned a1 = cA + (unsigned)(t + 1) * kstep;
;             const unsigned a2 = last ? nA : cA + (unsigned)(t + 2) * kstep; const unsigned b2 = last ? nB : cB + (unsigned)(t + 2) * kstep;
;             const unsigned a3 = a2 + kstep; const unsigned b3 = b2 + kstep;
;             PG8_LDB(B0, 0, 0); PG8_LDB(B1, 0, 1); PG8_SCHED; PG8_LDA(At, 0, 0); PG8_STAGE_A(PG8_SA(1, 1), a1 + hstepA);
;             PG8_WAIT_V(8); PG8_WAIT_L(0); PG8_BAR; PG8_MMA(0, 0, At, B0); PG8_MMA(0, 1, At, B1); PG8_BAR; PG8_SCHED;
;     ...
; #pragma unroll
;         for (int a = 0; a < 2; ++a)
; #pragma unroll
;             for (int b = 0; b < 2; ++b)
; #pragma unroll
;                 for (int m = 0; m < 4; ++m)
; #pragma unroll
;                     for (int n = 0; n < 2; ++n) acc[a][b][m][n] = (f32x4){0.f, 0.f, 0.f, 0.f};
;         cur = nxt; cA = nA; cB = nB; ++ui;
.LBB0_2205:
	s_lshl_b32 s50, s49, 20
	s_and_b64 s[0:1], s[2:3], exec
	s_cselect_b32 s0, s50, s7
	s_lshl_b32 s51, s48, 20
	s_and_b64 s[52:53], s[2:3], exec
	v_mov_b32_e32 v0, 0
	s_cselect_b32 s1, s51, s6
	v_add_u32_e32 v132, s7, v168
	v_add_u32_e32 v133, s7, v169
	s_addk_i32 s6, 0x100
	s_addk_i32 s7, 0x100
	s_mov_b32 s52, -2
	s_waitcnt lgkmcnt(0)
	v_mov_b32_e32 v1, v0
	v_mov_b32_e32 v2, v0
	v_mov_b32_e32 v3, v0
	v_mov_b32_e32 v4, v0
	v_mov_b32_e32 v5, v0
	v_mov_b32_e32 v6, v0
	v_mov_b32_e32 v7, v0
	v_mov_b32_e32 v8, v0
	v_mov_b32_e32 v9, v0
	v_mov_b32_e32 v10, v0
	v_mov_b32_e32 v11, v0
	v_mov_b32_e32 v12, v0
	v_mov_b32_e32 v13, v0
	v_mov_b32_e32 v14, v0
	v_mov_b32_e32 v15, v0
	v_mov_b32_e32 v16, v0
	v_mov_b32_e32 v17, v0
	v_mov_b32_e32 v18, v0
	v_mov_b32_e32 v19, v0
	v_mov_b32_e32 v20, v0
	v_mov_b32_e32 v21, v0
	v_mov_b32_e32 v22, v0
	v_mov_b32_e32 v23, v0
	v_mov_b32_e32 v24, v0
	v_mov_b32_e32 v25, v0
	v_mov_b32_e32 v26, v0
	v_mov_b32_e32 v27, v0
	v_mov_b32_e32 v28, v0
	v_mov_b32_e32 v29, v0
	v_mov_b32_e32 v30, v0
	v_mov_b32_e32 v31, v0
	v_mov_b32_e32 v32, v0
	v_mov_b32_e32 v33, v0
	v_mov_b32_e32 v34, v0
	v_mov_b32_e32 v35, v0
	v_mov_b32_e32 v36, v0
	v_mov_b32_e32 v37, v0
	v_mov_b32_e32 v38, v0
	v_mov_b32_e32 v39, v0
	v_mov_b32_e32 v40, v0
	v_mov_b32_e32 v41, v0
	v_mov_b32_e32 v42, v0
	v_mov_b32_e32 v43, v0
	v_mov_b32_e32 v44, v0
	v_mov_b32_e32 v45, v0
	v_mov_b32_e32 v46, v0
	v_mov_b32_e32 v47, v0
	v_mov_b32_e32 v48, v0
	v_mov_b32_e32 v49, v0
	v_mov_b32_e32 v50, v0
	v_mov_b32_e32 v51, v0
	v_mov_b32_e32 v52, v0
	v_mov_b32_e32 v53, v0
	v_mov_b32_e32 v54, v0
	v_mov_b32_e32 v55, v0
	v_mov_b32_e32 v56, v0
	v_mov_b32_e32 v57, v0
	v_mov_b32_e32 v58, v0
	v_mov_b32_e32 v59, v0
	v_mov_b32_e32 v60, v0
	v_mov_b32_e32 v61, v0
	v_mov_b32_e32 v62, v0
	v_mov_b32_e32 v63, v0
	v_mov_b32_e32 v64, v0
	v_mov_b32_e32 v65, v0
	v_mov_b32_e32 v66, v0
	v_mov_b32_e32 v67, v0
	v_mov_b32_e32 v68, v0
	v_mov_b32_e32 v69, v0
	v_mov_b32_e32 v70, v0
	v_mov_b32_e32 v71, v0
	v_mov_b32_e32 v72, v0
	v_mov_b32_e32 v73, v0
	v_mov_b32_e32 v74, v0
	v_mov_b32_e32 v75, v0
	v_mov_b32_e32 v76, v0
	v_mov_b32_e32 v77, v0
	v_mov_b32_e32 v78, v0
	v_mov_b32_e32 v79, v0
	v_mov_b32_e32 v80, v0
	v_mov_b32_e32 v81, v0
	v_mov_b32_e32 v82, v0
	v_mov_b32_e32 v83, v0
	v_mov_b32_e32 v84, v0
	v_mov_b32_e32 v85, v0
	v_mov_b32_e32 v86, v0
	v_mov_b32_e32 v87, v0
	v_mov_b32_e32 v88, v0
	v_mov_b32_e32 v89, v0
	v_mov_b32_e32 v90, v0
	v_mov_b32_e32 v91, v0
	v_mov_b32_e32 v92, v0
	v_mov_b32_e32 v93, v0
	v_mov_b32_e32 v94, v0
	v_mov_b32_e32 v95, v0
	v_mov_b32_e32 v96, v0
	v_mov_b32_e32 v97, v0
	v_mov_b32_e32 v98, v0
	v_mov_b32_e32 v99, v0
	v_mov_b32_e32 v100, v0
	v_mov_b32_e32 v101, v0
	v_mov_b32_e32 v102, v0
	v_mov_b32_e32 v103, v0
	v_mov_b32_e32 v104, v0
	v_mov_b32_e32 v105, v0
	v_mov_b32_e32 v106, v0
	v_mov_b32_e32 v107, v0
	v_mov_b32_e32 v108, v0
	v_mov_b32_e32 v109, v0
	v_mov_b32_e32 v110, v0
	v_mov_b32_e32 v111, v0
	v_mov_b32_e32 v112, v0
	v_mov_b32_e32 v113, v0
	v_mov_b32_e32 v114, v0
	v_mov_b32_e32 v115, v0
	v_mov_b32_e32 v116, v0
	v_mov_b32_e32 v117, v0
	v_mov_b32_e32 v118, v0
	v_mov_b32_e32 v119, v0
	v_mov_b32_e32 v120, v0
	v_mov_b32_e32 v121, v0
	v_mov_b32_e32 v122, v0
	v_mov_b32_e32 v123, v0
	v_mov_b32_e32 v124, v0
	v_mov_b32_e32 v125, v0
	v_mov_b32_e32 v126, v0
	v_mov_b32_e32 v127, v0
	s_cmp_lg_u32 s80, 0
	s_cbranch_scc0 .LBB0_2206
	ds_read_b128 v[134:137], v170
	ds_read_b128 v[138:141], v170 offset:1024
	ds_read_b128 v[142:145], v170 offset:2048
	ds_read_b128 v[146:149], v170 offset:3072
	ds_read_b128 v[150:153], v171
	ds_read_b128 v[154:157], v171 offset:1024
	ds_read_b128 v[174:177], v171 offset:2048
	ds_read_b128 v[178:181], v171 offset:3072
	s_cmp_eq_u32 s52, 28
	s_cselect_b32 s55, s0, s7
	s_cselect_b32 s54, s1, s6
	s_or_b32 s53, s55, 0x80
	s_add_i32 m0, s34, 0xc000
	ds_read_b128 v[182:185], v172
	ds_read_b128 v[186:189], v172 offset:1024
	ds_read_b128 v[190:193], v172 offset:2048
	ds_read_b128 v[194:197], v172 offset:3072
	ds_read_b128 v[198:201], v172 offset:4096
	ds_read_b128 v[202:205], v172 offset:5120
	ds_read_b128 v[206:209], v172 offset:6144
	ds_read_b128 v[210:213], v172 offset:7168
	global_load_lds_dwordx4 v133, s[14:15]
	s_add_i32 m0, s34, 0xe000
	s_nop 0
	global_load_lds_dwordx4 v132, s[14:15]
	s_waitcnt vmcnt(40)
	s_waitcnt lgkmcnt(0)
	s_barrier
	s_setprio 1
	s_waitcnt lgkmcnt(0)
	v_mfma_f32_16x16x32_bf16 v[124:127], v[134:137], v[182:185], v[124:127]
	v_mfma_f32_16x16x32_bf16 v[120:123], v[142:145], v[182:185], v[120:123]
	v_mfma_f32_16x16x32_bf16 v[116:119], v[134:137], v[190:193], v[116:119]
	v_mfma_f32_16x16x32_bf16 v[112:115], v[142:145], v[190:193], v[112:115]
	v_mfma_f32_16x16x32_bf16 v[108:111], v[134:137], v[198:201], v[108:111]
	v_mfma_f32_16x16x32_bf16 v[104:107], v[142:145], v[198:201], v[104:107]
	v_mfma_f32_16x16x32_bf16 v[100:103], v[134:137], v[206:209], v[100:103]
	v_mfma_f32_16x16x32_bf16 v[96:99], v[142:145], v[206:209], v[96:99]
	v_mfma_f32_16x16x32_bf16 v[124:127], v[138:141], v[186:189], v[124:127]
	v_mfma_f32_16x16x32_bf16 v[120:123], v[146:149], v[186:189], v[120:123]
	v_mfma_f32_16x16x32_bf16 v[116:119], v[138:141], v[194:197], v[116:119]
	v_mfma_f32_16x16x32_bf16 v[112:115], v[146:149], v[194:197], v[112:115]
	v_mfma_f32_16x16x32_bf16 v[108:111], v[138:141], v[202:205], v[108:111]
	v_mfma_f32_16x16x32_bf16 v[104:107], v[146:149], v[202:205], v[104:107]
	v_mfma_f32_16x16x32_bf16 v[100:103], v[138:141], v[210:213], v[100:103]
	v_mfma_f32_16x16x32_bf16 v[96:99], v[146:149], v[210:213], v[96:99]
	s_setprio 0
	s_setprio 1
	v_mfma_f32_16x16x32_bf16 v[92:95], v[150:153], v[182:185], v[92:95]
	v_mfma_f32_16x16x32_bf16 v[88:91], v[174:177], v[182:185], v[88:91]
	v_mfma_f32_16x16x32_bf16 v[84:87], v[150:153], v[190:193], v[84:87]
	v_mfma_f32_16x16x32_bf16 v[80:83], v[174:177], v[190:193], v[80:83]
	v_mfma_f32_16x16x32_bf16 v[76:79], v[150:153], v[198:201], v[76:79]
	v_mfma_f32_16x16x32_bf16 v[72:75], v[174:177], v[198:201], v[72:75]
	v_mfma_f32_16x16x32_bf16 v[68:71], v[150:153], v[206:209], v[68:71]
	v_mfma_f32_16x16x32_bf16 v[64:67], v[174:177], v[206:209], v[64:67]
	v_mfma_f32_16x16x32_bf16 v[92:95], v[154:157], v[186:189], v[92:95]
	v_mfma_f32_16x16x32_bf16 v[88:91], v[178:181], v[186:189], v[88:91]
	v_mfma_f32_16x16x32_bf16 v[84:87], v[154:157], v[194:197], v[84:87]
	v_mfma_f32_16x16x32_bf16 v[80:83], v[178:181], v[194:197], v[80:83]
	v_mfma_f32_16x16x32_bf16 v[76:79], v[154:157], v[202:205], v[76:79]
	v_mfma_f32_16x16x32_bf16 v[72:75], v[178:181], v[202:205], v[72:75]
	v_mfma_f32_16x16x32_bf16 v[68:71], v[154:157], v[210:213], v[68:71]
	v_mfma_f32_16x16x32_bf16 v[64:67], v[178:181], v[210:213], v[64:67]
	s_setprio 0
	s_barrier
; #define PG8_STAGE_A(bufoff, off) PG8_STAGE_X(bufoff, rsA, g.A, off, voffA)
; #define PG8_STAGE_B(bufoff, off) PG8_STAGE_X(bufoff, rsB, g.Bt, off, voffB)
; #define PG8_LDA(dst, b, h) do { _Pragma("unroll") for (int m = 0; m < 4; ++m) _Pragma("unroll") for (int k = 0; k < 2; ++k) { const v4i_t f_ = *(const LAS v4i_t*)(lds + PG8_SA(b, h) + aoff + m * 2048 + k * KOFF); dst[m][4 * k] = f_[0]; dst[m][4 * k + 1] = f_[1]; dst[m][4 * k + 2] = f_[2]; dst[m][4 * k + 3] = f_[3]; } } while (0)
; #define PG8_LDB(dst, b, h) do { _Pragma("unroll") for (int n = 0; n < 2; ++n) _Pragma("unroll") for (int k = 0; k < 2; ++k) { const v4i_t f_ = *(const LAS v4i_t*)(lds + PG8_SB(b, h) + boff + n * 2048 + k * KOFF); dst[n][4 * k] = f_[0]; dst[n][4 * k + 1] = f_[1]; dst[n][4 * k + 2] = f_[2]; dst[n][4 * k + 3] = f_[3]; } } while (0)
; #define PG8_WAIT_V(n) asm volatile("s_waitcnt vmcnt(" #n ")" ::: "memory")
; #define PG8_WAIT_L(n) asm volatile("s_waitcnt lgkmcnt(" #n ")" ::: "memory")
; #define PG8_BAR __builtin_amdgcn_s_barrier()
; #define PG8_SCHED __builtin_amdgcn_sched_barrier(0)
; template <class Epi, class Sched, bool ALIGN_EPI, bool F8 = false>
; __device__ __forceinline__ void gemm_phase(LAS unsigned char* lds, const Gemm g, const Sched& S, const Epi& E) {
;     ...
;             PG8_LDB(B0, 0, 0); PG8_LDB(B1, 0, 1); PG8_SCHED; PG8_LDA(At, 0, 0); PG8_STAGE_A(PG8_SA(1, 1), a1 + hstepA);
;             PG8_WAIT_V(8); PG8_WAIT_L(0); PG8_BAR; PG8_MMA(0, 0, At, B0); PG8_MMA(0, 1, At, B1); PG8_BAR; PG8_SCHED;
;             PG8_LDA(At, 0, 1); PG8_STAGE_B(PG8_SB(0, 0), b2); PG8_STAGE_B(PG8_SB(0, 1), b2 + hstepB); PG8_STAGE_A(PG8_SA(0, 0), a2);
;             PG8_WAIT_V(8); PG8_WAIT_L(0); PG8_BAR; PG8_MMA(1, 0, At, B0); PG8_MMA(1, 1, At, B1); PG8_BAR; PG8_SCHED;
;             PG8_LDB(B0, 1, 0); PG8_LDB(B1, 1, 1); PG8_SCHED; PG8_LDA(At, 1, 0); PG8_STAGE_A(PG8_SA(0, 1), a2 + hstepA);
;             PG8_WAIT_V(8); PG8_WAIT_L(0); PG8_BAR; PG8_MMA(0, 0, At, B0); PG8_MMA(0, 1, At, B1); PG8_BAR; PG8_SCHED;
	s_add_i32 s56, s45, s33
	v_add_u32_e32 v158, s54, v162
	s_mov_b32 m0, s56
	ds_read_b128 v[182:185], v172 offset:16384
	ds_read_b128 v[186:189], v172 offset:17408
	ds_read_b128 v[190:193], v172 offset:18432
	ds_read_b128 v[194:197], v172 offset:19456
	ds_read_b128 v[198:201], v172 offset:20480
	ds_read_b128 v[202:205], v172 offset:21504
	ds_read_b128 v[206:209], v172 offset:22528
	ds_read_b128 v[210:213], v172 offset:23552
	global_load_lds_dwordx4 v158, s[16:17]
	v_add_u32_e32 v158, s54, v164
	s_add_i32 m0, s56, 0x2000
	s_add_i32 s56, s54, 0x80000
	s_add_i32 s57, s46, s33
	global_load_lds_dwordx4 v158, s[16:17]
	v_add_u32_e32 v158, s56, v162
	s_mov_b32 m0, s57
	s_nop 0
	global_load_lds_dwordx4 v158, s[16:17]
	v_add_u32_e32 v158, s56, v164
	s_add_i32 m0, s57, 0x2000
	s_nop 0
	global_load_lds_dwordx4 v158, s[16:17]
	v_add_u32_e32 v158, s55, v161
	s_mov_b32 m0, s34
	s_nop 0
	global_load_lds_dwordx4 v158, s[14:15]
	v_add_u32_e32 v158, s55, v163
	s_mov_b32 m0, s35
	s_nop 0
	global_load_lds_dwordx4 v158, s[14:15]
	s_waitcnt vmcnt(40)
	s_waitcnt lgkmcnt(0)
	s_barrier
	s_setprio 1
	s_waitcnt lgkmcnt(0)
	v_mfma_f32_16x16x32_bf16 v[60:63], v[134:137], v[182:185], v[60:63]
	v_mfma_f32_16x16x32_bf16 v[56:59], v[142:145], v[182:185], v[56:59]
	v_mfma_f32_16x16x32_bf16 v[52:55], v[134:137], v[190:193], v[52:55]
	v_mfma_f32_16x16x32_bf16 v[48:51], v[142:145], v[190:193], v[48:51]
	v_mfma_f32_16x16x32_bf16 v[44:47], v[134:137], v[198:201], v[44:47]
	v_mfma_f32_16x16x32_bf16 v[40:43], v[142:145], v[198:201], v[40:43]
	v_mfma_f32_16x16x32_bf16 v[36:39], v[134:137], v[206:209], v[36:39]
	v_mfma_f32_16x16x32_bf16 v[32:35], v[142:145], v[206:209], v[32:35]
	v_mfma_f32_16x16x32_bf16 v[60:63], v[138:141], v[186:189], v[60:63]
	v_mfma_f32_16x16x32_bf16 v[56:59], v[146:149], v[186:189], v[56:59]
	v_mfma_f32_16x16x32_bf16 v[52:55], v[138:141], v[194:197], v[52:55]
	v_mfma_f32_16x16x32_bf16 v[48:51], v[146:149], v[194:197], v[48:51]
	v_mfma_f32_16x16x32_bf16 v[44:47], v[138:141], v[202:205], v[44:47]
	v_mfma_f32_16x16x32_bf16 v[40:43], v[146:149], v[202:205], v[40:43]
	v_mfma_f32_16x16x32_bf16 v[36:39], v[138:141], v[210:213], v[36:39]
	v_mfma_f32_16x16x32_bf16 v[32:35], v[146:149], v[210:213], v[32:35]
	s_setprio 0
	s_setprio 1
	v_mfma_f32_16x16x32_bf16 v[28:31], v[150:153], v[182:185], v[28:31]
	v_mfma_f32_16x16x32_bf16 v[24:27], v[174:177], v[182:185], v[24:27]
	v_mfma_f32_16x16x32_bf16 v[20:23], v[150:153], v[190:193], v[20:23]
	v_mfma_f32_16x16x32_bf16 v[16:19], v[174:177], v[190:193], v[16:19]
	v_mfma_f32_16x16x32_bf16 v[12:15], v[150:153], v[198:201], v[12:15]
	v_mfma_f32_16x16x32_bf16 v[8:11], v[174:177], v[198:201], v[8:11]
	v_mfma_f32_16x16x32_bf16 v[4:7], v[150:153], v[206:209], v[4:7]
	v_mfma_f32_16x16x32_bf16 v[0:3], v[174:177], v[206:209], v[0:3]
	v_mfma_f32_16x16x32_bf16 v[28:31], v[154:157], v[186:189], v[28:31]
	v_mfma_f32_16x16x32_bf16 v[24:27], v[178:181], v[186:189], v[24:27]
	v_mfma_f32_16x16x32_bf16 v[20:23], v[154:157], v[194:197], v[20:23]
	v_mfma_f32_16x16x32_bf16 v[16:19], v[178:181], v[194:197], v[16:19]
	v_mfma_f32_16x16x32_bf16 v[12:15], v[154:157], v[202:205], v[12:15]
	v_mfma_f32_16x16x32_bf16 v[8:11], v[178:181], v[202:205], v[8:11]
	v_mfma_f32_16x16x32_bf16 v[4:7], v[154:157], v[210:213], v[4:7]
	v_mfma_f32_16x16x32_bf16 v[0:3], v[178:181], v[210:213], v[0:3]
	s_setprio 0
	s_barrier
	s_add_i32 s56, 0, 0x18000
	s_add_i32 s57, 0, 0x1c000
	v_add_u32_e32 v146, s56, v165
	v_add_u32_e32 v158, s57, v165
	ds_read_b128 v[134:137], v146
	ds_read_b128 v[138:141], v146 offset:1024
	ds_read_b128 v[142:145], v146 offset:2048
	ds_read_b128 v[146:149], v146 offset:3072
	ds_read_b128 v[150:153], v158
	ds_read_b128 v[154:157], v158 offset:1024
	ds_read_b128 v[174:177], v158 offset:2048
	ds_read_b128 v[178:181], v158 offset:3072
	s_add_i32 s55, s55, 0x80000
	s_mov_b32 m0, s36
	v_add_u32_e32 v158, s55, v161
	ds_read_b128 v[182:185], v172 offset:32768
	ds_read_b128 v[186:189], v172 offset:33792
	ds_read_b128 v[190:193], v172 offset:34816
	ds_read_b128 v[194:197], v172 offset:35840
	ds_read_b128 v[198:201], v172 offset:36864
	ds_read_b128 v[202:205], v172 offset:37888
	ds_read_b128 v[206:209], v172 offset:38912
	ds_read_b128 v[210:213], v172 offset:39936
	global_load_lds_dwordx4 v158, s[14:15]
	v_add_u32_e32 v158, s55, v163
	s_mov_b32 m0, s37
	s_nop 0
	global_load_lds_dwordx4 v158, s[14:15]
	s_waitcnt vmcnt(8)
	s_waitcnt lgkmcnt(0)
	s_barrier
; #define PG8_STAGE_A(bufoff, off) PG8_STAGE_X(bufoff, rsA, g.A, off, voffA)
; #define PG8_STAGE_B(bufoff, off) PG8_STAGE_X(bufoff, rsB, g.Bt, off, voffB)
; #define PG8_LDA(dst, b, h) do { _Pragma("unroll") for (int m = 0; m < 4; ++m) _Pragma("unroll") for (int k = 0; k < 2; ++k) { const v4i_t f_ = *(const LAS v4i_t*)(lds + PG8_SA(b, h) + aoff + m * 2048 + k * KOFF); dst[m][4 * k] = f_[0]; dst[m][4 * k + 1] = f_[1]; dst[m][4 * k + 2] = f_[2]; dst[m][4 * k + 3] = f_[3]; } } while (0)
; #define PG8_WAIT_V(n) asm volatile("s_waitcnt vmcnt(" #n ")" ::: "memory")
; #define PG8_WAIT_L(n) asm volatile("s_waitcnt lgkmcnt(" #n ")" ::: "memory")
; #define PG8_BAR __builtin_amdgcn_s_barrier()
; #define PG8_SCHED __builtin_amdgcn_sched_barrier(0)
; template <class Epi, class Sched, bool ALIGN_EPI, bool F8 = false>
; __device__ __forceinline__ void gemm_phase(LAS unsigned char* lds, const Gemm g, const Sched& S, const Epi& E) {
;     ...
;             PG8_WAIT_V(8); PG8_WAIT_L(0); PG8_BAR; PG8_MMA(0, 0, At, B0); PG8_MMA(0, 1, At, B1); PG8_BAR; PG8_SCHED;
;             PG8_LDA(At, 1, 1); PG8_STAGE_B(PG8_SB(1, 0), b3); PG8_STAGE_B(PG8_SB(1, 1), b3 + hstepB); PG8_STAGE_A(PG8_SA(1, 0), a3);
;             PG8_WAIT_V(8); PG8_WAIT_L(0); PG8_BAR; PG8_MMA(1, 0, At, B0); PG8_MMA(1, 1, At, B1); PG8_BAR; PG8_SCHED;
	s_setprio 1
	s_waitcnt lgkmcnt(0)
	v_mfma_f32_16x16x32_bf16 v[124:127], v[134:137], v[182:185], v[124:127]
	v_mfma_f32_16x16x32_bf16 v[120:123], v[142:145], v[182:185], v[120:123]
	v_mfma_f32_16x16x32_bf16 v[116:119], v[134:137], v[190:193], v[116:119]
	v_mfma_f32_16x16x32_bf16 v[112:115], v[142:145], v[190:193], v[112:115]
	v_mfma_f32_16x16x32_bf16 v[108:111], v[134:137], v[198:201], v[108:111]
	v_mfma_f32_16x16x32_bf16 v[104:107], v[142:145], v[198:201], v[104:107]
	v_mfma_f32_16x16x32_bf16 v[100:103], v[134:137], v[206:209], v[100:103]
	v_mfma_f32_16x16x32_bf16 v[96:99], v[142:145], v[206:209], v[96:99]
	v_mfma_f32_16x16x32_bf16 v[124:127], v[138:141], v[186:189], v[124:127]
	v_mfma_f32_16x16x32_bf16 v[120:123], v[146:149], v[186:189], v[120:123]
	v_mfma_f32_16x16x32_bf16 v[116:119], v[138:141], v[194:197], v[116:119]
	v_mfma_f32_16x16x32_bf16 v[112:115], v[146:149], v[194:197], v[112:115]
	v_mfma_f32_16x16x32_bf16 v[108:111], v[138:141], v[202:205], v[108:111]
	v_mfma_f32_16x16x32_bf16 v[104:107], v[146:149], v[202:205], v[104:107]
	v_mfma_f32_16x16x32_bf16 v[100:103], v[138:141], v[210:213], v[100:103]
	v_mfma_f32_16x16x32_bf16 v[96:99], v[146:149], v[210:213], v[96:99]
	s_setprio 0
	s_setprio 1
	v_mfma_f32_16x16x32_bf16 v[92:95], v[150:153], v[182:185], v[92:95]
	v_mfma_f32_16x16x32_bf16 v[88:91], v[174:177], v[182:185], v[88:91]
	v_mfma_f32_16x16x32_bf16 v[84:87], v[150:153], v[190:193], v[84:87]
	v_mfma_f32_16x16x32_bf16 v[80:83], v[174:177], v[190:193], v[80:83]
	v_mfma_f32_16x16x32_bf16 v[76:79], v[150:153], v[198:201], v[76:79]
	v_mfma_f32_16x16x32_bf16 v[72:75], v[174:177], v[198:201], v[72:75]
	v_mfma_f32_16x16x32_bf16 v[68:71], v[150:153], v[206:209], v[68:71]
	v_mfma_f32_16x16x32_bf16 v[64:67], v[174:177], v[206:209], v[64:67]
	v_mfma_f32_16x16x32_bf16 v[92:95], v[154:157], v[186:189], v[92:95]
	v_mfma_f32_16x16x32_bf16 v[88:91], v[178:181], v[186:189], v[88:91]
	v_mfma_f32_16x16x32_bf16 v[84:87], v[154:157], v[194:197], v[84:87]
	v_mfma_f32_16x16x32_bf16 v[80:83], v[178:181], v[194:197], v[80:83]
	v_mfma_f32_16x16x32_bf16 v[76:79], v[154:157], v[202:205], v[76:79]
	v_mfma_f32_16x16x32_bf16 v[72:75], v[178:181], v[202:205], v[72:75]
	v_mfma_f32_16x16x32_bf16 v[68:71], v[154:157], v[210:213], v[68:71]
	v_mfma_f32_16x16x32_bf16 v[64:67], v[178:181], v[210:213], v[64:67]
	s_setprio 0
	s_barrier
	s_or_b32 s55, s54, 0x80
	s_add_i32 s56, s56, s33
	v_add_u32_e32 v158, s55, v162
	s_mov_b32 m0, s56
	ds_read_b128 v[182:185], v172 offset:49152
	ds_read_b128 v[186:189], v172 offset:50176
	ds_read_b128 v[190:193], v172 offset:51200
	ds_read_b128 v[194:197], v172 offset:52224
	ds_read_b128 v[198:201], v172 offset:53248
	ds_read_b128 v[202:205], v172 offset:54272
	ds_read_b128 v[206:209], v172 offset:55296
	ds_read_b128 v[210:213], v172 offset:56320
	global_load_lds_dwordx4 v158, s[16:17]
	v_add_u32_e32 v158, s55, v164
	s_add_i32 m0, s56, 0x2000
	s_add_i32 s54, s54, 0x80080
	s_add_i32 s55, s57, s33
	global_load_lds_dwordx4 v158, s[16:17]
	v_add_u32_e32 v158, s54, v162
	s_mov_b32 m0, s55
	s_nop 0
	global_load_lds_dwordx4 v158, s[16:17]
	v_add_u32_e32 v158, s54, v164
	s_add_i32 m0, s55, 0x2000
	s_nop 0
	global_load_lds_dwordx4 v158, s[16:17]
	v_add_u32_e32 v158, s53, v161
	s_mov_b32 m0, s39
	s_nop 0
	global_load_lds_dwordx4 v158, s[14:15]
	v_add_u32_e32 v158, s53, v163
	s_mov_b32 m0, s40
	s_nop 0
	global_load_lds_dwordx4 v158, s[14:15]
	s_waitcnt vmcnt(8)
	s_waitcnt lgkmcnt(0)
	s_barrier
	s_setprio 1
	s_waitcnt lgkmcnt(0)
	v_mfma_f32_16x16x32_bf16 v[60:63], v[134:137], v[182:185], v[60:63]
	v_mfma_f32_16x16x32_bf16 v[56:59], v[142:145], v[182:185], v[56:59]
	v_mfma_f32_16x16x32_bf16 v[52:55], v[134:137], v[190:193], v[52:55]
	v_mfma_f32_16x16x32_bf16 v[48:51], v[142:145], v[190:193], v[48:51]
	v_mfma_f32_16x16x32_bf16 v[44:47], v[134:137], v[198:201], v[44:47]
	v_mfma_f32_16x16x32_bf16 v[40:43], v[142:145], v[198:201], v[40:43]
	v_mfma_f32_16x16x32_bf16 v[36:39], v[134:137], v[206:209], v[36:39]
	v_mfma_f32_16x16x32_bf16 v[32:35], v[142:145], v[206:209], v[32:35]
	v_mfma_f32_16x16x32_bf16 v[60:63], v[138:141], v[186:189], v[60:63]
	v_mfma_f32_16x16x32_bf16 v[56:59], v[146:149], v[186:189], v[56:59]
	v_mfma_f32_16x16x32_bf16 v[52:55], v[138:141], v[194:197], v[52:55]
	v_mfma_f32_16x16x32_bf16 v[48:51], v[146:149], v[194:197], v[48:51]
	v_mfma_f32_16x16x32_bf16 v[44:47], v[138:141], v[202:205], v[44:47]
	v_mfma_f32_16x16x32_bf16 v[40:43], v[146:149], v[202:205], v[40:43]
	v_mfma_f32_16x16x32_bf16 v[36:39], v[138:141], v[210:213], v[36:39]
	v_mfma_f32_16x16x32_bf16 v[32:35], v[146:149], v[210:213], v[32:35]
	s_setprio 0
	s_setprio 1
	v_mfma_f32_16x16x32_bf16 v[28:31], v[150:153], v[182:185], v[28:31]
	v_mfma_f32_16x16x32_bf16 v[24:27], v[174:177], v[182:185], v[24:27]
	v_mfma_f32_16x16x32_bf16 v[20:23], v[150:153], v[190:193], v[20:23]
	v_mfma_f32_16x16x32_bf16 v[16:19], v[174:177], v[190:193], v[16:19]
	v_mfma_f32_16x16x32_bf16 v[12:15], v[150:153], v[198:201], v[12:15]
	v_mfma_f32_16x16x32_bf16 v[8:11], v[174:177], v[198:201], v[8:11]
	v_mfma_f32_16x16x32_bf16 v[4:7], v[150:153], v[206:209], v[4:7]
	v_mfma_f32_16x16x32_bf16 v[0:3], v[174:177], v[206:209], v[0:3]
	v_mfma_f32_16x16x32_bf16 v[28:31], v[154:157], v[186:189], v[28:31]
	v_mfma_f32_16x16x32_bf16 v[24:27], v[178:181], v[186:189], v[24:27]
	v_mfma_f32_16x16x32_bf16 v[20:23], v[154:157], v[194:197], v[20:23]
	v_mfma_f32_16x16x32_bf16 v[16:19], v[178:181], v[194:197], v[16:19]
	v_mfma_f32_16x16x32_bf16 v[12:15], v[154:157], v[202:205], v[12:15]
	v_mfma_f32_16x16x32_bf16 v[8:11], v[178:181], v[202:205], v[8:11]
	v_mfma_f32_16x16x32_bf16 v[4:7], v[154:157], v[210:213], v[4:7]
	v_mfma_f32_16x16x32_bf16 v[0:3], v[178:181], v[210:213], v[0:3]
	s_setprio 0
	s_barrier
	s_add_i32 s52, s52, 2
	s_addk_i32 s6, 0x100
	s_addk_i32 s7, 0x100
	v_add_u32_e32 v132, 0x100, v132
	s_cmp_gt_u32 s52, 29
	v_add_u32_e32 v133, 0x100, v133
	s_cbranch_scc0 .LBB0_2206
	s_branch .Lpeel_after_pl11

; #define PG8_BAR __builtin_amdgcn_s_barrier()
; template <class Epi, class Sched, bool ALIGN_EPI, bool F8 = false>
; __device__ __forceinline__ void gemm_phase(LAS unsigned char* lds, const Gemm g, const Sched& S, const Epi& E) {
;     ...
;         }
;         if constexpr (ALIGN_EPI) { if (wr == 0) PG8_BAR; }
.Lpeel_after_pl11:
	s_and_b64 vcc, exec, s[28:29]
	s_cbranch_vccz .LBB0_2209
	s_barrier
